# GEMM K-loops via LDS-DMA (global_load_lds_dwordx4) into XOR-swizzled unpadded LDS tiles, loads interleaved with MFMAs; plus v19 MLA loop edits
# speedup vs baseline: 1.0098x; 1.0098x over previous
; #define MFMA(a, b, c) __builtin_amdgcn_mfma_f32_32x32x16_bf16((a), (b), (c), 0, 0, 0)
; template <bool SWAP>
; DI void gemm_block(const bf16_t* __restrict__ A, int lda, const bf16_t* __restrict__ Bt, int ldb, int K, f32x16 (&acc)[2][2], bf16_t* sA, bf16_t* sB) {
;     ...
;   const int lrow = tid >> 3, lch = (tid & 7) * 8;
;   const bf16_t* ga = A + (size_t)lrow * lda + lch;
;   const bf16_t* gb = Bt + (size_t)lrow * ldb + lch;
;   const int soff = lrow * LDT + lch;
;   u32x4 ra[4], rb[4];
; #pragma unroll
;   for (int i = 0; i < 4; ++i) { ra[i] = *(const u32x4*)(ga + (size_t)i * 32 * lda); rb[i] = *(const u32x4*)(gb + (size_t)i * 32 * ldb); }
; #pragma unroll
;   for (int i = 0; i < 4; ++i) { *(u32x4*)(sA + soff + i * 32 * LDT) = ra[i]; *(u32x4*)(sB + soff + i * 32 * LDT) = rb[i]; }
;   __syncthreads();
;   const int nk = K >> 6;
;   for (int kt = 0; kt < nk; ++kt) {
;     const int cur = kt & 1;
;     const bool more = kt + 1 < nk;
;     if (more) {
;       const int k0 = (kt + 1) * 64;
; #pragma unroll
;       for (int i = 0; i < 4; ++i) { ra[i] = *(const u32x4*)(ga + (size_t)i * 32 * lda + k0); rb[i] = *(const u32x4*)(gb + (size_t)i * 32 * ldb + k0); }
;     }
;     const bf16_t* ab = sA + cur * 128 * LDT + (64 * wr + l32) * LDT + h * 8;
;     const bf16_t* bb = sB + cur * 128 * LDT + (64 * wc + l32) * LDT + h * 8;
;     __builtin_amdgcn_s_setprio(1);
;     __builtin_amdgcn_iglp_opt(0);
; #pragma unroll
;     for (int ks = 0; ks < 4; ++ks) {
;       const bf16x8 a0 = *(const bf16x8*)(ab + ks * 16), a1 = *(const bf16x8*)(ab + 32 * LDT + ks * 16);
;       const bf16x8 b0 = *(const bf16x8*)(bb + ks * 16), b1 = *(const bf16x8*)(bb + 32 * LDT + ks * 16);
;       if (!SWAP) {
;         acc[0][0] = MFMA(a0, b0, acc[0][0]); acc[0][1] = MFMA(a0, b1, acc[0][1]);
;         acc[1][0] = MFMA(a1, b0, acc[1][0]); acc[1][1] = MFMA(a1, b1, acc[1][1]);
;       } else {
;         acc[0][0] = MFMA(b0, a0, acc[0][0]); acc[0][1] = MFMA(b1, a0, acc[0][1]);
;         acc[1][0] = MFMA(b0, a1, acc[1][0]); acc[1][1] = MFMA(b1, a1, acc[1][1]);
;       }
;     }
;     __builtin_amdgcn_s_setprio(0);
;     if (more) {
;       const int nb = (cur ^ 1) * 128 * LDT;
; #pragma unroll
;       for (int i = 0; i < 4; ++i) { *(u32x4*)(sA + nb + soff + i * 32 * LDT) = ra[i]; *(u32x4*)(sB + nb + soff + i * 32 * LDT) = rb[i]; }
;     }
;     __syncthreads();
;   }
.LBB0_232:
	v_mov_b32_e32 v84, v188
	s_andn2_b64 vcc, exec, s[22:23]
	s_mov_b64 s[22:23], -1
	s_cbranch_vccz .LBB0_234
	v_mov_b32_e32 v34, v188
	s_waitcnt vmcnt(7)
	v_ashrrev_i32_e32 v2, 3, v34
	v_lshlrev_b32_e32 v0, 3, v34
	v_ashrrev_i32_e32 v3, 31, v2
	v_and_b32_e32 v35, 56, v0
	v_lshlrev_b64 v[4:5], 11, v[2:3]
	s_waitcnt vmcnt(6)
	v_lshl_add_u64 v[6:7], s[20:21], 0, v[4:5]
	v_lshrrev_b32_e32 v20, 4, v34
	v_and_b32_e32 v21, 7, v34
	v_and_b32_e32 v20, 7, v20
	v_xor_b32_e32 v20, v20, v21
	v_lshlrev_b32_e32 v0, 4, v20
	v_lshl_add_u64 v[68:69], v[6:7], 0, v[0:1]
	v_lshl_add_u64 v[4:5], s[42:43], 0, v[4:5]
	v_add_co_u32_e32 v72, vcc, s50, v68
	v_lshl_add_u64 v[70:71], v[4:5], 0, v[0:1]
	s_nop 0
	v_addc_co_u32_e32 v73, vcc, 0, v69, vcc
	v_add_co_u32_e32 v74, vcc, s50, v70
	v_mul_lo_u32 v0, v2, s33
	s_nop 0
	v_addc_co_u32_e32 v75, vcc, 0, v71, vcc
	v_add_co_u32_e32 v76, vcc, s51, v68
	s_nop 0
	s_nop 0
	v_addc_co_u32_e32 v77, vcc, 0, v69, vcc
	v_add_co_u32_e32 v78, vcc, s51, v70
	s_nop 0
	s_nop 0
	v_addc_co_u32_e32 v79, vcc, 0, v71, vcc
	v_add_co_u32_e32 v80, vcc, s52, v68
	s_nop 0
	s_nop 0
	v_addc_co_u32_e32 v81, vcc, 0, v69, vcc
	v_add_co_u32_e32 v82, vcc, s52, v70
	s_nop 0
	s_nop 0
	v_addc_co_u32_e32 v83, vcc, 0, v71, vcc
	s_nop 0
	s_nop 0
	s_nop 0
	s_nop 0
	v_add_lshl_u32 v85, v0, v35, 1
	v_and_b32_e32 v0, 31, v34
	v_add_u32_e32 v86, 0x9000, v85
	v_lshrrev_b32_e32 v2, 1, v34
	v_and_or_b32 v3, v2, s53, v0
	v_and_b32_e32 v0, 16, v2
	v_and_b32_e32 v2, 0x5f, v34
	v_mad_u64_u32 v[66:67], s[0:1], v3, s54, v[0:1]
	v_mad_u32_u24 v0, v2, s54, v0
	v_lshrrev_b32_e32 v20, 6, v34
	v_and_b32_e32 v21, 31, v34
	v_readfirstlane_b32 s100, v20
	v_lshrrev_b32_e32 v22, 7, v34
	v_bfe_u32 v23, v34, 6, 1
	s_lshl_b32 s100, s100, 10
	v_lshl_or_b32 v22, v22, 6, v21
	v_lshl_or_b32 v23, v23, 6, v21
	s_add_u32 m0, s100, 2048
	s_nop 0
	global_load_lds_dwordx4 v[68:69], off
	s_add_u32 m0, s100, 18432
	s_nop 0
	global_load_lds_dwordx4 v[70:71], off
	s_add_u32 m0, s100, 6144
	s_nop 0
	global_load_lds_dwordx4 v[72:73], off
	s_add_u32 m0, s100, 22528
	s_nop 0
	global_load_lds_dwordx4 v[74:75], off
	s_add_u32 m0, s100, 10240
	s_nop 0
	global_load_lds_dwordx4 v[76:77], off
	s_add_u32 m0, s100, 26624
	s_nop 0
	global_load_lds_dwordx4 v[78:79], off
	s_add_u32 m0, s100, 14336
	s_nop 0
	global_load_lds_dwordx4 v[80:81], off
	s_add_u32 m0, s100, 30720
	s_nop 0
	global_load_lds_dwordx4 v[82:83], off
	v_lshrrev_b32_e32 v24, 5, v34
	v_lshrrev_b32_e32 v25, 1, v34
	v_xor_b32_e32 v24, v24, v25
	v_and_b32_e32 v24, 1, v24
	v_bfe_u32 v25, v34, 2, 2
	v_lshlrev_b32_e32 v22, 7, v22
	v_lshlrev_b32_e32 v23, 7, v23
	v_lshl_add_u32 v22, v24, 4, v22
	v_lshl_add_u32 v23, v24, 4, v23
	v_add_u32_e32 v22, 2048, v22
	v_add_u32_e32 v23, 18432, v23
	v_lshl_add_u32 v204, v25, 5, v22
	v_lshl_add_u32 v208, v25, 5, v23
	v_xor_b32_e32 v26, 1, v25
	v_lshl_add_u32 v205, v26, 5, v22
	v_lshl_add_u32 v209, v26, 5, v23
	v_xor_b32_e32 v26, 2, v25
	v_lshl_add_u32 v206, v26, 5, v22
	v_lshl_add_u32 v210, v26, 5, v23
	v_xor_b32_e32 v26, 3, v25
	v_lshl_add_u32 v207, v26, 5, v22
	v_lshl_add_u32 v211, v26, 5, v23
	s_waitcnt vmcnt(0)
	s_waitcnt lgkmcnt(0)
	s_barrier
	ds_read_b128 v[120:123], v204
	ds_read_b128 v[128:131], v208
	ds_read_b128 v[132:135], v208 offset:4096
	ds_read_b128 v[124:127], v204 offset:4096
	ds_read_b128 v[136:139], v205
	ds_read_b128 v[184:187], v209
	ds_read_b128 v[200:203], v209 offset:4096
	ds_read_b128 v[140:143], v205 offset:4096
	s_setprio 1
	s_waitcnt lgkmcnt(4)
	s_add_u32 m0, s100, 34688
	v_mfma_f32_32x32x16_bf16 v[34:49], v[128:131], v[120:123], 0
	global_load_lds_dwordx4 v[68:69], off offset:128
	s_add_u32 m0, s100, 51072
	v_mfma_f32_32x32x16_bf16 v[18:33], v[132:135], v[120:123], 0
	global_load_lds_dwordx4 v[70:71], off offset:128
	s_add_u32 m0, s100, 38784
	v_mfma_f32_32x32x16_bf16 v[50:65], v[132:135], v[124:127], 0
	global_load_lds_dwordx4 v[72:73], off offset:128
	s_add_u32 m0, s100, 55168
	v_mfma_f32_32x32x16_bf16 v[2:17], v[128:131], v[124:127], 0
	global_load_lds_dwordx4 v[74:75], off offset:128
	ds_read_b128 v[120:123], v206
	ds_read_b128 v[128:131], v210
	ds_read_b128 v[132:135], v210 offset:4096
	ds_read_b128 v[124:127], v206 offset:4096
	s_waitcnt lgkmcnt(4)
	s_add_u32 m0, s100, 42880
	v_mfma_f32_32x32x16_bf16 v[34:49], v[184:187], v[136:139], v[34:49]
	global_load_lds_dwordx4 v[76:77], off offset:128
	s_add_u32 m0, s100, 59264
	v_mfma_f32_32x32x16_bf16 v[18:33], v[200:203], v[136:139], v[18:33]
	global_load_lds_dwordx4 v[78:79], off offset:128
	s_add_u32 m0, s100, 46976
	v_mfma_f32_32x32x16_bf16 v[50:65], v[200:203], v[140:143], v[50:65]
	global_load_lds_dwordx4 v[80:81], off offset:128
	s_add_u32 m0, s100, 63360
	v_mfma_f32_32x32x16_bf16 v[2:17], v[184:187], v[140:143], v[2:17]
	global_load_lds_dwordx4 v[82:83], off offset:128
	ds_read_b128 v[136:139], v207
	ds_read_b128 v[184:187], v211
	ds_read_b128 v[200:203], v211 offset:4096
	ds_read_b128 v[140:143], v207 offset:4096
	s_waitcnt lgkmcnt(4)
	v_mfma_f32_32x32x16_bf16 v[34:49], v[128:131], v[120:123], v[34:49]
	v_mfma_f32_32x32x16_bf16 v[18:33], v[132:135], v[120:123], v[18:33]
	v_mfma_f32_32x32x16_bf16 v[50:65], v[132:135], v[124:127], v[50:65]
	v_mfma_f32_32x32x16_bf16 v[2:17], v[128:131], v[124:127], v[2:17]
	s_waitcnt lgkmcnt(0)
	v_mfma_f32_32x32x16_bf16 v[34:49], v[184:187], v[136:139], v[34:49]
	v_mfma_f32_32x32x16_bf16 v[18:33], v[200:203], v[136:139], v[18:33]
	v_mfma_f32_32x32x16_bf16 v[50:65], v[200:203], v[140:143], v[50:65]
	v_mfma_f32_32x32x16_bf16 v[2:17], v[184:187], v[140:143], v[2:17]
	s_setprio 0
	s_waitcnt vmcnt(0)
	s_barrier
; #define MFMA(a, b, c) __builtin_amdgcn_mfma_f32_32x32x16_bf16((a), (b), (c), 0, 0, 0)
; template <bool SWAP>
; DI void gemm_block(const bf16_t* __restrict__ A, int lda, const bf16_t* __restrict__ Bt, int ldb, int K, f32x16 (&acc)[2][2], bf16_t* sA, bf16_t* sB) {
;     ...
;   for (int kt = 0; kt < nk; ++kt) {
;     const int cur = kt & 1;
;     const bool more = kt + 1 < nk;
;     if (more) {
;       const int k0 = (kt + 1) * 64;
; #pragma unroll
;       for (int i = 0; i < 4; ++i) { ra[i] = *(const u32x4*)(ga + (size_t)i * 32 * lda + k0); rb[i] = *(const u32x4*)(gb + (size_t)i * 32 * ldb + k0); }
;     }
;     const bf16_t* ab = sA + cur * 128 * LDT + (64 * wr + l32) * LDT + h * 8;
;     const bf16_t* bb = sB + cur * 128 * LDT + (64 * wc + l32) * LDT + h * 8;
;     __builtin_amdgcn_s_setprio(1);
;     __builtin_amdgcn_iglp_opt(0);
; #pragma unroll
;     for (int ks = 0; ks < 4; ++ks) {
;       const bf16x8 a0 = *(const bf16x8*)(ab + ks * 16), a1 = *(const bf16x8*)(ab + 32 * LDT + ks * 16);
;       const bf16x8 b0 = *(const bf16x8*)(bb + ks * 16), b1 = *(const bf16x8*)(bb + 32 * LDT + ks * 16);
;       if (!SWAP) {
;         acc[0][0] = MFMA(a0, b0, acc[0][0]); acc[0][1] = MFMA(a0, b1, acc[0][1]);
;         acc[1][0] = MFMA(a1, b0, acc[1][0]); acc[1][1] = MFMA(a1, b1, acc[1][1]);
;       } else {
;         acc[0][0] = MFMA(b0, a0, acc[0][0]); acc[0][1] = MFMA(b1, a0, acc[0][1]);
;         acc[1][0] = MFMA(b0, a1, acc[1][0]); acc[1][1] = MFMA(b1, a1, acc[1][1]);
;       }
;     }
;     __builtin_amdgcn_s_setprio(0);
;     if (more) {
;       const int nb = (cur ^ 1) * 128 * LDT;
; #pragma unroll
;       for (int i = 0; i < 4; ++i) { *(u32x4*)(sA + nb + soff + i * 32 * LDT) = ra[i]; *(u32x4*)(sB + nb + soff + i * 32 * LDT) = rb[i]; }
;     }
;     __syncthreads();
;   }
	ds_read_b128 v[120:123], v204 offset:32768
	ds_read_b128 v[128:131], v208 offset:32768
	ds_read_b128 v[132:135], v208 offset:36864
	ds_read_b128 v[124:127], v204 offset:36864
	ds_read_b128 v[136:139], v205 offset:32768
	ds_read_b128 v[184:187], v209 offset:32768
	ds_read_b128 v[200:203], v209 offset:36864
	ds_read_b128 v[140:143], v205 offset:36864
	s_setprio 1
	s_waitcnt lgkmcnt(4)
	s_add_u32 m0, s100, 1792
	v_mfma_f32_32x32x16_bf16 v[34:49], v[128:131], v[120:123], v[34:49]
	global_load_lds_dwordx4 v[68:69], off offset:256
	s_add_u32 m0, s100, 18176
	v_mfma_f32_32x32x16_bf16 v[18:33], v[132:135], v[120:123], v[18:33]
	global_load_lds_dwordx4 v[70:71], off offset:256
	s_add_u32 m0, s100, 5888
	v_mfma_f32_32x32x16_bf16 v[50:65], v[132:135], v[124:127], v[50:65]
	global_load_lds_dwordx4 v[72:73], off offset:256
	s_add_u32 m0, s100, 22272
	v_mfma_f32_32x32x16_bf16 v[2:17], v[128:131], v[124:127], v[2:17]
	global_load_lds_dwordx4 v[74:75], off offset:256
	ds_read_b128 v[120:123], v206 offset:32768
	ds_read_b128 v[128:131], v210 offset:32768
	ds_read_b128 v[132:135], v210 offset:36864
	ds_read_b128 v[124:127], v206 offset:36864
	s_waitcnt lgkmcnt(4)
	s_add_u32 m0, s100, 9984
	v_mfma_f32_32x32x16_bf16 v[34:49], v[184:187], v[136:139], v[34:49]
	global_load_lds_dwordx4 v[76:77], off offset:256
	s_add_u32 m0, s100, 26368
	v_mfma_f32_32x32x16_bf16 v[18:33], v[200:203], v[136:139], v[18:33]
	global_load_lds_dwordx4 v[78:79], off offset:256
	s_add_u32 m0, s100, 14080
	v_mfma_f32_32x32x16_bf16 v[50:65], v[200:203], v[140:143], v[50:65]
	global_load_lds_dwordx4 v[80:81], off offset:256
	s_add_u32 m0, s100, 30464
	v_mfma_f32_32x32x16_bf16 v[2:17], v[184:187], v[140:143], v[2:17]
	global_load_lds_dwordx4 v[82:83], off offset:256
	ds_read_b128 v[136:139], v207 offset:32768
	ds_read_b128 v[184:187], v211 offset:32768
	ds_read_b128 v[200:203], v211 offset:36864
	ds_read_b128 v[140:143], v207 offset:36864
	s_waitcnt lgkmcnt(4)
	v_mfma_f32_32x32x16_bf16 v[34:49], v[128:131], v[120:123], v[34:49]
	v_mfma_f32_32x32x16_bf16 v[18:33], v[132:135], v[120:123], v[18:33]
	v_mfma_f32_32x32x16_bf16 v[50:65], v[132:135], v[124:127], v[50:65]
	v_mfma_f32_32x32x16_bf16 v[2:17], v[128:131], v[124:127], v[2:17]
	s_waitcnt lgkmcnt(0)
	v_mfma_f32_32x32x16_bf16 v[34:49], v[184:187], v[136:139], v[34:49]
	v_mfma_f32_32x32x16_bf16 v[18:33], v[200:203], v[136:139], v[18:33]
	v_mfma_f32_32x32x16_bf16 v[50:65], v[200:203], v[140:143], v[50:65]
	v_mfma_f32_32x32x16_bf16 v[2:17], v[184:187], v[140:143], v[2:17]
	s_setprio 0
	s_waitcnt vmcnt(0)
	s_barrier
	ds_read_b128 v[120:123], v204
	ds_read_b128 v[128:131], v208
	ds_read_b128 v[132:135], v208 offset:4096
	ds_read_b128 v[124:127], v204 offset:4096
	ds_read_b128 v[136:139], v205
	ds_read_b128 v[184:187], v209
	ds_read_b128 v[200:203], v209 offset:4096
	ds_read_b128 v[140:143], v205 offset:4096
	s_setprio 1
	s_waitcnt lgkmcnt(4)
	s_add_u32 m0, s100, 34432
	v_mfma_f32_32x32x16_bf16 v[34:49], v[128:131], v[120:123], v[34:49]
	global_load_lds_dwordx4 v[68:69], off offset:384
	s_add_u32 m0, s100, 50816
	v_mfma_f32_32x32x16_bf16 v[18:33], v[132:135], v[120:123], v[18:33]
	global_load_lds_dwordx4 v[70:71], off offset:384
	s_add_u32 m0, s100, 38528
	v_mfma_f32_32x32x16_bf16 v[50:65], v[132:135], v[124:127], v[50:65]
	global_load_lds_dwordx4 v[72:73], off offset:384
	s_add_u32 m0, s100, 54912
	v_mfma_f32_32x32x16_bf16 v[2:17], v[128:131], v[124:127], v[2:17]
	global_load_lds_dwordx4 v[74:75], off offset:384
	ds_read_b128 v[120:123], v206
	ds_read_b128 v[128:131], v210
	ds_read_b128 v[132:135], v210 offset:4096
	ds_read_b128 v[124:127], v206 offset:4096
	s_waitcnt lgkmcnt(4)
	s_add_u32 m0, s100, 42624
	v_mfma_f32_32x32x16_bf16 v[34:49], v[184:187], v[136:139], v[34:49]
	global_load_lds_dwordx4 v[76:77], off offset:384
	s_add_u32 m0, s100, 59008
	v_mfma_f32_32x32x16_bf16 v[18:33], v[200:203], v[136:139], v[18:33]
	global_load_lds_dwordx4 v[78:79], off offset:384
	s_add_u32 m0, s100, 46720
	v_mfma_f32_32x32x16_bf16 v[50:65], v[200:203], v[140:143], v[50:65]
	global_load_lds_dwordx4 v[80:81], off offset:384
	s_add_u32 m0, s100, 63104
	v_mfma_f32_32x32x16_bf16 v[2:17], v[184:187], v[140:143], v[2:17]
	global_load_lds_dwordx4 v[82:83], off offset:384
	ds_read_b128 v[136:139], v207
	ds_read_b128 v[184:187], v211
	ds_read_b128 v[200:203], v211 offset:4096
	ds_read_b128 v[140:143], v207 offset:4096
	s_waitcnt lgkmcnt(4)
	v_mfma_f32_32x32x16_bf16 v[34:49], v[128:131], v[120:123], v[34:49]
	v_mfma_f32_32x32x16_bf16 v[18:33], v[132:135], v[120:123], v[18:33]
	v_mfma_f32_32x32x16_bf16 v[50:65], v[132:135], v[124:127], v[50:65]
	v_mfma_f32_32x32x16_bf16 v[2:17], v[128:131], v[124:127], v[2:17]
	s_waitcnt lgkmcnt(0)
	v_mfma_f32_32x32x16_bf16 v[34:49], v[184:187], v[136:139], v[34:49]
	v_mfma_f32_32x32x16_bf16 v[18:33], v[200:203], v[136:139], v[18:33]
	v_mfma_f32_32x32x16_bf16 v[50:65], v[200:203], v[140:143], v[50:65]
	v_mfma_f32_32x32x16_bf16 v[2:17], v[184:187], v[140:143], v[2:17]
	s_setprio 0
	s_waitcnt vmcnt(0)
	s_barrier
; #define MFMA(a, b, c) __builtin_amdgcn_mfma_f32_32x32x16_bf16((a), (b), (c), 0, 0, 0)
; template <bool SWAP>
; DI void gemm_block(const bf16_t* __restrict__ A, int lda, const bf16_t* __restrict__ Bt, int ldb, int K, f32x16 (&acc)[2][2], bf16_t* sA, bf16_t* sB) {
;     ...
;   for (int kt = 0; kt < nk; ++kt) {
;     const int cur = kt & 1;
;     const bool more = kt + 1 < nk;
;     if (more) {
;       const int k0 = (kt + 1) * 64;
; #pragma unroll
;       for (int i = 0; i < 4; ++i) { ra[i] = *(const u32x4*)(ga + (size_t)i * 32 * lda + k0); rb[i] = *(const u32x4*)(gb + (size_t)i * 32 * ldb + k0); }
;     }
;     const bf16_t* ab = sA + cur * 128 * LDT + (64 * wr + l32) * LDT + h * 8;
;     const bf16_t* bb = sB + cur * 128 * LDT + (64 * wc + l32) * LDT + h * 8;
;     __builtin_amdgcn_s_setprio(1);
;     __builtin_amdgcn_iglp_opt(0);
; #pragma unroll
;     for (int ks = 0; ks < 4; ++ks) {
;       const bf16x8 a0 = *(const bf16x8*)(ab + ks * 16), a1 = *(const bf16x8*)(ab + 32 * LDT + ks * 16);
;       const bf16x8 b0 = *(const bf16x8*)(bb + ks * 16), b1 = *(const bf16x8*)(bb + 32 * LDT + ks * 16);
;       if (!SWAP) {
;         acc[0][0] = MFMA(a0, b0, acc[0][0]); acc[0][1] = MFMA(a0, b1, acc[0][1]);
;         acc[1][0] = MFMA(a1, b0, acc[1][0]); acc[1][1] = MFMA(a1, b1, acc[1][1]);
;       } else {
;         acc[0][0] = MFMA(b0, a0, acc[0][0]); acc[0][1] = MFMA(b1, a0, acc[0][1]);
;         acc[1][0] = MFMA(b0, a1, acc[1][0]); acc[1][1] = MFMA(b1, a1, acc[1][1]);
;       }
;     }
;     __builtin_amdgcn_s_setprio(0);
;     if (more) {
;       const int nb = (cur ^ 1) * 128 * LDT;
; #pragma unroll
;       for (int i = 0; i < 4; ++i) { *(u32x4*)(sA + nb + soff + i * 32 * LDT) = ra[i]; *(u32x4*)(sB + nb + soff + i * 32 * LDT) = rb[i]; }
;     }
;     __syncthreads();
;   }
	ds_read_b128 v[120:123], v204 offset:32768
	ds_read_b128 v[128:131], v208 offset:32768
	ds_read_b128 v[132:135], v208 offset:36864
	ds_read_b128 v[124:127], v204 offset:36864
	ds_read_b128 v[136:139], v205 offset:32768
	ds_read_b128 v[184:187], v209 offset:32768
	ds_read_b128 v[200:203], v209 offset:36864
	ds_read_b128 v[140:143], v205 offset:36864
	s_setprio 1
	s_waitcnt lgkmcnt(4)
	s_add_u32 m0, s100, 1536
	v_mfma_f32_32x32x16_bf16 v[34:49], v[128:131], v[120:123], v[34:49]
	global_load_lds_dwordx4 v[68:69], off offset:512
	s_add_u32 m0, s100, 17920
	v_mfma_f32_32x32x16_bf16 v[18:33], v[132:135], v[120:123], v[18:33]
	global_load_lds_dwordx4 v[70:71], off offset:512
	s_add_u32 m0, s100, 5632
	v_mfma_f32_32x32x16_bf16 v[50:65], v[132:135], v[124:127], v[50:65]
	global_load_lds_dwordx4 v[72:73], off offset:512
	s_add_u32 m0, s100, 22016
	v_mfma_f32_32x32x16_bf16 v[2:17], v[128:131], v[124:127], v[2:17]
	global_load_lds_dwordx4 v[74:75], off offset:512
	ds_read_b128 v[120:123], v206 offset:32768
	ds_read_b128 v[128:131], v210 offset:32768
	ds_read_b128 v[132:135], v210 offset:36864
	ds_read_b128 v[124:127], v206 offset:36864
	s_waitcnt lgkmcnt(4)
	s_add_u32 m0, s100, 9728
	v_mfma_f32_32x32x16_bf16 v[34:49], v[184:187], v[136:139], v[34:49]
	global_load_lds_dwordx4 v[76:77], off offset:512
	s_add_u32 m0, s100, 26112
	v_mfma_f32_32x32x16_bf16 v[18:33], v[200:203], v[136:139], v[18:33]
	global_load_lds_dwordx4 v[78:79], off offset:512
	s_add_u32 m0, s100, 13824
	v_mfma_f32_32x32x16_bf16 v[50:65], v[200:203], v[140:143], v[50:65]
	global_load_lds_dwordx4 v[80:81], off offset:512
	s_add_u32 m0, s100, 30208
	v_mfma_f32_32x32x16_bf16 v[2:17], v[184:187], v[140:143], v[2:17]
	global_load_lds_dwordx4 v[82:83], off offset:512
	ds_read_b128 v[136:139], v207 offset:32768
	ds_read_b128 v[184:187], v211 offset:32768
	ds_read_b128 v[200:203], v211 offset:36864
	ds_read_b128 v[140:143], v207 offset:36864
	s_waitcnt lgkmcnt(4)
	v_mfma_f32_32x32x16_bf16 v[34:49], v[128:131], v[120:123], v[34:49]
	v_mfma_f32_32x32x16_bf16 v[18:33], v[132:135], v[120:123], v[18:33]
	v_mfma_f32_32x32x16_bf16 v[50:65], v[132:135], v[124:127], v[50:65]
	v_mfma_f32_32x32x16_bf16 v[2:17], v[128:131], v[124:127], v[2:17]
	s_waitcnt lgkmcnt(0)
	v_mfma_f32_32x32x16_bf16 v[34:49], v[184:187], v[136:139], v[34:49]
	v_mfma_f32_32x32x16_bf16 v[18:33], v[200:203], v[136:139], v[18:33]
	v_mfma_f32_32x32x16_bf16 v[50:65], v[200:203], v[140:143], v[50:65]
	v_mfma_f32_32x32x16_bf16 v[2:17], v[184:187], v[140:143], v[2:17]
	s_setprio 0
	s_waitcnt vmcnt(0)
	s_barrier
	ds_read_b128 v[120:123], v204
	ds_read_b128 v[128:131], v208
	ds_read_b128 v[132:135], v208 offset:4096
	ds_read_b128 v[124:127], v204 offset:4096
	ds_read_b128 v[136:139], v205
	ds_read_b128 v[184:187], v209
	ds_read_b128 v[200:203], v209 offset:4096
	ds_read_b128 v[140:143], v205 offset:4096
	s_setprio 1
	s_waitcnt lgkmcnt(4)
	s_add_u32 m0, s100, 34176
	v_mfma_f32_32x32x16_bf16 v[34:49], v[128:131], v[120:123], v[34:49]
	global_load_lds_dwordx4 v[68:69], off offset:640
	s_add_u32 m0, s100, 50560
	v_mfma_f32_32x32x16_bf16 v[18:33], v[132:135], v[120:123], v[18:33]
	global_load_lds_dwordx4 v[70:71], off offset:640
	s_add_u32 m0, s100, 38272
	v_mfma_f32_32x32x16_bf16 v[50:65], v[132:135], v[124:127], v[50:65]
	global_load_lds_dwordx4 v[72:73], off offset:640
	s_add_u32 m0, s100, 54656
	v_mfma_f32_32x32x16_bf16 v[2:17], v[128:131], v[124:127], v[2:17]
	global_load_lds_dwordx4 v[74:75], off offset:640
	ds_read_b128 v[120:123], v206
	ds_read_b128 v[128:131], v210
	ds_read_b128 v[132:135], v210 offset:4096
	ds_read_b128 v[124:127], v206 offset:4096
	s_waitcnt lgkmcnt(4)
	s_add_u32 m0, s100, 42368
	v_mfma_f32_32x32x16_bf16 v[34:49], v[184:187], v[136:139], v[34:49]
	global_load_lds_dwordx4 v[76:77], off offset:640
	s_add_u32 m0, s100, 58752
	v_mfma_f32_32x32x16_bf16 v[18:33], v[200:203], v[136:139], v[18:33]
	global_load_lds_dwordx4 v[78:79], off offset:640
	s_add_u32 m0, s100, 46464
	v_mfma_f32_32x32x16_bf16 v[50:65], v[200:203], v[140:143], v[50:65]
	global_load_lds_dwordx4 v[80:81], off offset:640
	s_add_u32 m0, s100, 62848
	v_mfma_f32_32x32x16_bf16 v[2:17], v[184:187], v[140:143], v[2:17]
	global_load_lds_dwordx4 v[82:83], off offset:640
	ds_read_b128 v[136:139], v207
	ds_read_b128 v[184:187], v211
	ds_read_b128 v[200:203], v211 offset:4096
	ds_read_b128 v[140:143], v207 offset:4096
	s_waitcnt lgkmcnt(4)
	v_mfma_f32_32x32x16_bf16 v[34:49], v[128:131], v[120:123], v[34:49]
	v_mfma_f32_32x32x16_bf16 v[18:33], v[132:135], v[120:123], v[18:33]
	v_mfma_f32_32x32x16_bf16 v[50:65], v[132:135], v[124:127], v[50:65]
	v_mfma_f32_32x32x16_bf16 v[2:17], v[128:131], v[124:127], v[2:17]
	s_waitcnt lgkmcnt(0)
	v_mfma_f32_32x32x16_bf16 v[34:49], v[184:187], v[136:139], v[34:49]
	v_mfma_f32_32x32x16_bf16 v[18:33], v[200:203], v[136:139], v[18:33]
	v_mfma_f32_32x32x16_bf16 v[50:65], v[200:203], v[140:143], v[50:65]
	v_mfma_f32_32x32x16_bf16 v[2:17], v[184:187], v[140:143], v[2:17]
	s_setprio 0
	s_waitcnt vmcnt(0)
	s_barrier
; #define MFMA(a, b, c) __builtin_amdgcn_mfma_f32_32x32x16_bf16((a), (b), (c), 0, 0, 0)
; template <bool SWAP>
; DI void gemm_block(const bf16_t* __restrict__ A, int lda, const bf16_t* __restrict__ Bt, int ldb, int K, f32x16 (&acc)[2][2], bf16_t* sA, bf16_t* sB) {
;     ...
;   for (int kt = 0; kt < nk; ++kt) {
;     const int cur = kt & 1;
;     const bool more = kt + 1 < nk;
;     if (more) {
;       const int k0 = (kt + 1) * 64;
; #pragma unroll
;       for (int i = 0; i < 4; ++i) { ra[i] = *(const u32x4*)(ga + (size_t)i * 32 * lda + k0); rb[i] = *(const u32x4*)(gb + (size_t)i * 32 * ldb + k0); }
;     }
;     const bf16_t* ab = sA + cur * 128 * LDT + (64 * wr + l32) * LDT + h * 8;
;     const bf16_t* bb = sB + cur * 128 * LDT + (64 * wc + l32) * LDT + h * 8;
;     __builtin_amdgcn_s_setprio(1);
;     __builtin_amdgcn_iglp_opt(0);
; #pragma unroll
;     for (int ks = 0; ks < 4; ++ks) {
;       const bf16x8 a0 = *(const bf16x8*)(ab + ks * 16), a1 = *(const bf16x8*)(ab + 32 * LDT + ks * 16);
;       const bf16x8 b0 = *(const bf16x8*)(bb + ks * 16), b1 = *(const bf16x8*)(bb + 32 * LDT + ks * 16);
;       if (!SWAP) {
;         acc[0][0] = MFMA(a0, b0, acc[0][0]); acc[0][1] = MFMA(a0, b1, acc[0][1]);
;         acc[1][0] = MFMA(a1, b0, acc[1][0]); acc[1][1] = MFMA(a1, b1, acc[1][1]);
;       } else {
;         acc[0][0] = MFMA(b0, a0, acc[0][0]); acc[0][1] = MFMA(b1, a0, acc[0][1]);
;         acc[1][0] = MFMA(b0, a1, acc[1][0]); acc[1][1] = MFMA(b1, a1, acc[1][1]);
;       }
;     }
;     __builtin_amdgcn_s_setprio(0);
;     if (more) {
;       const int nb = (cur ^ 1) * 128 * LDT;
; #pragma unroll
;       for (int i = 0; i < 4; ++i) { *(u32x4*)(sA + nb + soff + i * 32 * LDT) = ra[i]; *(u32x4*)(sB + nb + soff + i * 32 * LDT) = rb[i]; }
;     }
;     __syncthreads();
;   }
	ds_read_b128 v[120:123], v204 offset:32768
	ds_read_b128 v[128:131], v208 offset:32768
	ds_read_b128 v[132:135], v208 offset:36864
	ds_read_b128 v[124:127], v204 offset:36864
	ds_read_b128 v[136:139], v205 offset:32768
	ds_read_b128 v[184:187], v209 offset:32768
	ds_read_b128 v[200:203], v209 offset:36864
	ds_read_b128 v[140:143], v205 offset:36864
	s_setprio 1
	s_waitcnt lgkmcnt(4)
	s_add_u32 m0, s100, 1280
	v_mfma_f32_32x32x16_bf16 v[34:49], v[128:131], v[120:123], v[34:49]
	global_load_lds_dwordx4 v[68:69], off offset:768
	s_add_u32 m0, s100, 17664
	v_mfma_f32_32x32x16_bf16 v[18:33], v[132:135], v[120:123], v[18:33]
	global_load_lds_dwordx4 v[70:71], off offset:768
	s_add_u32 m0, s100, 5376
	v_mfma_f32_32x32x16_bf16 v[50:65], v[132:135], v[124:127], v[50:65]
	global_load_lds_dwordx4 v[72:73], off offset:768
	s_add_u32 m0, s100, 21760
	v_mfma_f32_32x32x16_bf16 v[2:17], v[128:131], v[124:127], v[2:17]
	global_load_lds_dwordx4 v[74:75], off offset:768
	ds_read_b128 v[120:123], v206 offset:32768
	ds_read_b128 v[128:131], v210 offset:32768
	ds_read_b128 v[132:135], v210 offset:36864
	ds_read_b128 v[124:127], v206 offset:36864
	s_waitcnt lgkmcnt(4)
	s_add_u32 m0, s100, 9472
	v_mfma_f32_32x32x16_bf16 v[34:49], v[184:187], v[136:139], v[34:49]
	global_load_lds_dwordx4 v[76:77], off offset:768
	s_add_u32 m0, s100, 25856
	v_mfma_f32_32x32x16_bf16 v[18:33], v[200:203], v[136:139], v[18:33]
	global_load_lds_dwordx4 v[78:79], off offset:768
	s_add_u32 m0, s100, 13568
	v_mfma_f32_32x32x16_bf16 v[50:65], v[200:203], v[140:143], v[50:65]
	global_load_lds_dwordx4 v[80:81], off offset:768
	s_add_u32 m0, s100, 29952
	v_mfma_f32_32x32x16_bf16 v[2:17], v[184:187], v[140:143], v[2:17]
	global_load_lds_dwordx4 v[82:83], off offset:768
	ds_read_b128 v[136:139], v207 offset:32768
	ds_read_b128 v[184:187], v211 offset:32768
	ds_read_b128 v[200:203], v211 offset:36864
	ds_read_b128 v[140:143], v207 offset:36864
	s_waitcnt lgkmcnt(4)
	v_mfma_f32_32x32x16_bf16 v[34:49], v[128:131], v[120:123], v[34:49]
	v_mfma_f32_32x32x16_bf16 v[18:33], v[132:135], v[120:123], v[18:33]
	v_mfma_f32_32x32x16_bf16 v[50:65], v[132:135], v[124:127], v[50:65]
	v_mfma_f32_32x32x16_bf16 v[2:17], v[128:131], v[124:127], v[2:17]
	s_waitcnt lgkmcnt(0)
	v_mfma_f32_32x32x16_bf16 v[34:49], v[184:187], v[136:139], v[34:49]
	v_mfma_f32_32x32x16_bf16 v[18:33], v[200:203], v[136:139], v[18:33]
	v_mfma_f32_32x32x16_bf16 v[50:65], v[200:203], v[140:143], v[50:65]
	v_mfma_f32_32x32x16_bf16 v[2:17], v[184:187], v[140:143], v[2:17]
	s_setprio 0
	s_waitcnt vmcnt(0)
	s_barrier
	ds_read_b128 v[120:123], v204
	ds_read_b128 v[128:131], v208
	ds_read_b128 v[132:135], v208 offset:4096
	ds_read_b128 v[124:127], v204 offset:4096
	ds_read_b128 v[136:139], v205
	ds_read_b128 v[184:187], v209
	ds_read_b128 v[200:203], v209 offset:4096
	ds_read_b128 v[140:143], v205 offset:4096
	s_setprio 1
	s_waitcnt lgkmcnt(4)
	s_add_u32 m0, s100, 33920
	v_mfma_f32_32x32x16_bf16 v[34:49], v[128:131], v[120:123], v[34:49]
	global_load_lds_dwordx4 v[68:69], off offset:896
	s_add_u32 m0, s100, 50304
	v_mfma_f32_32x32x16_bf16 v[18:33], v[132:135], v[120:123], v[18:33]
	global_load_lds_dwordx4 v[70:71], off offset:896
	s_add_u32 m0, s100, 38016
	v_mfma_f32_32x32x16_bf16 v[50:65], v[132:135], v[124:127], v[50:65]
	global_load_lds_dwordx4 v[72:73], off offset:896
	s_add_u32 m0, s100, 54400
	v_mfma_f32_32x32x16_bf16 v[2:17], v[128:131], v[124:127], v[2:17]
	global_load_lds_dwordx4 v[74:75], off offset:896
	ds_read_b128 v[120:123], v206
	ds_read_b128 v[128:131], v210
	ds_read_b128 v[132:135], v210 offset:4096
	ds_read_b128 v[124:127], v206 offset:4096
	s_waitcnt lgkmcnt(4)
	s_add_u32 m0, s100, 42112
	v_mfma_f32_32x32x16_bf16 v[34:49], v[184:187], v[136:139], v[34:49]
	global_load_lds_dwordx4 v[76:77], off offset:896
	s_add_u32 m0, s100, 58496
	v_mfma_f32_32x32x16_bf16 v[18:33], v[200:203], v[136:139], v[18:33]
	global_load_lds_dwordx4 v[78:79], off offset:896
	s_add_u32 m0, s100, 46208
	v_mfma_f32_32x32x16_bf16 v[50:65], v[200:203], v[140:143], v[50:65]
	global_load_lds_dwordx4 v[80:81], off offset:896
	s_add_u32 m0, s100, 62592
	v_mfma_f32_32x32x16_bf16 v[2:17], v[184:187], v[140:143], v[2:17]
	global_load_lds_dwordx4 v[82:83], off offset:896
	ds_read_b128 v[136:139], v207
	ds_read_b128 v[184:187], v211
	ds_read_b128 v[200:203], v211 offset:4096
	ds_read_b128 v[140:143], v207 offset:4096
	s_waitcnt lgkmcnt(4)
	v_mfma_f32_32x32x16_bf16 v[34:49], v[128:131], v[120:123], v[34:49]
	v_mfma_f32_32x32x16_bf16 v[18:33], v[132:135], v[120:123], v[18:33]
	v_mfma_f32_32x32x16_bf16 v[50:65], v[132:135], v[124:127], v[50:65]
	v_mfma_f32_32x32x16_bf16 v[2:17], v[128:131], v[124:127], v[2:17]
	s_waitcnt lgkmcnt(0)
	v_mfma_f32_32x32x16_bf16 v[34:49], v[184:187], v[136:139], v[34:49]
	v_mfma_f32_32x32x16_bf16 v[18:33], v[200:203], v[136:139], v[18:33]
	v_mfma_f32_32x32x16_bf16 v[50:65], v[200:203], v[140:143], v[50:65]
	v_mfma_f32_32x32x16_bf16 v[2:17], v[184:187], v[140:143], v[2:17]
	s_setprio 0
	s_waitcnt vmcnt(0)
	s_barrier
; #define MFMA(a, b, c) __builtin_amdgcn_mfma_f32_32x32x16_bf16((a), (b), (c), 0, 0, 0)
; template <bool SWAP>
; DI void gemm_block(const bf16_t* __restrict__ A, int lda, const bf16_t* __restrict__ Bt, int ldb, int K, f32x16 (&acc)[2][2], bf16_t* sA, bf16_t* sB) {
;     ...
;   for (int kt = 0; kt < nk; ++kt) {
;     const int cur = kt & 1;
;     const bool more = kt + 1 < nk;
;     if (more) {
;       const int k0 = (kt + 1) * 64;
; #pragma unroll
;       for (int i = 0; i < 4; ++i) { ra[i] = *(const u32x4*)(ga + (size_t)i * 32 * lda + k0); rb[i] = *(const u32x4*)(gb + (size_t)i * 32 * ldb + k0); }
;     }
;     const bf16_t* ab = sA + cur * 128 * LDT + (64 * wr + l32) * LDT + h * 8;
;     const bf16_t* bb = sB + cur * 128 * LDT + (64 * wc + l32) * LDT + h * 8;
;     __builtin_amdgcn_s_setprio(1);
;     __builtin_amdgcn_iglp_opt(0);
; #pragma unroll
;     for (int ks = 0; ks < 4; ++ks) {
;       const bf16x8 a0 = *(const bf16x8*)(ab + ks * 16), a1 = *(const bf16x8*)(ab + 32 * LDT + ks * 16);
;       const bf16x8 b0 = *(const bf16x8*)(bb + ks * 16), b1 = *(const bf16x8*)(bb + 32 * LDT + ks * 16);
;       if (!SWAP) {
;         acc[0][0] = MFMA(a0, b0, acc[0][0]); acc[0][1] = MFMA(a0, b1, acc[0][1]);
;         acc[1][0] = MFMA(a1, b0, acc[1][0]); acc[1][1] = MFMA(a1, b1, acc[1][1]);
;       } else {
;         acc[0][0] = MFMA(b0, a0, acc[0][0]); acc[0][1] = MFMA(b1, a0, acc[0][1]);
;         acc[1][0] = MFMA(b0, a1, acc[1][0]); acc[1][1] = MFMA(b1, a1, acc[1][1]);
;       }
;     }
;     __builtin_amdgcn_s_setprio(0);
;     if (more) {
;       const int nb = (cur ^ 1) * 128 * LDT;
; #pragma unroll
;       for (int i = 0; i < 4; ++i) { *(u32x4*)(sA + nb + soff + i * 32 * LDT) = ra[i]; *(u32x4*)(sB + nb + soff + i * 32 * LDT) = rb[i]; }
;     }
;     __syncthreads();
;   }
	ds_read_b128 v[120:123], v204 offset:32768
	ds_read_b128 v[128:131], v208 offset:32768
	ds_read_b128 v[132:135], v208 offset:36864
	ds_read_b128 v[124:127], v204 offset:36864
	ds_read_b128 v[136:139], v205 offset:32768
	ds_read_b128 v[184:187], v209 offset:32768
	ds_read_b128 v[200:203], v209 offset:36864
	ds_read_b128 v[140:143], v205 offset:36864
	s_setprio 1
	s_waitcnt lgkmcnt(4)
	s_add_u32 m0, s100, 1024
	v_mfma_f32_32x32x16_bf16 v[34:49], v[128:131], v[120:123], v[34:49]
	global_load_lds_dwordx4 v[68:69], off offset:1024
	s_add_u32 m0, s100, 17408
	v_mfma_f32_32x32x16_bf16 v[18:33], v[132:135], v[120:123], v[18:33]
	global_load_lds_dwordx4 v[70:71], off offset:1024
	s_add_u32 m0, s100, 5120
	v_mfma_f32_32x32x16_bf16 v[50:65], v[132:135], v[124:127], v[50:65]
	global_load_lds_dwordx4 v[72:73], off offset:1024
	s_add_u32 m0, s100, 21504
	v_mfma_f32_32x32x16_bf16 v[2:17], v[128:131], v[124:127], v[2:17]
	global_load_lds_dwordx4 v[74:75], off offset:1024
	ds_read_b128 v[120:123], v206 offset:32768
	ds_read_b128 v[128:131], v210 offset:32768
	ds_read_b128 v[132:135], v210 offset:36864
	ds_read_b128 v[124:127], v206 offset:36864
	s_waitcnt lgkmcnt(4)
	s_add_u32 m0, s100, 9216
	v_mfma_f32_32x32x16_bf16 v[34:49], v[184:187], v[136:139], v[34:49]
	global_load_lds_dwordx4 v[76:77], off offset:1024
	s_add_u32 m0, s100, 25600
	v_mfma_f32_32x32x16_bf16 v[18:33], v[200:203], v[136:139], v[18:33]
	global_load_lds_dwordx4 v[78:79], off offset:1024
	s_add_u32 m0, s100, 13312
	v_mfma_f32_32x32x16_bf16 v[50:65], v[200:203], v[140:143], v[50:65]
	global_load_lds_dwordx4 v[80:81], off offset:1024
	s_add_u32 m0, s100, 29696
	v_mfma_f32_32x32x16_bf16 v[2:17], v[184:187], v[140:143], v[2:17]
	global_load_lds_dwordx4 v[82:83], off offset:1024
	ds_read_b128 v[136:139], v207 offset:32768
	ds_read_b128 v[184:187], v211 offset:32768
	ds_read_b128 v[200:203], v211 offset:36864
	ds_read_b128 v[140:143], v207 offset:36864
	s_waitcnt lgkmcnt(4)
	v_mfma_f32_32x32x16_bf16 v[34:49], v[128:131], v[120:123], v[34:49]
	v_mfma_f32_32x32x16_bf16 v[18:33], v[132:135], v[120:123], v[18:33]
	v_mfma_f32_32x32x16_bf16 v[50:65], v[132:135], v[124:127], v[50:65]
	v_mfma_f32_32x32x16_bf16 v[2:17], v[128:131], v[124:127], v[2:17]
	s_waitcnt lgkmcnt(0)
	v_mfma_f32_32x32x16_bf16 v[34:49], v[184:187], v[136:139], v[34:49]
	v_mfma_f32_32x32x16_bf16 v[18:33], v[200:203], v[136:139], v[18:33]
	v_mfma_f32_32x32x16_bf16 v[50:65], v[200:203], v[140:143], v[50:65]
	v_mfma_f32_32x32x16_bf16 v[2:17], v[184:187], v[140:143], v[2:17]
	s_setprio 0
	s_waitcnt vmcnt(0)
	s_barrier
	ds_read_b128 v[120:123], v204
	ds_read_b128 v[128:131], v208
	ds_read_b128 v[132:135], v208 offset:4096
	ds_read_b128 v[124:127], v204 offset:4096
	ds_read_b128 v[136:139], v205
	ds_read_b128 v[184:187], v209
	ds_read_b128 v[200:203], v209 offset:4096
	ds_read_b128 v[140:143], v205 offset:4096
	s_setprio 1
	s_waitcnt lgkmcnt(4)
	s_add_u32 m0, s100, 33664
	v_mfma_f32_32x32x16_bf16 v[34:49], v[128:131], v[120:123], v[34:49]
	global_load_lds_dwordx4 v[68:69], off offset:1152
	s_add_u32 m0, s100, 50048
	v_mfma_f32_32x32x16_bf16 v[18:33], v[132:135], v[120:123], v[18:33]
	global_load_lds_dwordx4 v[70:71], off offset:1152
	s_add_u32 m0, s100, 37760
	v_mfma_f32_32x32x16_bf16 v[50:65], v[132:135], v[124:127], v[50:65]
	global_load_lds_dwordx4 v[72:73], off offset:1152
	s_add_u32 m0, s100, 54144
	v_mfma_f32_32x32x16_bf16 v[2:17], v[128:131], v[124:127], v[2:17]
	global_load_lds_dwordx4 v[74:75], off offset:1152
	ds_read_b128 v[120:123], v206
	ds_read_b128 v[128:131], v210
	ds_read_b128 v[132:135], v210 offset:4096
	ds_read_b128 v[124:127], v206 offset:4096
	s_waitcnt lgkmcnt(4)
	s_add_u32 m0, s100, 41856
	v_mfma_f32_32x32x16_bf16 v[34:49], v[184:187], v[136:139], v[34:49]
	global_load_lds_dwordx4 v[76:77], off offset:1152
	s_add_u32 m0, s100, 58240
	v_mfma_f32_32x32x16_bf16 v[18:33], v[200:203], v[136:139], v[18:33]
	global_load_lds_dwordx4 v[78:79], off offset:1152
	s_add_u32 m0, s100, 45952
	v_mfma_f32_32x32x16_bf16 v[50:65], v[200:203], v[140:143], v[50:65]
	global_load_lds_dwordx4 v[80:81], off offset:1152
	s_add_u32 m0, s100, 62336
	v_mfma_f32_32x32x16_bf16 v[2:17], v[184:187], v[140:143], v[2:17]
	global_load_lds_dwordx4 v[82:83], off offset:1152
	ds_read_b128 v[136:139], v207
	ds_read_b128 v[184:187], v211
	ds_read_b128 v[200:203], v211 offset:4096
	ds_read_b128 v[140:143], v207 offset:4096
	s_waitcnt lgkmcnt(4)
	v_mfma_f32_32x32x16_bf16 v[34:49], v[128:131], v[120:123], v[34:49]
	v_mfma_f32_32x32x16_bf16 v[18:33], v[132:135], v[120:123], v[18:33]
	v_mfma_f32_32x32x16_bf16 v[50:65], v[132:135], v[124:127], v[50:65]
	v_mfma_f32_32x32x16_bf16 v[2:17], v[128:131], v[124:127], v[2:17]
	s_waitcnt lgkmcnt(0)
	v_mfma_f32_32x32x16_bf16 v[34:49], v[184:187], v[136:139], v[34:49]
	v_mfma_f32_32x32x16_bf16 v[18:33], v[200:203], v[136:139], v[18:33]
	v_mfma_f32_32x32x16_bf16 v[50:65], v[200:203], v[140:143], v[50:65]
	v_mfma_f32_32x32x16_bf16 v[2:17], v[184:187], v[140:143], v[2:17]
	s_setprio 0
	s_waitcnt vmcnt(0)
	s_barrier
; #define MFMA(a, b, c) __builtin_amdgcn_mfma_f32_32x32x16_bf16((a), (b), (c), 0, 0, 0)
; template <bool SWAP>
; DI void gemm_block(const bf16_t* __restrict__ A, int lda, const bf16_t* __restrict__ Bt, int ldb, int K, f32x16 (&acc)[2][2], bf16_t* sA, bf16_t* sB) {
;     ...
;   for (int kt = 0; kt < nk; ++kt) {
;     const int cur = kt & 1;
;     const bool more = kt + 1 < nk;
;     if (more) {
;       const int k0 = (kt + 1) * 64;
; #pragma unroll
;       for (int i = 0; i < 4; ++i) { ra[i] = *(const u32x4*)(ga + (size_t)i * 32 * lda + k0); rb[i] = *(const u32x4*)(gb + (size_t)i * 32 * ldb + k0); }
;     }
;     const bf16_t* ab = sA + cur * 128 * LDT + (64 * wr + l32) * LDT + h * 8;
;     const bf16_t* bb = sB + cur * 128 * LDT + (64 * wc + l32) * LDT + h * 8;
;     __builtin_amdgcn_s_setprio(1);
;     __builtin_amdgcn_iglp_opt(0);
; #pragma unroll
;     for (int ks = 0; ks < 4; ++ks) {
;       const bf16x8 a0 = *(const bf16x8*)(ab + ks * 16), a1 = *(const bf16x8*)(ab + 32 * LDT + ks * 16);
;       const bf16x8 b0 = *(const bf16x8*)(bb + ks * 16), b1 = *(const bf16x8*)(bb + 32 * LDT + ks * 16);
;       if (!SWAP) {
;         acc[0][0] = MFMA(a0, b0, acc[0][0]); acc[0][1] = MFMA(a0, b1, acc[0][1]);
;         acc[1][0] = MFMA(a1, b0, acc[1][0]); acc[1][1] = MFMA(a1, b1, acc[1][1]);
;       } else {
;         acc[0][0] = MFMA(b0, a0, acc[0][0]); acc[0][1] = MFMA(b1, a0, acc[0][1]);
;         acc[1][0] = MFMA(b0, a1, acc[1][0]); acc[1][1] = MFMA(b1, a1, acc[1][1]);
;       }
;     }
;     __builtin_amdgcn_s_setprio(0);
;     if (more) {
;       const int nb = (cur ^ 1) * 128 * LDT;
; #pragma unroll
;       for (int i = 0; i < 4; ++i) { *(u32x4*)(sA + nb + soff + i * 32 * LDT) = ra[i]; *(u32x4*)(sB + nb + soff + i * 32 * LDT) = rb[i]; }
;     }
;     __syncthreads();
;   }
	ds_read_b128 v[120:123], v204 offset:32768
	ds_read_b128 v[128:131], v208 offset:32768
	ds_read_b128 v[132:135], v208 offset:36864
	ds_read_b128 v[124:127], v204 offset:36864
	ds_read_b128 v[136:139], v205 offset:32768
	ds_read_b128 v[184:187], v209 offset:32768
	ds_read_b128 v[200:203], v209 offset:36864
	ds_read_b128 v[140:143], v205 offset:36864
	s_setprio 1
	s_waitcnt lgkmcnt(4)
	s_add_u32 m0, s100, 768
	v_mfma_f32_32x32x16_bf16 v[34:49], v[128:131], v[120:123], v[34:49]
	global_load_lds_dwordx4 v[68:69], off offset:1280
	s_add_u32 m0, s100, 17152
	v_mfma_f32_32x32x16_bf16 v[18:33], v[132:135], v[120:123], v[18:33]
	global_load_lds_dwordx4 v[70:71], off offset:1280
	s_add_u32 m0, s100, 4864
	v_mfma_f32_32x32x16_bf16 v[50:65], v[132:135], v[124:127], v[50:65]
	global_load_lds_dwordx4 v[72:73], off offset:1280
	s_add_u32 m0, s100, 21248
	v_mfma_f32_32x32x16_bf16 v[2:17], v[128:131], v[124:127], v[2:17]
	global_load_lds_dwordx4 v[74:75], off offset:1280
	ds_read_b128 v[120:123], v206 offset:32768
	ds_read_b128 v[128:131], v210 offset:32768
	ds_read_b128 v[132:135], v210 offset:36864
	ds_read_b128 v[124:127], v206 offset:36864
	s_waitcnt lgkmcnt(4)
	s_add_u32 m0, s100, 8960
	v_mfma_f32_32x32x16_bf16 v[34:49], v[184:187], v[136:139], v[34:49]
	global_load_lds_dwordx4 v[76:77], off offset:1280
	s_add_u32 m0, s100, 25344
	v_mfma_f32_32x32x16_bf16 v[18:33], v[200:203], v[136:139], v[18:33]
	global_load_lds_dwordx4 v[78:79], off offset:1280
	s_add_u32 m0, s100, 13056
	v_mfma_f32_32x32x16_bf16 v[50:65], v[200:203], v[140:143], v[50:65]
	global_load_lds_dwordx4 v[80:81], off offset:1280
	s_add_u32 m0, s100, 29440
	v_mfma_f32_32x32x16_bf16 v[2:17], v[184:187], v[140:143], v[2:17]
	global_load_lds_dwordx4 v[82:83], off offset:1280
	ds_read_b128 v[136:139], v207 offset:32768
	ds_read_b128 v[184:187], v211 offset:32768
	ds_read_b128 v[200:203], v211 offset:36864
	ds_read_b128 v[140:143], v207 offset:36864
	s_waitcnt lgkmcnt(4)
	v_mfma_f32_32x32x16_bf16 v[34:49], v[128:131], v[120:123], v[34:49]
	v_mfma_f32_32x32x16_bf16 v[18:33], v[132:135], v[120:123], v[18:33]
	v_mfma_f32_32x32x16_bf16 v[50:65], v[132:135], v[124:127], v[50:65]
	v_mfma_f32_32x32x16_bf16 v[2:17], v[128:131], v[124:127], v[2:17]
	s_waitcnt lgkmcnt(0)
	v_mfma_f32_32x32x16_bf16 v[34:49], v[184:187], v[136:139], v[34:49]
	v_mfma_f32_32x32x16_bf16 v[18:33], v[200:203], v[136:139], v[18:33]
	v_mfma_f32_32x32x16_bf16 v[50:65], v[200:203], v[140:143], v[50:65]
	v_mfma_f32_32x32x16_bf16 v[2:17], v[184:187], v[140:143], v[2:17]
	s_setprio 0
	s_waitcnt vmcnt(0)
	s_barrier
	ds_read_b128 v[120:123], v204
	ds_read_b128 v[128:131], v208
	ds_read_b128 v[132:135], v208 offset:4096
	ds_read_b128 v[124:127], v204 offset:4096
	ds_read_b128 v[136:139], v205
	ds_read_b128 v[184:187], v209
	ds_read_b128 v[200:203], v209 offset:4096
	ds_read_b128 v[140:143], v205 offset:4096
	s_setprio 1
	s_waitcnt lgkmcnt(4)
	s_add_u32 m0, s100, 33408
	v_mfma_f32_32x32x16_bf16 v[34:49], v[128:131], v[120:123], v[34:49]
	global_load_lds_dwordx4 v[68:69], off offset:1408
	s_add_u32 m0, s100, 49792
	v_mfma_f32_32x32x16_bf16 v[18:33], v[132:135], v[120:123], v[18:33]
	global_load_lds_dwordx4 v[70:71], off offset:1408
	s_add_u32 m0, s100, 37504
	v_mfma_f32_32x32x16_bf16 v[50:65], v[132:135], v[124:127], v[50:65]
	global_load_lds_dwordx4 v[72:73], off offset:1408
	s_add_u32 m0, s100, 53888
	v_mfma_f32_32x32x16_bf16 v[2:17], v[128:131], v[124:127], v[2:17]
	global_load_lds_dwordx4 v[74:75], off offset:1408
	ds_read_b128 v[120:123], v206
	ds_read_b128 v[128:131], v210
	ds_read_b128 v[132:135], v210 offset:4096
	ds_read_b128 v[124:127], v206 offset:4096
	s_waitcnt lgkmcnt(4)
	s_add_u32 m0, s100, 41600
	v_mfma_f32_32x32x16_bf16 v[34:49], v[184:187], v[136:139], v[34:49]
	global_load_lds_dwordx4 v[76:77], off offset:1408
	s_add_u32 m0, s100, 57984
	v_mfma_f32_32x32x16_bf16 v[18:33], v[200:203], v[136:139], v[18:33]
	global_load_lds_dwordx4 v[78:79], off offset:1408
	s_add_u32 m0, s100, 45696
	v_mfma_f32_32x32x16_bf16 v[50:65], v[200:203], v[140:143], v[50:65]
	global_load_lds_dwordx4 v[80:81], off offset:1408
	s_add_u32 m0, s100, 62080
	v_mfma_f32_32x32x16_bf16 v[2:17], v[184:187], v[140:143], v[2:17]
	global_load_lds_dwordx4 v[82:83], off offset:1408
	ds_read_b128 v[136:139], v207
	ds_read_b128 v[184:187], v211
	ds_read_b128 v[200:203], v211 offset:4096
	ds_read_b128 v[140:143], v207 offset:4096
	s_waitcnt lgkmcnt(4)
	v_mfma_f32_32x32x16_bf16 v[34:49], v[128:131], v[120:123], v[34:49]
	v_mfma_f32_32x32x16_bf16 v[18:33], v[132:135], v[120:123], v[18:33]
	v_mfma_f32_32x32x16_bf16 v[50:65], v[132:135], v[124:127], v[50:65]
	v_mfma_f32_32x32x16_bf16 v[2:17], v[128:131], v[124:127], v[2:17]
	s_waitcnt lgkmcnt(0)
	v_mfma_f32_32x32x16_bf16 v[34:49], v[184:187], v[136:139], v[34:49]
	v_mfma_f32_32x32x16_bf16 v[18:33], v[200:203], v[136:139], v[18:33]
	v_mfma_f32_32x32x16_bf16 v[50:65], v[200:203], v[140:143], v[50:65]
	v_mfma_f32_32x32x16_bf16 v[2:17], v[184:187], v[140:143], v[2:17]
	s_setprio 0
	s_waitcnt vmcnt(0)
	s_barrier
; #define MFMA(a, b, c) __builtin_amdgcn_mfma_f32_32x32x16_bf16((a), (b), (c), 0, 0, 0)
; template <bool SWAP>
; DI void gemm_block(const bf16_t* __restrict__ A, int lda, const bf16_t* __restrict__ Bt, int ldb, int K, f32x16 (&acc)[2][2], bf16_t* sA, bf16_t* sB) {
;     ...
;   for (int kt = 0; kt < nk; ++kt) {
;     const int cur = kt & 1;
;     const bool more = kt + 1 < nk;
;     if (more) {
;       const int k0 = (kt + 1) * 64;
; #pragma unroll
;       for (int i = 0; i < 4; ++i) { ra[i] = *(const u32x4*)(ga + (size_t)i * 32 * lda + k0); rb[i] = *(const u32x4*)(gb + (size_t)i * 32 * ldb + k0); }
;     }
;     const bf16_t* ab = sA + cur * 128 * LDT + (64 * wr + l32) * LDT + h * 8;
;     const bf16_t* bb = sB + cur * 128 * LDT + (64 * wc + l32) * LDT + h * 8;
;     __builtin_amdgcn_s_setprio(1);
;     __builtin_amdgcn_iglp_opt(0);
; #pragma unroll
;     for (int ks = 0; ks < 4; ++ks) {
;       const bf16x8 a0 = *(const bf16x8*)(ab + ks * 16), a1 = *(const bf16x8*)(ab + 32 * LDT + ks * 16);
;       const bf16x8 b0 = *(const bf16x8*)(bb + ks * 16), b1 = *(const bf16x8*)(bb + 32 * LDT + ks * 16);
;       if (!SWAP) {
;         acc[0][0] = MFMA(a0, b0, acc[0][0]); acc[0][1] = MFMA(a0, b1, acc[0][1]);
;         acc[1][0] = MFMA(a1, b0, acc[1][0]); acc[1][1] = MFMA(a1, b1, acc[1][1]);
;       } else {
;         acc[0][0] = MFMA(b0, a0, acc[0][0]); acc[0][1] = MFMA(b1, a0, acc[0][1]);
;         acc[1][0] = MFMA(b0, a1, acc[1][0]); acc[1][1] = MFMA(b1, a1, acc[1][1]);
;       }
;     }
;     __builtin_amdgcn_s_setprio(0);
;     if (more) {
;       const int nb = (cur ^ 1) * 128 * LDT;
; #pragma unroll
;       for (int i = 0; i < 4; ++i) { *(u32x4*)(sA + nb + soff + i * 32 * LDT) = ra[i]; *(u32x4*)(sB + nb + soff + i * 32 * LDT) = rb[i]; }
;     }
;     __syncthreads();
;   }
	ds_read_b128 v[120:123], v204 offset:32768
	ds_read_b128 v[128:131], v208 offset:32768
	ds_read_b128 v[132:135], v208 offset:36864
	ds_read_b128 v[124:127], v204 offset:36864
	ds_read_b128 v[136:139], v205 offset:32768
	ds_read_b128 v[184:187], v209 offset:32768
	ds_read_b128 v[200:203], v209 offset:36864
	ds_read_b128 v[140:143], v205 offset:36864
	s_setprio 1
	s_waitcnt lgkmcnt(4)
	s_add_u32 m0, s100, 512
	v_mfma_f32_32x32x16_bf16 v[34:49], v[128:131], v[120:123], v[34:49]
	global_load_lds_dwordx4 v[68:69], off offset:1536
	s_add_u32 m0, s100, 16896
	v_mfma_f32_32x32x16_bf16 v[18:33], v[132:135], v[120:123], v[18:33]
	global_load_lds_dwordx4 v[70:71], off offset:1536
	s_add_u32 m0, s100, 4608
	v_mfma_f32_32x32x16_bf16 v[50:65], v[132:135], v[124:127], v[50:65]
	global_load_lds_dwordx4 v[72:73], off offset:1536
	s_add_u32 m0, s100, 20992
	v_mfma_f32_32x32x16_bf16 v[2:17], v[128:131], v[124:127], v[2:17]
	global_load_lds_dwordx4 v[74:75], off offset:1536
	ds_read_b128 v[120:123], v206 offset:32768
	ds_read_b128 v[128:131], v210 offset:32768
	ds_read_b128 v[132:135], v210 offset:36864
	ds_read_b128 v[124:127], v206 offset:36864
	s_waitcnt lgkmcnt(4)
	s_add_u32 m0, s100, 8704
	v_mfma_f32_32x32x16_bf16 v[34:49], v[184:187], v[136:139], v[34:49]
	global_load_lds_dwordx4 v[76:77], off offset:1536
	s_add_u32 m0, s100, 25088
	v_mfma_f32_32x32x16_bf16 v[18:33], v[200:203], v[136:139], v[18:33]
	global_load_lds_dwordx4 v[78:79], off offset:1536
	s_add_u32 m0, s100, 12800
	v_mfma_f32_32x32x16_bf16 v[50:65], v[200:203], v[140:143], v[50:65]
	global_load_lds_dwordx4 v[80:81], off offset:1536
	s_add_u32 m0, s100, 29184
	v_mfma_f32_32x32x16_bf16 v[2:17], v[184:187], v[140:143], v[2:17]
	global_load_lds_dwordx4 v[82:83], off offset:1536
	ds_read_b128 v[136:139], v207 offset:32768
	ds_read_b128 v[184:187], v211 offset:32768
	ds_read_b128 v[200:203], v211 offset:36864
	ds_read_b128 v[140:143], v207 offset:36864
	s_waitcnt lgkmcnt(4)
	v_mfma_f32_32x32x16_bf16 v[34:49], v[128:131], v[120:123], v[34:49]
	v_mfma_f32_32x32x16_bf16 v[18:33], v[132:135], v[120:123], v[18:33]
	v_mfma_f32_32x32x16_bf16 v[50:65], v[132:135], v[124:127], v[50:65]
	v_mfma_f32_32x32x16_bf16 v[2:17], v[128:131], v[124:127], v[2:17]
	s_waitcnt lgkmcnt(0)
	v_mfma_f32_32x32x16_bf16 v[34:49], v[184:187], v[136:139], v[34:49]
	v_mfma_f32_32x32x16_bf16 v[18:33], v[200:203], v[136:139], v[18:33]
	v_mfma_f32_32x32x16_bf16 v[50:65], v[200:203], v[140:143], v[50:65]
	v_mfma_f32_32x32x16_bf16 v[2:17], v[184:187], v[140:143], v[2:17]
	s_setprio 0
	s_waitcnt vmcnt(0)
	s_barrier
	ds_read_b128 v[120:123], v204
	ds_read_b128 v[128:131], v208
	ds_read_b128 v[132:135], v208 offset:4096
	ds_read_b128 v[124:127], v204 offset:4096
	ds_read_b128 v[136:139], v205
	ds_read_b128 v[184:187], v209
	ds_read_b128 v[200:203], v209 offset:4096
	ds_read_b128 v[140:143], v205 offset:4096
	s_setprio 1
	s_waitcnt lgkmcnt(4)
	s_add_u32 m0, s100, 33152
	v_mfma_f32_32x32x16_bf16 v[34:49], v[128:131], v[120:123], v[34:49]
	global_load_lds_dwordx4 v[68:69], off offset:1664
	s_add_u32 m0, s100, 49536
	v_mfma_f32_32x32x16_bf16 v[18:33], v[132:135], v[120:123], v[18:33]
	global_load_lds_dwordx4 v[70:71], off offset:1664
	s_add_u32 m0, s100, 37248
	v_mfma_f32_32x32x16_bf16 v[50:65], v[132:135], v[124:127], v[50:65]
	global_load_lds_dwordx4 v[72:73], off offset:1664
	s_add_u32 m0, s100, 53632
	v_mfma_f32_32x32x16_bf16 v[2:17], v[128:131], v[124:127], v[2:17]
	global_load_lds_dwordx4 v[74:75], off offset:1664
	ds_read_b128 v[120:123], v206
	ds_read_b128 v[128:131], v210
	ds_read_b128 v[132:135], v210 offset:4096
	ds_read_b128 v[124:127], v206 offset:4096
	s_waitcnt lgkmcnt(4)
	s_add_u32 m0, s100, 41344
	v_mfma_f32_32x32x16_bf16 v[34:49], v[184:187], v[136:139], v[34:49]
	global_load_lds_dwordx4 v[76:77], off offset:1664
	s_add_u32 m0, s100, 57728
	v_mfma_f32_32x32x16_bf16 v[18:33], v[200:203], v[136:139], v[18:33]
	global_load_lds_dwordx4 v[78:79], off offset:1664
	s_add_u32 m0, s100, 45440
	v_mfma_f32_32x32x16_bf16 v[50:65], v[200:203], v[140:143], v[50:65]
	global_load_lds_dwordx4 v[80:81], off offset:1664
	s_add_u32 m0, s100, 61824
	v_mfma_f32_32x32x16_bf16 v[2:17], v[184:187], v[140:143], v[2:17]
	global_load_lds_dwordx4 v[82:83], off offset:1664
	ds_read_b128 v[136:139], v207
	ds_read_b128 v[184:187], v211
	ds_read_b128 v[200:203], v211 offset:4096
	ds_read_b128 v[140:143], v207 offset:4096
	s_waitcnt lgkmcnt(4)
	v_mfma_f32_32x32x16_bf16 v[34:49], v[128:131], v[120:123], v[34:49]
	v_mfma_f32_32x32x16_bf16 v[18:33], v[132:135], v[120:123], v[18:33]
	v_mfma_f32_32x32x16_bf16 v[50:65], v[132:135], v[124:127], v[50:65]
	v_mfma_f32_32x32x16_bf16 v[2:17], v[128:131], v[124:127], v[2:17]
	s_waitcnt lgkmcnt(0)
	v_mfma_f32_32x32x16_bf16 v[34:49], v[184:187], v[136:139], v[34:49]
	v_mfma_f32_32x32x16_bf16 v[18:33], v[200:203], v[136:139], v[18:33]
	v_mfma_f32_32x32x16_bf16 v[50:65], v[200:203], v[140:143], v[50:65]
	v_mfma_f32_32x32x16_bf16 v[2:17], v[184:187], v[140:143], v[2:17]
	s_setprio 0
	s_waitcnt vmcnt(0)
	s_barrier
; #define MFMA(a, b, c) __builtin_amdgcn_mfma_f32_32x32x16_bf16((a), (b), (c), 0, 0, 0)
; template <bool SWAP>
; DI void gemm_block(const bf16_t* __restrict__ A, int lda, const bf16_t* __restrict__ Bt, int ldb, int K, f32x16 (&acc)[2][2], bf16_t* sA, bf16_t* sB) {
;     ...
;   for (int kt = 0; kt < nk; ++kt) {
;     const int cur = kt & 1;
;     const bool more = kt + 1 < nk;
;     if (more) {
;       const int k0 = (kt + 1) * 64;
; #pragma unroll
;       for (int i = 0; i < 4; ++i) { ra[i] = *(const u32x4*)(ga + (size_t)i * 32 * lda + k0); rb[i] = *(const u32x4*)(gb + (size_t)i * 32 * ldb + k0); }
;     }
;     const bf16_t* ab = sA + cur * 128 * LDT + (64 * wr + l32) * LDT + h * 8;
;     const bf16_t* bb = sB + cur * 128 * LDT + (64 * wc + l32) * LDT + h * 8;
;     __builtin_amdgcn_s_setprio(1);
;     __builtin_amdgcn_iglp_opt(0);
; #pragma unroll
;     for (int ks = 0; ks < 4; ++ks) {
;       const bf16x8 a0 = *(const bf16x8*)(ab + ks * 16), a1 = *(const bf16x8*)(ab + 32 * LDT + ks * 16);
;       const bf16x8 b0 = *(const bf16x8*)(bb + ks * 16), b1 = *(const bf16x8*)(bb + 32 * LDT + ks * 16);
;       if (!SWAP) {
;         acc[0][0] = MFMA(a0, b0, acc[0][0]); acc[0][1] = MFMA(a0, b1, acc[0][1]);
;         acc[1][0] = MFMA(a1, b0, acc[1][0]); acc[1][1] = MFMA(a1, b1, acc[1][1]);
;       } else {
;         acc[0][0] = MFMA(b0, a0, acc[0][0]); acc[0][1] = MFMA(b1, a0, acc[0][1]);
;         acc[1][0] = MFMA(b0, a1, acc[1][0]); acc[1][1] = MFMA(b1, a1, acc[1][1]);
;       }
;     }
;     __builtin_amdgcn_s_setprio(0);
;     if (more) {
;       const int nb = (cur ^ 1) * 128 * LDT;
; #pragma unroll
;       for (int i = 0; i < 4; ++i) { *(u32x4*)(sA + nb + soff + i * 32 * LDT) = ra[i]; *(u32x4*)(sB + nb + soff + i * 32 * LDT) = rb[i]; }
;     }
;     __syncthreads();
;   }
	ds_read_b128 v[120:123], v204 offset:32768
	ds_read_b128 v[128:131], v208 offset:32768
	ds_read_b128 v[132:135], v208 offset:36864
	ds_read_b128 v[124:127], v204 offset:36864
	ds_read_b128 v[136:139], v205 offset:32768
	ds_read_b128 v[184:187], v209 offset:32768
	ds_read_b128 v[200:203], v209 offset:36864
	ds_read_b128 v[140:143], v205 offset:36864
	s_setprio 1
	s_waitcnt lgkmcnt(4)
	s_add_u32 m0, s100, 256
	v_mfma_f32_32x32x16_bf16 v[34:49], v[128:131], v[120:123], v[34:49]
	global_load_lds_dwordx4 v[68:69], off offset:1792
	s_add_u32 m0, s100, 16640
	v_mfma_f32_32x32x16_bf16 v[18:33], v[132:135], v[120:123], v[18:33]
	global_load_lds_dwordx4 v[70:71], off offset:1792
	s_add_u32 m0, s100, 4352
	v_mfma_f32_32x32x16_bf16 v[50:65], v[132:135], v[124:127], v[50:65]
	global_load_lds_dwordx4 v[72:73], off offset:1792
	s_add_u32 m0, s100, 20736
	v_mfma_f32_32x32x16_bf16 v[2:17], v[128:131], v[124:127], v[2:17]
	global_load_lds_dwordx4 v[74:75], off offset:1792
	ds_read_b128 v[120:123], v206 offset:32768
	ds_read_b128 v[128:131], v210 offset:32768
	ds_read_b128 v[132:135], v210 offset:36864
	ds_read_b128 v[124:127], v206 offset:36864
	s_waitcnt lgkmcnt(4)
	s_add_u32 m0, s100, 8448
	v_mfma_f32_32x32x16_bf16 v[34:49], v[184:187], v[136:139], v[34:49]
	global_load_lds_dwordx4 v[76:77], off offset:1792
	s_add_u32 m0, s100, 24832
	v_mfma_f32_32x32x16_bf16 v[18:33], v[200:203], v[136:139], v[18:33]
	global_load_lds_dwordx4 v[78:79], off offset:1792
	s_add_u32 m0, s100, 12544
	v_mfma_f32_32x32x16_bf16 v[50:65], v[200:203], v[140:143], v[50:65]
	global_load_lds_dwordx4 v[80:81], off offset:1792
	s_add_u32 m0, s100, 28928
	v_mfma_f32_32x32x16_bf16 v[2:17], v[184:187], v[140:143], v[2:17]
	global_load_lds_dwordx4 v[82:83], off offset:1792
	ds_read_b128 v[136:139], v207 offset:32768
	ds_read_b128 v[184:187], v211 offset:32768
	ds_read_b128 v[200:203], v211 offset:36864
	ds_read_b128 v[140:143], v207 offset:36864
	s_waitcnt lgkmcnt(4)
	v_mfma_f32_32x32x16_bf16 v[34:49], v[128:131], v[120:123], v[34:49]
	v_mfma_f32_32x32x16_bf16 v[18:33], v[132:135], v[120:123], v[18:33]
	v_mfma_f32_32x32x16_bf16 v[50:65], v[132:135], v[124:127], v[50:65]
	v_mfma_f32_32x32x16_bf16 v[2:17], v[128:131], v[124:127], v[2:17]
	s_waitcnt lgkmcnt(0)
	v_mfma_f32_32x32x16_bf16 v[34:49], v[184:187], v[136:139], v[34:49]
	v_mfma_f32_32x32x16_bf16 v[18:33], v[200:203], v[136:139], v[18:33]
	v_mfma_f32_32x32x16_bf16 v[50:65], v[200:203], v[140:143], v[50:65]
	v_mfma_f32_32x32x16_bf16 v[2:17], v[184:187], v[140:143], v[2:17]
	s_setprio 0
	s_waitcnt vmcnt(0)
	s_barrier
	ds_read_b128 v[120:123], v204
	ds_read_b128 v[128:131], v208
	ds_read_b128 v[132:135], v208 offset:4096
	ds_read_b128 v[124:127], v204 offset:4096
	ds_read_b128 v[136:139], v205
	ds_read_b128 v[184:187], v209
	ds_read_b128 v[200:203], v209 offset:4096
	ds_read_b128 v[140:143], v205 offset:4096
	s_setprio 1
	s_waitcnt lgkmcnt(4)
	s_add_u32 m0, s100, 32896
	v_mfma_f32_32x32x16_bf16 v[34:49], v[128:131], v[120:123], v[34:49]
	global_load_lds_dwordx4 v[68:69], off offset:1920
	s_add_u32 m0, s100, 49280
	v_mfma_f32_32x32x16_bf16 v[18:33], v[132:135], v[120:123], v[18:33]
	global_load_lds_dwordx4 v[70:71], off offset:1920
	s_add_u32 m0, s100, 36992
	v_mfma_f32_32x32x16_bf16 v[50:65], v[132:135], v[124:127], v[50:65]
	global_load_lds_dwordx4 v[72:73], off offset:1920
	s_add_u32 m0, s100, 53376
	v_mfma_f32_32x32x16_bf16 v[2:17], v[128:131], v[124:127], v[2:17]
	global_load_lds_dwordx4 v[74:75], off offset:1920
	ds_read_b128 v[120:123], v206
	ds_read_b128 v[128:131], v210
	ds_read_b128 v[132:135], v210 offset:4096
	ds_read_b128 v[124:127], v206 offset:4096
	s_waitcnt lgkmcnt(4)
	s_add_u32 m0, s100, 41088
	v_mfma_f32_32x32x16_bf16 v[34:49], v[184:187], v[136:139], v[34:49]
	global_load_lds_dwordx4 v[76:77], off offset:1920
	s_add_u32 m0, s100, 57472
	v_mfma_f32_32x32x16_bf16 v[18:33], v[200:203], v[136:139], v[18:33]
	global_load_lds_dwordx4 v[78:79], off offset:1920
	s_add_u32 m0, s100, 45184
	v_mfma_f32_32x32x16_bf16 v[50:65], v[200:203], v[140:143], v[50:65]
	global_load_lds_dwordx4 v[80:81], off offset:1920
	s_add_u32 m0, s100, 61568
	v_mfma_f32_32x32x16_bf16 v[2:17], v[184:187], v[140:143], v[2:17]
	global_load_lds_dwordx4 v[82:83], off offset:1920
	ds_read_b128 v[136:139], v207
	ds_read_b128 v[184:187], v211
	ds_read_b128 v[200:203], v211 offset:4096
	ds_read_b128 v[140:143], v207 offset:4096
	s_waitcnt lgkmcnt(4)
	v_mfma_f32_32x32x16_bf16 v[34:49], v[128:131], v[120:123], v[34:49]
	v_mfma_f32_32x32x16_bf16 v[18:33], v[132:135], v[120:123], v[18:33]
	v_mfma_f32_32x32x16_bf16 v[50:65], v[132:135], v[124:127], v[50:65]
	v_mfma_f32_32x32x16_bf16 v[2:17], v[128:131], v[124:127], v[2:17]
	s_waitcnt lgkmcnt(0)
	v_mfma_f32_32x32x16_bf16 v[34:49], v[184:187], v[136:139], v[34:49]
	v_mfma_f32_32x32x16_bf16 v[18:33], v[200:203], v[136:139], v[18:33]
	v_mfma_f32_32x32x16_bf16 v[50:65], v[200:203], v[140:143], v[50:65]
	v_mfma_f32_32x32x16_bf16 v[2:17], v[184:187], v[140:143], v[2:17]
	s_setprio 0
	s_waitcnt vmcnt(0)
	s_barrier
	ds_read_b128 v[120:123], v204 offset:32768
	ds_read_b128 v[128:131], v208 offset:32768
	ds_read_b128 v[132:135], v208 offset:36864
	ds_read_b128 v[124:127], v204 offset:36864
	ds_read_b128 v[136:139], v205 offset:32768
	ds_read_b128 v[184:187], v209 offset:32768
	ds_read_b128 v[200:203], v209 offset:36864
	ds_read_b128 v[140:143], v205 offset:36864
	s_setprio 1
	s_waitcnt lgkmcnt(4)
	v_mfma_f32_32x32x16_bf16 v[34:49], v[128:131], v[120:123], v[34:49]
	v_mfma_f32_32x32x16_bf16 v[18:33], v[132:135], v[120:123], v[18:33]
	v_mfma_f32_32x32x16_bf16 v[50:65], v[132:135], v[124:127], v[50:65]
	v_mfma_f32_32x32x16_bf16 v[2:17], v[128:131], v[124:127], v[2:17]
	ds_read_b128 v[120:123], v206 offset:32768
	ds_read_b128 v[128:131], v210 offset:32768
	ds_read_b128 v[132:135], v210 offset:36864
	ds_read_b128 v[124:127], v206 offset:36864
	s_waitcnt lgkmcnt(4)
	v_mfma_f32_32x32x16_bf16 v[34:49], v[184:187], v[136:139], v[34:49]
	v_mfma_f32_32x32x16_bf16 v[18:33], v[200:203], v[136:139], v[18:33]
	v_mfma_f32_32x32x16_bf16 v[50:65], v[200:203], v[140:143], v[50:65]
	v_mfma_f32_32x32x16_bf16 v[2:17], v[184:187], v[140:143], v[2:17]
	ds_read_b128 v[136:139], v207 offset:32768
	ds_read_b128 v[184:187], v211 offset:32768
	ds_read_b128 v[200:203], v211 offset:36864
	ds_read_b128 v[140:143], v207 offset:36864
	s_waitcnt lgkmcnt(4)
	v_mfma_f32_32x32x16_bf16 v[34:49], v[128:131], v[120:123], v[34:49]
	v_mfma_f32_32x32x16_bf16 v[18:33], v[132:135], v[120:123], v[18:33]
	v_mfma_f32_32x32x16_bf16 v[50:65], v[132:135], v[124:127], v[50:65]
	v_mfma_f32_32x32x16_bf16 v[2:17], v[128:131], v[124:127], v[2:17]
	s_waitcnt lgkmcnt(0)
	v_mfma_f32_32x32x16_bf16 v[34:49], v[184:187], v[136:139], v[34:49]
	v_mfma_f32_32x32x16_bf16 v[18:33], v[200:203], v[136:139], v[18:33]
	v_mfma_f32_32x32x16_bf16 v[50:65], v[200:203], v[140:143], v[50:65]
	v_mfma_f32_32x32x16_bf16 v[2:17], v[184:187], v[140:143], v[2:17]
	s_setprio 0
	s_nop 7
	s_nop 7
	s_barrier
	s_mov_b64 s[22:23], 0
; template <bool SWAP>
; DI void gemm_block(const bf16_t* __restrict__ A, int lda, const bf16_t* __restrict__ Bt, int ldb, int K, f32x16 (&acc)[2][2], bf16_t* sA, bf16_t* sB) {
;   const int tid = get_tid(), lane = tid & 63, wave = tid >> 6, wr = wave >> 1, wc = wave & 1, l32 = lane & 31, h = lane >> 5;
; #pragma unroll
;   for (int i = 0; i < 2; ++i)
; #pragma unroll
;     for (int j = 0; j < 2; ++j)
; #pragma unroll
;       for (int e = 0; e < 16; ++e) acc[i][j][e] = 0.f;
;   const int lrow = tid >> 3, lch = (tid & 7) * 8;
;   const bf16_t* ga = A + (size_t)lrow * lda + lch;
;   const bf16_t* gb = Bt + (size_t)lrow * ldb + lch;
;   const int soff = lrow * LDT + lch;
;   u32x4 ra[4], rb[4];
; #pragma unroll
;   for (int i = 0; i < 4; ++i) { ra[i] = *(const u32x4*)(ga + (size_t)i * 32 * lda); rb[i] = *(const u32x4*)(gb + (size_t)i * 32 * ldb); }
; #pragma unroll
;   for (int i = 0; i < 4; ++i) { *(u32x4*)(sA + soff + i * 32 * LDT) = ra[i]; *(u32x4*)(sB + soff + i * 32 * LDT) = rb[i]; }
;   __syncthreads();
;   const int nk = K >> 6;
;   for (int kt = 0; kt < nk; ++kt) {
;     const int cur = kt & 1;
;     const bool more = kt + 1 < nk;
;     if (more) {
;       const int k0 = (kt + 1) * 64;
; #pragma unroll
;       for (int i = 0; i < 4; ++i) { ra[i] = *(const u32x4*)(ga + (size_t)i * 32 * lda + k0); rb[i] = *(const u32x4*)(gb + (size_t)i * 32 * ldb + k0); }
;     }
;     const bf16_t* ab = sA + cur * 128 * LDT + (64 * wr + l32) * LDT + h * 8;
;     const bf16_t* bb = sB + cur * 128 * LDT + (64 * wc + l32) * LDT + h * 8;
;     __builtin_amdgcn_s_setprio(1);
;     __builtin_amdgcn_iglp_opt(0);
; #pragma unroll
;     for (int ks = 0; ks < 4; ++ks) {
;       const bf16x8 a0 = *(const bf16x8*)(ab + ks * 16), a1 = *(const bf16x8*)(ab + 32 * LDT + ks * 16);
;       const bf16x8 b0 = *(const bf16x8*)(bb + ks * 16), b1 = *(const bf16x8*)(bb + 32 * LDT + ks * 16);
;       if (!SWAP) {
;         acc[0][0] = MFMA(a0, b0, acc[0][0]); acc[0][1] = MFMA(a0, b1, acc[0][1]);
;         acc[1][0] = MFMA(a1, b0, acc[1][0]); acc[1][1] = MFMA(a1, b1, acc[1][1]);
;       } else {
;         acc[0][0] = MFMA(b0, a0, acc[0][0]); acc[0][1] = MFMA(b1, a0, acc[0][1]);
;         acc[1][0] = MFMA(b0, a1, acc[1][0]); acc[1][1] = MFMA(b1, a1, acc[1][1]);
;       }
;     }
;     __builtin_amdgcn_s_setprio(0);
;     if (more) {
;       const int nb = (cur ^ 1) * 128 * LDT;
; #pragma unroll
.LBB0_234:
	s_andn2_b64 vcc, exec, s[22:23]
	s_cbranch_vccnz .LBB0_236
	s_nop 1
	v_mov_b32_e32 v34, v188
	s_waitcnt vmcnt(7)
	s_nop 1
	v_ashrrev_i32_e32 v2, 3, v34
	v_lshlrev_b32_e32 v0, 3, v34
	v_ashrrev_i32_e32 v3, 31, v2
	v_and_b32_e32 v35, 56, v0
	v_lshlrev_b64 v[4:5], 11, v[2:3]
	s_waitcnt vmcnt(6)
	v_lshl_add_u64 v[6:7], s[20:21], 0, v[4:5]
	v_lshrrev_b32_e32 v20, 4, v34
	v_and_b32_e32 v21, 7, v34
	v_and_b32_e32 v20, 7, v20
	v_xor_b32_e32 v20, v20, v21
	v_lshlrev_b32_e32 v0, 4, v20
	v_lshl_add_u64 v[68:69], v[6:7], 0, v[0:1]
	v_lshl_add_u64 v[4:5], s[42:43], 0, v[4:5]
	v_add_co_u32_e32 v72, vcc, s50, v68
	v_lshl_add_u64 v[70:71], v[4:5], 0, v[0:1]
	s_nop 0
	v_addc_co_u32_e32 v73, vcc, 0, v69, vcc
	v_add_co_u32_e32 v74, vcc, s50, v70
	v_mul_lo_u32 v0, v2, s33
	s_nop 0
	v_addc_co_u32_e32 v75, vcc, 0, v71, vcc
	v_add_co_u32_e32 v76, vcc, s51, v68
	s_nop 0
	s_nop 0
	v_addc_co_u32_e32 v77, vcc, 0, v69, vcc
	v_add_co_u32_e32 v78, vcc, s51, v70
	s_nop 0
	s_nop 0
	v_addc_co_u32_e32 v79, vcc, 0, v71, vcc
	v_add_co_u32_e32 v80, vcc, s52, v68
	s_nop 0
	s_nop 0
	v_addc_co_u32_e32 v81, vcc, 0, v69, vcc
	v_add_co_u32_e32 v82, vcc, s52, v70
	s_nop 0
	s_nop 0
	v_addc_co_u32_e32 v83, vcc, 0, v71, vcc
	s_nop 0
	s_nop 0
	s_nop 0
	s_nop 0
	v_add_lshl_u32 v85, v0, v35, 1
	v_and_b32_e32 v0, 31, v34
	v_add_u32_e32 v86, 0x9000, v85
	v_lshrrev_b32_e32 v2, 1, v34
	v_and_or_b32 v3, v2, s53, v0
	v_and_b32_e32 v0, 16, v2
	v_and_b32_e32 v2, 0x5f, v34
	v_mad_u64_u32 v[66:67], s[0:1], v3, s54, v[0:1]
	v_mad_u32_u24 v0, v2, s54, v0
	v_lshrrev_b32_e32 v20, 6, v34
	v_and_b32_e32 v21, 31, v34
	v_readfirstlane_b32 s100, v20
	v_lshrrev_b32_e32 v22, 7, v34
	v_bfe_u32 v23, v34, 6, 1
	s_lshl_b32 s100, s100, 10
	v_lshl_or_b32 v22, v22, 6, v21
	v_lshl_or_b32 v23, v23, 6, v21
	s_add_u32 m0, s100, 2048
	s_nop 0
	global_load_lds_dwordx4 v[68:69], off
	s_add_u32 m0, s100, 18432
	s_nop 0
	global_load_lds_dwordx4 v[70:71], off
	s_add_u32 m0, s100, 6144
	s_nop 0
	global_load_lds_dwordx4 v[72:73], off
	s_add_u32 m0, s100, 22528
	s_nop 0
	global_load_lds_dwordx4 v[74:75], off
	s_add_u32 m0, s100, 10240
	s_nop 0
	global_load_lds_dwordx4 v[76:77], off
	s_add_u32 m0, s100, 26624
	s_nop 0
	global_load_lds_dwordx4 v[78:79], off
	s_add_u32 m0, s100, 14336
	s_nop 0
	global_load_lds_dwordx4 v[80:81], off
	s_add_u32 m0, s100, 30720
	s_nop 0
	global_load_lds_dwordx4 v[82:83], off
	v_lshrrev_b32_e32 v24, 5, v34
	v_lshrrev_b32_e32 v25, 1, v34
	v_xor_b32_e32 v24, v24, v25
	v_and_b32_e32 v24, 1, v24
	v_bfe_u32 v25, v34, 2, 2
	v_lshlrev_b32_e32 v22, 7, v22
	v_lshlrev_b32_e32 v23, 7, v23
	v_lshl_add_u32 v22, v24, 4, v22
	v_lshl_add_u32 v23, v24, 4, v23
	v_add_u32_e32 v22, 2048, v22
	v_add_u32_e32 v23, 18432, v23
	v_lshl_add_u32 v204, v25, 5, v22
	v_lshl_add_u32 v208, v25, 5, v23
	v_xor_b32_e32 v26, 1, v25
	v_lshl_add_u32 v205, v26, 5, v22
	v_lshl_add_u32 v209, v26, 5, v23
	v_xor_b32_e32 v26, 2, v25
	v_lshl_add_u32 v206, v26, 5, v22
	v_lshl_add_u32 v210, v26, 5, v23
	v_xor_b32_e32 v26, 3, v25
	v_lshl_add_u32 v207, v26, 5, v22
	v_lshl_add_u32 v211, v26, 5, v23
	s_waitcnt vmcnt(0)
	s_waitcnt lgkmcnt(0)
	s_barrier
	ds_read_b128 v[120:123], v204
	ds_read_b128 v[128:131], v208
	ds_read_b128 v[132:135], v208 offset:4096
	ds_read_b128 v[124:127], v204 offset:4096
	ds_read_b128 v[136:139], v205
	ds_read_b128 v[184:187], v209
	ds_read_b128 v[200:203], v209 offset:4096
	ds_read_b128 v[140:143], v205 offset:4096
	s_setprio 1
	s_waitcnt lgkmcnt(4)
	s_add_u32 m0, s100, 34688
	v_mfma_f32_32x32x16_bf16 v[34:49], v[120:123], v[128:131], 0
	global_load_lds_dwordx4 v[68:69], off offset:128
	s_add_u32 m0, s100, 51072
	v_mfma_f32_32x32x16_bf16 v[18:33], v[120:123], v[132:135], 0
	global_load_lds_dwordx4 v[70:71], off offset:128
	s_add_u32 m0, s100, 38784
	v_mfma_f32_32x32x16_bf16 v[50:65], v[124:127], v[132:135], 0
	global_load_lds_dwordx4 v[72:73], off offset:128
	s_add_u32 m0, s100, 55168
	v_mfma_f32_32x32x16_bf16 v[2:17], v[124:127], v[128:131], 0
	global_load_lds_dwordx4 v[74:75], off offset:128
	ds_read_b128 v[120:123], v206
	ds_read_b128 v[128:131], v210
	ds_read_b128 v[132:135], v210 offset:4096
	ds_read_b128 v[124:127], v206 offset:4096
	s_waitcnt lgkmcnt(4)
	s_add_u32 m0, s100, 42880
	v_mfma_f32_32x32x16_bf16 v[34:49], v[136:139], v[184:187], v[34:49]
	global_load_lds_dwordx4 v[76:77], off offset:128
	s_add_u32 m0, s100, 59264
	v_mfma_f32_32x32x16_bf16 v[18:33], v[136:139], v[200:203], v[18:33]
	global_load_lds_dwordx4 v[78:79], off offset:128
	s_add_u32 m0, s100, 46976
	v_mfma_f32_32x32x16_bf16 v[50:65], v[140:143], v[200:203], v[50:65]
	global_load_lds_dwordx4 v[80:81], off offset:128
	s_add_u32 m0, s100, 63360
	v_mfma_f32_32x32x16_bf16 v[2:17], v[140:143], v[184:187], v[2:17]
	global_load_lds_dwordx4 v[82:83], off offset:128
	ds_read_b128 v[136:139], v207
	ds_read_b128 v[184:187], v211
	ds_read_b128 v[200:203], v211 offset:4096
	ds_read_b128 v[140:143], v207 offset:4096
	s_waitcnt lgkmcnt(4)
	v_mfma_f32_32x32x16_bf16 v[34:49], v[120:123], v[128:131], v[34:49]
	v_mfma_f32_32x32x16_bf16 v[18:33], v[120:123], v[132:135], v[18:33]
	v_mfma_f32_32x32x16_bf16 v[50:65], v[124:127], v[132:135], v[50:65]
	v_mfma_f32_32x32x16_bf16 v[2:17], v[124:127], v[128:131], v[2:17]
	s_waitcnt lgkmcnt(0)
	v_mfma_f32_32x32x16_bf16 v[34:49], v[136:139], v[184:187], v[34:49]
	v_mfma_f32_32x32x16_bf16 v[18:33], v[136:139], v[200:203], v[18:33]
	v_mfma_f32_32x32x16_bf16 v[50:65], v[140:143], v[200:203], v[50:65]
	v_mfma_f32_32x32x16_bf16 v[2:17], v[140:143], v[184:187], v[2:17]
	s_setprio 0
	s_waitcnt vmcnt(0)
	s_barrier
; #define MFMA(a, b, c) __builtin_amdgcn_mfma_f32_32x32x16_bf16((a), (b), (c), 0, 0, 0)
; template <bool SWAP>
; DI void gemm_block(const bf16_t* __restrict__ A, int lda, const bf16_t* __restrict__ Bt, int ldb, int K, f32x16 (&acc)[2][2], bf16_t* sA, bf16_t* sB) {
;     ...
;   for (int kt = 0; kt < nk; ++kt) {
;     const int cur = kt & 1;
;     const bool more = kt + 1 < nk;
;     if (more) {
;       const int k0 = (kt + 1) * 64;
; #pragma unroll
;       for (int i = 0; i < 4; ++i) { ra[i] = *(const u32x4*)(ga + (size_t)i * 32 * lda + k0); rb[i] = *(const u32x4*)(gb + (size_t)i * 32 * ldb + k0); }
;     }
;     const bf16_t* ab = sA + cur * 128 * LDT + (64 * wr + l32) * LDT + h * 8;
;     const bf16_t* bb = sB + cur * 128 * LDT + (64 * wc + l32) * LDT + h * 8;
;     __builtin_amdgcn_s_setprio(1);
;     __builtin_amdgcn_iglp_opt(0);
; #pragma unroll
;     for (int ks = 0; ks < 4; ++ks) {
;       const bf16x8 a0 = *(const bf16x8*)(ab + ks * 16), a1 = *(const bf16x8*)(ab + 32 * LDT + ks * 16);
;       const bf16x8 b0 = *(const bf16x8*)(bb + ks * 16), b1 = *(const bf16x8*)(bb + 32 * LDT + ks * 16);
;       if (!SWAP) {
;         acc[0][0] = MFMA(a0, b0, acc[0][0]); acc[0][1] = MFMA(a0, b1, acc[0][1]);
;         acc[1][0] = MFMA(a1, b0, acc[1][0]); acc[1][1] = MFMA(a1, b1, acc[1][1]);
;       } else {
;         acc[0][0] = MFMA(b0, a0, acc[0][0]); acc[0][1] = MFMA(b1, a0, acc[0][1]);
;         acc[1][0] = MFMA(b0, a1, acc[1][0]); acc[1][1] = MFMA(b1, a1, acc[1][1]);
;       }
;     }
;     __builtin_amdgcn_s_setprio(0);
;     if (more) {
;       const int nb = (cur ^ 1) * 128 * LDT;
; #pragma unroll
;       for (int i = 0; i < 4; ++i) { *(u32x4*)(sA + nb + soff + i * 32 * LDT) = ra[i]; *(u32x4*)(sB + nb + soff + i * 32 * LDT) = rb[i]; }
;     }
;     __syncthreads();
;   }
	ds_read_b128 v[120:123], v204 offset:32768
	ds_read_b128 v[128:131], v208 offset:32768
	ds_read_b128 v[132:135], v208 offset:36864
	ds_read_b128 v[124:127], v204 offset:36864
	ds_read_b128 v[136:139], v205 offset:32768
	ds_read_b128 v[184:187], v209 offset:32768
	ds_read_b128 v[200:203], v209 offset:36864
	ds_read_b128 v[140:143], v205 offset:36864
	s_setprio 1
	s_waitcnt lgkmcnt(4)
	s_add_u32 m0, s100, 1792
	v_mfma_f32_32x32x16_bf16 v[34:49], v[120:123], v[128:131], v[34:49]
	global_load_lds_dwordx4 v[68:69], off offset:256
	s_add_u32 m0, s100, 18176
	v_mfma_f32_32x32x16_bf16 v[18:33], v[120:123], v[132:135], v[18:33]
	global_load_lds_dwordx4 v[70:71], off offset:256
	s_add_u32 m0, s100, 5888
	v_mfma_f32_32x32x16_bf16 v[50:65], v[124:127], v[132:135], v[50:65]
	global_load_lds_dwordx4 v[72:73], off offset:256
	s_add_u32 m0, s100, 22272
	v_mfma_f32_32x32x16_bf16 v[2:17], v[124:127], v[128:131], v[2:17]
	global_load_lds_dwordx4 v[74:75], off offset:256
	ds_read_b128 v[120:123], v206 offset:32768
	ds_read_b128 v[128:131], v210 offset:32768
	ds_read_b128 v[132:135], v210 offset:36864
	ds_read_b128 v[124:127], v206 offset:36864
	s_waitcnt lgkmcnt(4)
	s_add_u32 m0, s100, 9984
	v_mfma_f32_32x32x16_bf16 v[34:49], v[136:139], v[184:187], v[34:49]
	global_load_lds_dwordx4 v[76:77], off offset:256
	s_add_u32 m0, s100, 26368
	v_mfma_f32_32x32x16_bf16 v[18:33], v[136:139], v[200:203], v[18:33]
	global_load_lds_dwordx4 v[78:79], off offset:256
	s_add_u32 m0, s100, 14080
	v_mfma_f32_32x32x16_bf16 v[50:65], v[140:143], v[200:203], v[50:65]
	global_load_lds_dwordx4 v[80:81], off offset:256
	s_add_u32 m0, s100, 30464
	v_mfma_f32_32x32x16_bf16 v[2:17], v[140:143], v[184:187], v[2:17]
	global_load_lds_dwordx4 v[82:83], off offset:256
	ds_read_b128 v[136:139], v207 offset:32768
	ds_read_b128 v[184:187], v211 offset:32768
	ds_read_b128 v[200:203], v211 offset:36864
	ds_read_b128 v[140:143], v207 offset:36864
	s_waitcnt lgkmcnt(4)
	v_mfma_f32_32x32x16_bf16 v[34:49], v[120:123], v[128:131], v[34:49]
	v_mfma_f32_32x32x16_bf16 v[18:33], v[120:123], v[132:135], v[18:33]
	v_mfma_f32_32x32x16_bf16 v[50:65], v[124:127], v[132:135], v[50:65]
	v_mfma_f32_32x32x16_bf16 v[2:17], v[124:127], v[128:131], v[2:17]
	s_waitcnt lgkmcnt(0)
	v_mfma_f32_32x32x16_bf16 v[34:49], v[136:139], v[184:187], v[34:49]
	v_mfma_f32_32x32x16_bf16 v[18:33], v[136:139], v[200:203], v[18:33]
	v_mfma_f32_32x32x16_bf16 v[50:65], v[140:143], v[200:203], v[50:65]
	v_mfma_f32_32x32x16_bf16 v[2:17], v[140:143], v[184:187], v[2:17]
	s_setprio 0
	s_waitcnt vmcnt(0)
	s_barrier
	ds_read_b128 v[120:123], v204
	ds_read_b128 v[128:131], v208
	ds_read_b128 v[132:135], v208 offset:4096
	ds_read_b128 v[124:127], v204 offset:4096
	ds_read_b128 v[136:139], v205
	ds_read_b128 v[184:187], v209
	ds_read_b128 v[200:203], v209 offset:4096
	ds_read_b128 v[140:143], v205 offset:4096
	s_setprio 1
	s_waitcnt lgkmcnt(4)
	s_add_u32 m0, s100, 34432
	v_mfma_f32_32x32x16_bf16 v[34:49], v[120:123], v[128:131], v[34:49]
	global_load_lds_dwordx4 v[68:69], off offset:384
	s_add_u32 m0, s100, 50816
	v_mfma_f32_32x32x16_bf16 v[18:33], v[120:123], v[132:135], v[18:33]
	global_load_lds_dwordx4 v[70:71], off offset:384
	s_add_u32 m0, s100, 38528
	v_mfma_f32_32x32x16_bf16 v[50:65], v[124:127], v[132:135], v[50:65]
	global_load_lds_dwordx4 v[72:73], off offset:384
	s_add_u32 m0, s100, 54912
	v_mfma_f32_32x32x16_bf16 v[2:17], v[124:127], v[128:131], v[2:17]
	global_load_lds_dwordx4 v[74:75], off offset:384
	ds_read_b128 v[120:123], v206
	ds_read_b128 v[128:131], v210
	ds_read_b128 v[132:135], v210 offset:4096
	ds_read_b128 v[124:127], v206 offset:4096
	s_waitcnt lgkmcnt(4)
	s_add_u32 m0, s100, 42624
	v_mfma_f32_32x32x16_bf16 v[34:49], v[136:139], v[184:187], v[34:49]
	global_load_lds_dwordx4 v[76:77], off offset:384
	s_add_u32 m0, s100, 59008
	v_mfma_f32_32x32x16_bf16 v[18:33], v[136:139], v[200:203], v[18:33]
	global_load_lds_dwordx4 v[78:79], off offset:384
	s_add_u32 m0, s100, 46720
	v_mfma_f32_32x32x16_bf16 v[50:65], v[140:143], v[200:203], v[50:65]
	global_load_lds_dwordx4 v[80:81], off offset:384
	s_add_u32 m0, s100, 63104
	v_mfma_f32_32x32x16_bf16 v[2:17], v[140:143], v[184:187], v[2:17]
	global_load_lds_dwordx4 v[82:83], off offset:384
	ds_read_b128 v[136:139], v207
	ds_read_b128 v[184:187], v211
	ds_read_b128 v[200:203], v211 offset:4096
	ds_read_b128 v[140:143], v207 offset:4096
	s_waitcnt lgkmcnt(4)
	v_mfma_f32_32x32x16_bf16 v[34:49], v[120:123], v[128:131], v[34:49]
	v_mfma_f32_32x32x16_bf16 v[18:33], v[120:123], v[132:135], v[18:33]
	v_mfma_f32_32x32x16_bf16 v[50:65], v[124:127], v[132:135], v[50:65]
	v_mfma_f32_32x32x16_bf16 v[2:17], v[124:127], v[128:131], v[2:17]
	s_waitcnt lgkmcnt(0)
	v_mfma_f32_32x32x16_bf16 v[34:49], v[136:139], v[184:187], v[34:49]
	v_mfma_f32_32x32x16_bf16 v[18:33], v[136:139], v[200:203], v[18:33]
	v_mfma_f32_32x32x16_bf16 v[50:65], v[140:143], v[200:203], v[50:65]
	v_mfma_f32_32x32x16_bf16 v[2:17], v[140:143], v[184:187], v[2:17]
	s_setprio 0
	s_waitcnt vmcnt(0)
	s_barrier
; #define MFMA(a, b, c) __builtin_amdgcn_mfma_f32_32x32x16_bf16((a), (b), (c), 0, 0, 0)
; template <bool SWAP>
; DI void gemm_block(const bf16_t* __restrict__ A, int lda, const bf16_t* __restrict__ Bt, int ldb, int K, f32x16 (&acc)[2][2], bf16_t* sA, bf16_t* sB) {
;     ...
;   for (int kt = 0; kt < nk; ++kt) {
;     const int cur = kt & 1;
;     const bool more = kt + 1 < nk;
;     if (more) {
;       const int k0 = (kt + 1) * 64;
; #pragma unroll
;       for (int i = 0; i < 4; ++i) { ra[i] = *(const u32x4*)(ga + (size_t)i * 32 * lda + k0); rb[i] = *(const u32x4*)(gb + (size_t)i * 32 * ldb + k0); }
;     }
;     const bf16_t* ab = sA + cur * 128 * LDT + (64 * wr + l32) * LDT + h * 8;
;     const bf16_t* bb = sB + cur * 128 * LDT + (64 * wc + l32) * LDT + h * 8;
;     __builtin_amdgcn_s_setprio(1);
;     __builtin_amdgcn_iglp_opt(0);
; #pragma unroll
;     for (int ks = 0; ks < 4; ++ks) {
;       const bf16x8 a0 = *(const bf16x8*)(ab + ks * 16), a1 = *(const bf16x8*)(ab + 32 * LDT + ks * 16);
;       const bf16x8 b0 = *(const bf16x8*)(bb + ks * 16), b1 = *(const bf16x8*)(bb + 32 * LDT + ks * 16);
;       if (!SWAP) {
;         acc[0][0] = MFMA(a0, b0, acc[0][0]); acc[0][1] = MFMA(a0, b1, acc[0][1]);
;         acc[1][0] = MFMA(a1, b0, acc[1][0]); acc[1][1] = MFMA(a1, b1, acc[1][1]);
;       } else {
;         acc[0][0] = MFMA(b0, a0, acc[0][0]); acc[0][1] = MFMA(b1, a0, acc[0][1]);
;         acc[1][0] = MFMA(b0, a1, acc[1][0]); acc[1][1] = MFMA(b1, a1, acc[1][1]);
;       }
;     }
;     __builtin_amdgcn_s_setprio(0);
;     if (more) {
;       const int nb = (cur ^ 1) * 128 * LDT;
; #pragma unroll
;       for (int i = 0; i < 4; ++i) { *(u32x4*)(sA + nb + soff + i * 32 * LDT) = ra[i]; *(u32x4*)(sB + nb + soff + i * 32 * LDT) = rb[i]; }
;     }
;     __syncthreads();
;   }
	ds_read_b128 v[120:123], v204 offset:32768
	ds_read_b128 v[128:131], v208 offset:32768
	ds_read_b128 v[132:135], v208 offset:36864
	ds_read_b128 v[124:127], v204 offset:36864
	ds_read_b128 v[136:139], v205 offset:32768
	ds_read_b128 v[184:187], v209 offset:32768
	ds_read_b128 v[200:203], v209 offset:36864
	ds_read_b128 v[140:143], v205 offset:36864
	s_setprio 1
	s_waitcnt lgkmcnt(4)
	s_add_u32 m0, s100, 1536
	v_mfma_f32_32x32x16_bf16 v[34:49], v[120:123], v[128:131], v[34:49]
	global_load_lds_dwordx4 v[68:69], off offset:512
	s_add_u32 m0, s100, 17920
	v_mfma_f32_32x32x16_bf16 v[18:33], v[120:123], v[132:135], v[18:33]
	global_load_lds_dwordx4 v[70:71], off offset:512
	s_add_u32 m0, s100, 5632
	v_mfma_f32_32x32x16_bf16 v[50:65], v[124:127], v[132:135], v[50:65]
	global_load_lds_dwordx4 v[72:73], off offset:512
	s_add_u32 m0, s100, 22016
	v_mfma_f32_32x32x16_bf16 v[2:17], v[124:127], v[128:131], v[2:17]
	global_load_lds_dwordx4 v[74:75], off offset:512
	ds_read_b128 v[120:123], v206 offset:32768
	ds_read_b128 v[128:131], v210 offset:32768
	ds_read_b128 v[132:135], v210 offset:36864
	ds_read_b128 v[124:127], v206 offset:36864
	s_waitcnt lgkmcnt(4)
	s_add_u32 m0, s100, 9728
	v_mfma_f32_32x32x16_bf16 v[34:49], v[136:139], v[184:187], v[34:49]
	global_load_lds_dwordx4 v[76:77], off offset:512
	s_add_u32 m0, s100, 26112
	v_mfma_f32_32x32x16_bf16 v[18:33], v[136:139], v[200:203], v[18:33]
	global_load_lds_dwordx4 v[78:79], off offset:512
	s_add_u32 m0, s100, 13824
	v_mfma_f32_32x32x16_bf16 v[50:65], v[140:143], v[200:203], v[50:65]
	global_load_lds_dwordx4 v[80:81], off offset:512
	s_add_u32 m0, s100, 30208
	v_mfma_f32_32x32x16_bf16 v[2:17], v[140:143], v[184:187], v[2:17]
	global_load_lds_dwordx4 v[82:83], off offset:512
	ds_read_b128 v[136:139], v207 offset:32768
	ds_read_b128 v[184:187], v211 offset:32768
	ds_read_b128 v[200:203], v211 offset:36864
	ds_read_b128 v[140:143], v207 offset:36864
	s_waitcnt lgkmcnt(4)
	v_mfma_f32_32x32x16_bf16 v[34:49], v[120:123], v[128:131], v[34:49]
	v_mfma_f32_32x32x16_bf16 v[18:33], v[120:123], v[132:135], v[18:33]
	v_mfma_f32_32x32x16_bf16 v[50:65], v[124:127], v[132:135], v[50:65]
	v_mfma_f32_32x32x16_bf16 v[2:17], v[124:127], v[128:131], v[2:17]
	s_waitcnt lgkmcnt(0)
	v_mfma_f32_32x32x16_bf16 v[34:49], v[136:139], v[184:187], v[34:49]
	v_mfma_f32_32x32x16_bf16 v[18:33], v[136:139], v[200:203], v[18:33]
	v_mfma_f32_32x32x16_bf16 v[50:65], v[140:143], v[200:203], v[50:65]
	v_mfma_f32_32x32x16_bf16 v[2:17], v[140:143], v[184:187], v[2:17]
	s_setprio 0
	s_waitcnt vmcnt(0)
	s_barrier
	ds_read_b128 v[120:123], v204
	ds_read_b128 v[128:131], v208
	ds_read_b128 v[132:135], v208 offset:4096
	ds_read_b128 v[124:127], v204 offset:4096
	ds_read_b128 v[136:139], v205
	ds_read_b128 v[184:187], v209
	ds_read_b128 v[200:203], v209 offset:4096
	ds_read_b128 v[140:143], v205 offset:4096
	s_setprio 1
	s_waitcnt lgkmcnt(4)
	s_add_u32 m0, s100, 34176
	v_mfma_f32_32x32x16_bf16 v[34:49], v[120:123], v[128:131], v[34:49]
	global_load_lds_dwordx4 v[68:69], off offset:640
	s_add_u32 m0, s100, 50560
	v_mfma_f32_32x32x16_bf16 v[18:33], v[120:123], v[132:135], v[18:33]
	global_load_lds_dwordx4 v[70:71], off offset:640
	s_add_u32 m0, s100, 38272
	v_mfma_f32_32x32x16_bf16 v[50:65], v[124:127], v[132:135], v[50:65]
	global_load_lds_dwordx4 v[72:73], off offset:640
	s_add_u32 m0, s100, 54656
	v_mfma_f32_32x32x16_bf16 v[2:17], v[124:127], v[128:131], v[2:17]
	global_load_lds_dwordx4 v[74:75], off offset:640
	ds_read_b128 v[120:123], v206
	ds_read_b128 v[128:131], v210
	ds_read_b128 v[132:135], v210 offset:4096
	ds_read_b128 v[124:127], v206 offset:4096
	s_waitcnt lgkmcnt(4)
	s_add_u32 m0, s100, 42368
	v_mfma_f32_32x32x16_bf16 v[34:49], v[136:139], v[184:187], v[34:49]
	global_load_lds_dwordx4 v[76:77], off offset:640
	s_add_u32 m0, s100, 58752
	v_mfma_f32_32x32x16_bf16 v[18:33], v[136:139], v[200:203], v[18:33]
	global_load_lds_dwordx4 v[78:79], off offset:640
	s_add_u32 m0, s100, 46464
	v_mfma_f32_32x32x16_bf16 v[50:65], v[140:143], v[200:203], v[50:65]
	global_load_lds_dwordx4 v[80:81], off offset:640
	s_add_u32 m0, s100, 62848
	v_mfma_f32_32x32x16_bf16 v[2:17], v[140:143], v[184:187], v[2:17]
	global_load_lds_dwordx4 v[82:83], off offset:640
	ds_read_b128 v[136:139], v207
	ds_read_b128 v[184:187], v211
	ds_read_b128 v[200:203], v211 offset:4096
	ds_read_b128 v[140:143], v207 offset:4096
	s_waitcnt lgkmcnt(4)
	v_mfma_f32_32x32x16_bf16 v[34:49], v[120:123], v[128:131], v[34:49]
	v_mfma_f32_32x32x16_bf16 v[18:33], v[120:123], v[132:135], v[18:33]
	v_mfma_f32_32x32x16_bf16 v[50:65], v[124:127], v[132:135], v[50:65]
	v_mfma_f32_32x32x16_bf16 v[2:17], v[124:127], v[128:131], v[2:17]
	s_waitcnt lgkmcnt(0)
	v_mfma_f32_32x32x16_bf16 v[34:49], v[136:139], v[184:187], v[34:49]
	v_mfma_f32_32x32x16_bf16 v[18:33], v[136:139], v[200:203], v[18:33]
	v_mfma_f32_32x32x16_bf16 v[50:65], v[140:143], v[200:203], v[50:65]
	v_mfma_f32_32x32x16_bf16 v[2:17], v[140:143], v[184:187], v[2:17]
	s_setprio 0
	s_waitcnt vmcnt(0)
	s_barrier
; #define MFMA(a, b, c) __builtin_amdgcn_mfma_f32_32x32x16_bf16((a), (b), (c), 0, 0, 0)
; template <bool SWAP>
; DI void gemm_block(const bf16_t* __restrict__ A, int lda, const bf16_t* __restrict__ Bt, int ldb, int K, f32x16 (&acc)[2][2], bf16_t* sA, bf16_t* sB) {
;     ...
;   for (int kt = 0; kt < nk; ++kt) {
;     const int cur = kt & 1;
;     const bool more = kt + 1 < nk;
;     if (more) {
;       const int k0 = (kt + 1) * 64;
; #pragma unroll
;       for (int i = 0; i < 4; ++i) { ra[i] = *(const u32x4*)(ga + (size_t)i * 32 * lda + k0); rb[i] = *(const u32x4*)(gb + (size_t)i * 32 * ldb + k0); }
;     }
;     const bf16_t* ab = sA + cur * 128 * LDT + (64 * wr + l32) * LDT + h * 8;
;     const bf16_t* bb = sB + cur * 128 * LDT + (64 * wc + l32) * LDT + h * 8;
;     __builtin_amdgcn_s_setprio(1);
;     __builtin_amdgcn_iglp_opt(0);
; #pragma unroll
;     for (int ks = 0; ks < 4; ++ks) {
;       const bf16x8 a0 = *(const bf16x8*)(ab + ks * 16), a1 = *(const bf16x8*)(ab + 32 * LDT + ks * 16);
;       const bf16x8 b0 = *(const bf16x8*)(bb + ks * 16), b1 = *(const bf16x8*)(bb + 32 * LDT + ks * 16);
;       if (!SWAP) {
;         acc[0][0] = MFMA(a0, b0, acc[0][0]); acc[0][1] = MFMA(a0, b1, acc[0][1]);
;         acc[1][0] = MFMA(a1, b0, acc[1][0]); acc[1][1] = MFMA(a1, b1, acc[1][1]);
;       } else {
;         acc[0][0] = MFMA(b0, a0, acc[0][0]); acc[0][1] = MFMA(b1, a0, acc[0][1]);
;         acc[1][0] = MFMA(b0, a1, acc[1][0]); acc[1][1] = MFMA(b1, a1, acc[1][1]);
;       }
;     }
;     __builtin_amdgcn_s_setprio(0);
;     if (more) {
;       const int nb = (cur ^ 1) * 128 * LDT;
; #pragma unroll
;       for (int i = 0; i < 4; ++i) { *(u32x4*)(sA + nb + soff + i * 32 * LDT) = ra[i]; *(u32x4*)(sB + nb + soff + i * 32 * LDT) = rb[i]; }
;     }
;     __syncthreads();
;   }
	ds_read_b128 v[120:123], v204 offset:32768
	ds_read_b128 v[128:131], v208 offset:32768
	ds_read_b128 v[132:135], v208 offset:36864
	ds_read_b128 v[124:127], v204 offset:36864
	ds_read_b128 v[136:139], v205 offset:32768
	ds_read_b128 v[184:187], v209 offset:32768
	ds_read_b128 v[200:203], v209 offset:36864
	ds_read_b128 v[140:143], v205 offset:36864
	s_setprio 1
	s_waitcnt lgkmcnt(4)
	s_add_u32 m0, s100, 1280
	v_mfma_f32_32x32x16_bf16 v[34:49], v[120:123], v[128:131], v[34:49]
	global_load_lds_dwordx4 v[68:69], off offset:768
	s_add_u32 m0, s100, 17664
	v_mfma_f32_32x32x16_bf16 v[18:33], v[120:123], v[132:135], v[18:33]
	global_load_lds_dwordx4 v[70:71], off offset:768
	s_add_u32 m0, s100, 5376
	v_mfma_f32_32x32x16_bf16 v[50:65], v[124:127], v[132:135], v[50:65]
	global_load_lds_dwordx4 v[72:73], off offset:768
	s_add_u32 m0, s100, 21760
	v_mfma_f32_32x32x16_bf16 v[2:17], v[124:127], v[128:131], v[2:17]
	global_load_lds_dwordx4 v[74:75], off offset:768
	ds_read_b128 v[120:123], v206 offset:32768
	ds_read_b128 v[128:131], v210 offset:32768
	ds_read_b128 v[132:135], v210 offset:36864
	ds_read_b128 v[124:127], v206 offset:36864
	s_waitcnt lgkmcnt(4)
	s_add_u32 m0, s100, 9472
	v_mfma_f32_32x32x16_bf16 v[34:49], v[136:139], v[184:187], v[34:49]
	global_load_lds_dwordx4 v[76:77], off offset:768
	s_add_u32 m0, s100, 25856
	v_mfma_f32_32x32x16_bf16 v[18:33], v[136:139], v[200:203], v[18:33]
	global_load_lds_dwordx4 v[78:79], off offset:768
	s_add_u32 m0, s100, 13568
	v_mfma_f32_32x32x16_bf16 v[50:65], v[140:143], v[200:203], v[50:65]
	global_load_lds_dwordx4 v[80:81], off offset:768
	s_add_u32 m0, s100, 29952
	v_mfma_f32_32x32x16_bf16 v[2:17], v[140:143], v[184:187], v[2:17]
	global_load_lds_dwordx4 v[82:83], off offset:768
	ds_read_b128 v[136:139], v207 offset:32768
	ds_read_b128 v[184:187], v211 offset:32768
	ds_read_b128 v[200:203], v211 offset:36864
	ds_read_b128 v[140:143], v207 offset:36864
	s_waitcnt lgkmcnt(4)
	v_mfma_f32_32x32x16_bf16 v[34:49], v[120:123], v[128:131], v[34:49]
	v_mfma_f32_32x32x16_bf16 v[18:33], v[120:123], v[132:135], v[18:33]
	v_mfma_f32_32x32x16_bf16 v[50:65], v[124:127], v[132:135], v[50:65]
	v_mfma_f32_32x32x16_bf16 v[2:17], v[124:127], v[128:131], v[2:17]
	s_waitcnt lgkmcnt(0)
	v_mfma_f32_32x32x16_bf16 v[34:49], v[136:139], v[184:187], v[34:49]
	v_mfma_f32_32x32x16_bf16 v[18:33], v[136:139], v[200:203], v[18:33]
	v_mfma_f32_32x32x16_bf16 v[50:65], v[140:143], v[200:203], v[50:65]
	v_mfma_f32_32x32x16_bf16 v[2:17], v[140:143], v[184:187], v[2:17]
	s_setprio 0
	s_waitcnt vmcnt(0)
	s_barrier
	ds_read_b128 v[120:123], v204
	ds_read_b128 v[128:131], v208
	ds_read_b128 v[132:135], v208 offset:4096
	ds_read_b128 v[124:127], v204 offset:4096
	ds_read_b128 v[136:139], v205
	ds_read_b128 v[184:187], v209
	ds_read_b128 v[200:203], v209 offset:4096
	ds_read_b128 v[140:143], v205 offset:4096
	s_setprio 1
	s_waitcnt lgkmcnt(4)
	s_add_u32 m0, s100, 33920
	v_mfma_f32_32x32x16_bf16 v[34:49], v[120:123], v[128:131], v[34:49]
	global_load_lds_dwordx4 v[68:69], off offset:896
	s_add_u32 m0, s100, 50304
	v_mfma_f32_32x32x16_bf16 v[18:33], v[120:123], v[132:135], v[18:33]
	global_load_lds_dwordx4 v[70:71], off offset:896
	s_add_u32 m0, s100, 38016
	v_mfma_f32_32x32x16_bf16 v[50:65], v[124:127], v[132:135], v[50:65]
	global_load_lds_dwordx4 v[72:73], off offset:896
	s_add_u32 m0, s100, 54400
	v_mfma_f32_32x32x16_bf16 v[2:17], v[124:127], v[128:131], v[2:17]
	global_load_lds_dwordx4 v[74:75], off offset:896
	ds_read_b128 v[120:123], v206
	ds_read_b128 v[128:131], v210
	ds_read_b128 v[132:135], v210 offset:4096
	ds_read_b128 v[124:127], v206 offset:4096
	s_waitcnt lgkmcnt(4)
	s_add_u32 m0, s100, 42112
	v_mfma_f32_32x32x16_bf16 v[34:49], v[136:139], v[184:187], v[34:49]
	global_load_lds_dwordx4 v[76:77], off offset:896
	s_add_u32 m0, s100, 58496
	v_mfma_f32_32x32x16_bf16 v[18:33], v[136:139], v[200:203], v[18:33]
	global_load_lds_dwordx4 v[78:79], off offset:896
	s_add_u32 m0, s100, 46208
	v_mfma_f32_32x32x16_bf16 v[50:65], v[140:143], v[200:203], v[50:65]
	global_load_lds_dwordx4 v[80:81], off offset:896
	s_add_u32 m0, s100, 62592
	v_mfma_f32_32x32x16_bf16 v[2:17], v[140:143], v[184:187], v[2:17]
	global_load_lds_dwordx4 v[82:83], off offset:896
	ds_read_b128 v[136:139], v207
	ds_read_b128 v[184:187], v211
	ds_read_b128 v[200:203], v211 offset:4096
	ds_read_b128 v[140:143], v207 offset:4096
	s_waitcnt lgkmcnt(4)
	v_mfma_f32_32x32x16_bf16 v[34:49], v[120:123], v[128:131], v[34:49]
	v_mfma_f32_32x32x16_bf16 v[18:33], v[120:123], v[132:135], v[18:33]
	v_mfma_f32_32x32x16_bf16 v[50:65], v[124:127], v[132:135], v[50:65]
	v_mfma_f32_32x32x16_bf16 v[2:17], v[124:127], v[128:131], v[2:17]
	s_waitcnt lgkmcnt(0)
	v_mfma_f32_32x32x16_bf16 v[34:49], v[136:139], v[184:187], v[34:49]
	v_mfma_f32_32x32x16_bf16 v[18:33], v[136:139], v[200:203], v[18:33]
	v_mfma_f32_32x32x16_bf16 v[50:65], v[140:143], v[200:203], v[50:65]
	v_mfma_f32_32x32x16_bf16 v[2:17], v[140:143], v[184:187], v[2:17]
	s_setprio 0
	s_waitcnt vmcnt(0)
	s_barrier
; #define MFMA(a, b, c) __builtin_amdgcn_mfma_f32_32x32x16_bf16((a), (b), (c), 0, 0, 0)
; template <bool SWAP>
; DI void gemm_block(const bf16_t* __restrict__ A, int lda, const bf16_t* __restrict__ Bt, int ldb, int K, f32x16 (&acc)[2][2], bf16_t* sA, bf16_t* sB) {
;     ...
;   for (int kt = 0; kt < nk; ++kt) {
;     const int cur = kt & 1;
;     const bool more = kt + 1 < nk;
;     if (more) {
;       const int k0 = (kt + 1) * 64;
; #pragma unroll
;       for (int i = 0; i < 4; ++i) { ra[i] = *(const u32x4*)(ga + (size_t)i * 32 * lda + k0); rb[i] = *(const u32x4*)(gb + (size_t)i * 32 * ldb + k0); }
;     }
;     const bf16_t* ab = sA + cur * 128 * LDT + (64 * wr + l32) * LDT + h * 8;
;     const bf16_t* bb = sB + cur * 128 * LDT + (64 * wc + l32) * LDT + h * 8;
;     __builtin_amdgcn_s_setprio(1);
;     __builtin_amdgcn_iglp_opt(0);
; #pragma unroll
;     for (int ks = 0; ks < 4; ++ks) {
;       const bf16x8 a0 = *(const bf16x8*)(ab + ks * 16), a1 = *(const bf16x8*)(ab + 32 * LDT + ks * 16);
;       const bf16x8 b0 = *(const bf16x8*)(bb + ks * 16), b1 = *(const bf16x8*)(bb + 32 * LDT + ks * 16);
;       if (!SWAP) {
;         acc[0][0] = MFMA(a0, b0, acc[0][0]); acc[0][1] = MFMA(a0, b1, acc[0][1]);
;         acc[1][0] = MFMA(a1, b0, acc[1][0]); acc[1][1] = MFMA(a1, b1, acc[1][1]);
;       } else {
;         acc[0][0] = MFMA(b0, a0, acc[0][0]); acc[0][1] = MFMA(b1, a0, acc[0][1]);
;         acc[1][0] = MFMA(b0, a1, acc[1][0]); acc[1][1] = MFMA(b1, a1, acc[1][1]);
;       }
;     }
;     __builtin_amdgcn_s_setprio(0);
;     if (more) {
;       const int nb = (cur ^ 1) * 128 * LDT;
; #pragma unroll
;       for (int i = 0; i < 4; ++i) { *(u32x4*)(sA + nb + soff + i * 32 * LDT) = ra[i]; *(u32x4*)(sB + nb + soff + i * 32 * LDT) = rb[i]; }
;     }
;     __syncthreads();
;   }
	ds_read_b128 v[120:123], v204 offset:32768
	ds_read_b128 v[128:131], v208 offset:32768
	ds_read_b128 v[132:135], v208 offset:36864
	ds_read_b128 v[124:127], v204 offset:36864
	ds_read_b128 v[136:139], v205 offset:32768
	ds_read_b128 v[184:187], v209 offset:32768
	ds_read_b128 v[200:203], v209 offset:36864
	ds_read_b128 v[140:143], v205 offset:36864
	s_setprio 1
	s_waitcnt lgkmcnt(4)
	s_add_u32 m0, s100, 1024
	v_mfma_f32_32x32x16_bf16 v[34:49], v[120:123], v[128:131], v[34:49]
	global_load_lds_dwordx4 v[68:69], off offset:1024
	s_add_u32 m0, s100, 17408
	v_mfma_f32_32x32x16_bf16 v[18:33], v[120:123], v[132:135], v[18:33]
	global_load_lds_dwordx4 v[70:71], off offset:1024
	s_add_u32 m0, s100, 5120
	v_mfma_f32_32x32x16_bf16 v[50:65], v[124:127], v[132:135], v[50:65]
	global_load_lds_dwordx4 v[72:73], off offset:1024
	s_add_u32 m0, s100, 21504
	v_mfma_f32_32x32x16_bf16 v[2:17], v[124:127], v[128:131], v[2:17]
	global_load_lds_dwordx4 v[74:75], off offset:1024
	ds_read_b128 v[120:123], v206 offset:32768
	ds_read_b128 v[128:131], v210 offset:32768
	ds_read_b128 v[132:135], v210 offset:36864
	ds_read_b128 v[124:127], v206 offset:36864
	s_waitcnt lgkmcnt(4)
	s_add_u32 m0, s100, 9216
	v_mfma_f32_32x32x16_bf16 v[34:49], v[136:139], v[184:187], v[34:49]
	global_load_lds_dwordx4 v[76:77], off offset:1024
	s_add_u32 m0, s100, 25600
	v_mfma_f32_32x32x16_bf16 v[18:33], v[136:139], v[200:203], v[18:33]
	global_load_lds_dwordx4 v[78:79], off offset:1024
	s_add_u32 m0, s100, 13312
	v_mfma_f32_32x32x16_bf16 v[50:65], v[140:143], v[200:203], v[50:65]
	global_load_lds_dwordx4 v[80:81], off offset:1024
	s_add_u32 m0, s100, 29696
	v_mfma_f32_32x32x16_bf16 v[2:17], v[140:143], v[184:187], v[2:17]
	global_load_lds_dwordx4 v[82:83], off offset:1024
	ds_read_b128 v[136:139], v207 offset:32768
	ds_read_b128 v[184:187], v211 offset:32768
	ds_read_b128 v[200:203], v211 offset:36864
	ds_read_b128 v[140:143], v207 offset:36864
	s_waitcnt lgkmcnt(4)
	v_mfma_f32_32x32x16_bf16 v[34:49], v[120:123], v[128:131], v[34:49]
	v_mfma_f32_32x32x16_bf16 v[18:33], v[120:123], v[132:135], v[18:33]
	v_mfma_f32_32x32x16_bf16 v[50:65], v[124:127], v[132:135], v[50:65]
	v_mfma_f32_32x32x16_bf16 v[2:17], v[124:127], v[128:131], v[2:17]
	s_waitcnt lgkmcnt(0)
	v_mfma_f32_32x32x16_bf16 v[34:49], v[136:139], v[184:187], v[34:49]
	v_mfma_f32_32x32x16_bf16 v[18:33], v[136:139], v[200:203], v[18:33]
	v_mfma_f32_32x32x16_bf16 v[50:65], v[140:143], v[200:203], v[50:65]
	v_mfma_f32_32x32x16_bf16 v[2:17], v[140:143], v[184:187], v[2:17]
	s_setprio 0
	s_waitcnt vmcnt(0)
	s_barrier
	ds_read_b128 v[120:123], v204
	ds_read_b128 v[128:131], v208
	ds_read_b128 v[132:135], v208 offset:4096
	ds_read_b128 v[124:127], v204 offset:4096
	ds_read_b128 v[136:139], v205
	ds_read_b128 v[184:187], v209
	ds_read_b128 v[200:203], v209 offset:4096
	ds_read_b128 v[140:143], v205 offset:4096
	s_setprio 1
	s_waitcnt lgkmcnt(4)
	s_add_u32 m0, s100, 33664
	v_mfma_f32_32x32x16_bf16 v[34:49], v[120:123], v[128:131], v[34:49]
	global_load_lds_dwordx4 v[68:69], off offset:1152
	s_add_u32 m0, s100, 50048
	v_mfma_f32_32x32x16_bf16 v[18:33], v[120:123], v[132:135], v[18:33]
	global_load_lds_dwordx4 v[70:71], off offset:1152
	s_add_u32 m0, s100, 37760
	v_mfma_f32_32x32x16_bf16 v[50:65], v[124:127], v[132:135], v[50:65]
	global_load_lds_dwordx4 v[72:73], off offset:1152
	s_add_u32 m0, s100, 54144
	v_mfma_f32_32x32x16_bf16 v[2:17], v[124:127], v[128:131], v[2:17]
	global_load_lds_dwordx4 v[74:75], off offset:1152
	ds_read_b128 v[120:123], v206
	ds_read_b128 v[128:131], v210
	ds_read_b128 v[132:135], v210 offset:4096
	ds_read_b128 v[124:127], v206 offset:4096
	s_waitcnt lgkmcnt(4)
	s_add_u32 m0, s100, 41856
	v_mfma_f32_32x32x16_bf16 v[34:49], v[136:139], v[184:187], v[34:49]
	global_load_lds_dwordx4 v[76:77], off offset:1152
	s_add_u32 m0, s100, 58240
	v_mfma_f32_32x32x16_bf16 v[18:33], v[136:139], v[200:203], v[18:33]
	global_load_lds_dwordx4 v[78:79], off offset:1152
	s_add_u32 m0, s100, 45952
	v_mfma_f32_32x32x16_bf16 v[50:65], v[140:143], v[200:203], v[50:65]
	global_load_lds_dwordx4 v[80:81], off offset:1152
	s_add_u32 m0, s100, 62336
	v_mfma_f32_32x32x16_bf16 v[2:17], v[140:143], v[184:187], v[2:17]
	global_load_lds_dwordx4 v[82:83], off offset:1152
	ds_read_b128 v[136:139], v207
	ds_read_b128 v[184:187], v211
	ds_read_b128 v[200:203], v211 offset:4096
	ds_read_b128 v[140:143], v207 offset:4096
	s_waitcnt lgkmcnt(4)
	v_mfma_f32_32x32x16_bf16 v[34:49], v[120:123], v[128:131], v[34:49]
	v_mfma_f32_32x32x16_bf16 v[18:33], v[120:123], v[132:135], v[18:33]
	v_mfma_f32_32x32x16_bf16 v[50:65], v[124:127], v[132:135], v[50:65]
	v_mfma_f32_32x32x16_bf16 v[2:17], v[124:127], v[128:131], v[2:17]
	s_waitcnt lgkmcnt(0)
	v_mfma_f32_32x32x16_bf16 v[34:49], v[136:139], v[184:187], v[34:49]
	v_mfma_f32_32x32x16_bf16 v[18:33], v[136:139], v[200:203], v[18:33]
	v_mfma_f32_32x32x16_bf16 v[50:65], v[140:143], v[200:203], v[50:65]
	v_mfma_f32_32x32x16_bf16 v[2:17], v[140:143], v[184:187], v[2:17]
	s_setprio 0
	s_waitcnt vmcnt(0)
	s_barrier
; #define MFMA(a, b, c) __builtin_amdgcn_mfma_f32_32x32x16_bf16((a), (b), (c), 0, 0, 0)
; template <bool SWAP>
; DI void gemm_block(const bf16_t* __restrict__ A, int lda, const bf16_t* __restrict__ Bt, int ldb, int K, f32x16 (&acc)[2][2], bf16_t* sA, bf16_t* sB) {
;     ...
;   for (int kt = 0; kt < nk; ++kt) {
;     const int cur = kt & 1;
;     const bool more = kt + 1 < nk;
;     if (more) {
;       const int k0 = (kt + 1) * 64;
; #pragma unroll
;       for (int i = 0; i < 4; ++i) { ra[i] = *(const u32x4*)(ga + (size_t)i * 32 * lda + k0); rb[i] = *(const u32x4*)(gb + (size_t)i * 32 * ldb + k0); }
;     }
;     const bf16_t* ab = sA + cur * 128 * LDT + (64 * wr + l32) * LDT + h * 8;
;     const bf16_t* bb = sB + cur * 128 * LDT + (64 * wc + l32) * LDT + h * 8;
;     __builtin_amdgcn_s_setprio(1);
;     __builtin_amdgcn_iglp_opt(0);
; #pragma unroll
;     for (int ks = 0; ks < 4; ++ks) {
;       const bf16x8 a0 = *(const bf16x8*)(ab + ks * 16), a1 = *(const bf16x8*)(ab + 32 * LDT + ks * 16);
;       const bf16x8 b0 = *(const bf16x8*)(bb + ks * 16), b1 = *(const bf16x8*)(bb + 32 * LDT + ks * 16);
;       if (!SWAP) {
;         acc[0][0] = MFMA(a0, b0, acc[0][0]); acc[0][1] = MFMA(a0, b1, acc[0][1]);
;         acc[1][0] = MFMA(a1, b0, acc[1][0]); acc[1][1] = MFMA(a1, b1, acc[1][1]);
;       } else {
;         acc[0][0] = MFMA(b0, a0, acc[0][0]); acc[0][1] = MFMA(b1, a0, acc[0][1]);
;         acc[1][0] = MFMA(b0, a1, acc[1][0]); acc[1][1] = MFMA(b1, a1, acc[1][1]);
;       }
;     }
;     __builtin_amdgcn_s_setprio(0);
;     if (more) {
;       const int nb = (cur ^ 1) * 128 * LDT;
; #pragma unroll
;       for (int i = 0; i < 4; ++i) { *(u32x4*)(sA + nb + soff + i * 32 * LDT) = ra[i]; *(u32x4*)(sB + nb + soff + i * 32 * LDT) = rb[i]; }
;     }
;     __syncthreads();
;   }
	ds_read_b128 v[120:123], v204 offset:32768
	ds_read_b128 v[128:131], v208 offset:32768
	ds_read_b128 v[132:135], v208 offset:36864
	ds_read_b128 v[124:127], v204 offset:36864
	ds_read_b128 v[136:139], v205 offset:32768
	ds_read_b128 v[184:187], v209 offset:32768
	ds_read_b128 v[200:203], v209 offset:36864
	ds_read_b128 v[140:143], v205 offset:36864
	s_setprio 1
	s_waitcnt lgkmcnt(4)
	s_add_u32 m0, s100, 768
	v_mfma_f32_32x32x16_bf16 v[34:49], v[120:123], v[128:131], v[34:49]
	global_load_lds_dwordx4 v[68:69], off offset:1280
	s_add_u32 m0, s100, 17152
	v_mfma_f32_32x32x16_bf16 v[18:33], v[120:123], v[132:135], v[18:33]
	global_load_lds_dwordx4 v[70:71], off offset:1280
	s_add_u32 m0, s100, 4864
	v_mfma_f32_32x32x16_bf16 v[50:65], v[124:127], v[132:135], v[50:65]
	global_load_lds_dwordx4 v[72:73], off offset:1280
	s_add_u32 m0, s100, 21248
	v_mfma_f32_32x32x16_bf16 v[2:17], v[124:127], v[128:131], v[2:17]
	global_load_lds_dwordx4 v[74:75], off offset:1280
	ds_read_b128 v[120:123], v206 offset:32768
	ds_read_b128 v[128:131], v210 offset:32768
	ds_read_b128 v[132:135], v210 offset:36864
	ds_read_b128 v[124:127], v206 offset:36864
	s_waitcnt lgkmcnt(4)
	s_add_u32 m0, s100, 8960
	v_mfma_f32_32x32x16_bf16 v[34:49], v[136:139], v[184:187], v[34:49]
	global_load_lds_dwordx4 v[76:77], off offset:1280
	s_add_u32 m0, s100, 25344
	v_mfma_f32_32x32x16_bf16 v[18:33], v[136:139], v[200:203], v[18:33]
	global_load_lds_dwordx4 v[78:79], off offset:1280
	s_add_u32 m0, s100, 13056
	v_mfma_f32_32x32x16_bf16 v[50:65], v[140:143], v[200:203], v[50:65]
	global_load_lds_dwordx4 v[80:81], off offset:1280
	s_add_u32 m0, s100, 29440
	v_mfma_f32_32x32x16_bf16 v[2:17], v[140:143], v[184:187], v[2:17]
	global_load_lds_dwordx4 v[82:83], off offset:1280
	ds_read_b128 v[136:139], v207 offset:32768
	ds_read_b128 v[184:187], v211 offset:32768
	ds_read_b128 v[200:203], v211 offset:36864
	ds_read_b128 v[140:143], v207 offset:36864
	s_waitcnt lgkmcnt(4)
	v_mfma_f32_32x32x16_bf16 v[34:49], v[120:123], v[128:131], v[34:49]
	v_mfma_f32_32x32x16_bf16 v[18:33], v[120:123], v[132:135], v[18:33]
	v_mfma_f32_32x32x16_bf16 v[50:65], v[124:127], v[132:135], v[50:65]
	v_mfma_f32_32x32x16_bf16 v[2:17], v[124:127], v[128:131], v[2:17]
	s_waitcnt lgkmcnt(0)
	v_mfma_f32_32x32x16_bf16 v[34:49], v[136:139], v[184:187], v[34:49]
	v_mfma_f32_32x32x16_bf16 v[18:33], v[136:139], v[200:203], v[18:33]
	v_mfma_f32_32x32x16_bf16 v[50:65], v[140:143], v[200:203], v[50:65]
	v_mfma_f32_32x32x16_bf16 v[2:17], v[140:143], v[184:187], v[2:17]
	s_setprio 0
	s_waitcnt vmcnt(0)
	s_barrier
	ds_read_b128 v[120:123], v204
	ds_read_b128 v[128:131], v208
	ds_read_b128 v[132:135], v208 offset:4096
	ds_read_b128 v[124:127], v204 offset:4096
	ds_read_b128 v[136:139], v205
	ds_read_b128 v[184:187], v209
	ds_read_b128 v[200:203], v209 offset:4096
	ds_read_b128 v[140:143], v205 offset:4096
	s_setprio 1
	s_waitcnt lgkmcnt(4)
	s_add_u32 m0, s100, 33408
	v_mfma_f32_32x32x16_bf16 v[34:49], v[120:123], v[128:131], v[34:49]
	global_load_lds_dwordx4 v[68:69], off offset:1408
	s_add_u32 m0, s100, 49792
	v_mfma_f32_32x32x16_bf16 v[18:33], v[120:123], v[132:135], v[18:33]
	global_load_lds_dwordx4 v[70:71], off offset:1408
	s_add_u32 m0, s100, 37504
	v_mfma_f32_32x32x16_bf16 v[50:65], v[124:127], v[132:135], v[50:65]
	global_load_lds_dwordx4 v[72:73], off offset:1408
	s_add_u32 m0, s100, 53888
	v_mfma_f32_32x32x16_bf16 v[2:17], v[124:127], v[128:131], v[2:17]
	global_load_lds_dwordx4 v[74:75], off offset:1408
	ds_read_b128 v[120:123], v206
	ds_read_b128 v[128:131], v210
	ds_read_b128 v[132:135], v210 offset:4096
	ds_read_b128 v[124:127], v206 offset:4096
	s_waitcnt lgkmcnt(4)
	s_add_u32 m0, s100, 41600
	v_mfma_f32_32x32x16_bf16 v[34:49], v[136:139], v[184:187], v[34:49]
	global_load_lds_dwordx4 v[76:77], off offset:1408
	s_add_u32 m0, s100, 57984
	v_mfma_f32_32x32x16_bf16 v[18:33], v[136:139], v[200:203], v[18:33]
	global_load_lds_dwordx4 v[78:79], off offset:1408
	s_add_u32 m0, s100, 45696
	v_mfma_f32_32x32x16_bf16 v[50:65], v[140:143], v[200:203], v[50:65]
	global_load_lds_dwordx4 v[80:81], off offset:1408
	s_add_u32 m0, s100, 62080
	v_mfma_f32_32x32x16_bf16 v[2:17], v[140:143], v[184:187], v[2:17]
	global_load_lds_dwordx4 v[82:83], off offset:1408
	ds_read_b128 v[136:139], v207
	ds_read_b128 v[184:187], v211
	ds_read_b128 v[200:203], v211 offset:4096
	ds_read_b128 v[140:143], v207 offset:4096
	s_waitcnt lgkmcnt(4)
	v_mfma_f32_32x32x16_bf16 v[34:49], v[120:123], v[128:131], v[34:49]
	v_mfma_f32_32x32x16_bf16 v[18:33], v[120:123], v[132:135], v[18:33]
	v_mfma_f32_32x32x16_bf16 v[50:65], v[124:127], v[132:135], v[50:65]
	v_mfma_f32_32x32x16_bf16 v[2:17], v[124:127], v[128:131], v[2:17]
	s_waitcnt lgkmcnt(0)
	v_mfma_f32_32x32x16_bf16 v[34:49], v[136:139], v[184:187], v[34:49]
	v_mfma_f32_32x32x16_bf16 v[18:33], v[136:139], v[200:203], v[18:33]
	v_mfma_f32_32x32x16_bf16 v[50:65], v[140:143], v[200:203], v[50:65]
	v_mfma_f32_32x32x16_bf16 v[2:17], v[140:143], v[184:187], v[2:17]
	s_setprio 0
	s_waitcnt vmcnt(0)
	s_barrier
; #define MFMA(a, b, c) __builtin_amdgcn_mfma_f32_32x32x16_bf16((a), (b), (c), 0, 0, 0)
; template <bool SWAP>
; DI void gemm_block(const bf16_t* __restrict__ A, int lda, const bf16_t* __restrict__ Bt, int ldb, int K, f32x16 (&acc)[2][2], bf16_t* sA, bf16_t* sB) {
;     ...
;   for (int kt = 0; kt < nk; ++kt) {
;     const int cur = kt & 1;
;     const bool more = kt + 1 < nk;
;     if (more) {
;       const int k0 = (kt + 1) * 64;
; #pragma unroll
;       for (int i = 0; i < 4; ++i) { ra[i] = *(const u32x4*)(ga + (size_t)i * 32 * lda + k0); rb[i] = *(const u32x4*)(gb + (size_t)i * 32 * ldb + k0); }
;     }
;     const bf16_t* ab = sA + cur * 128 * LDT + (64 * wr + l32) * LDT + h * 8;
;     const bf16_t* bb = sB + cur * 128 * LDT + (64 * wc + l32) * LDT + h * 8;
;     __builtin_amdgcn_s_setprio(1);
;     __builtin_amdgcn_iglp_opt(0);
; #pragma unroll
;     for (int ks = 0; ks < 4; ++ks) {
;       const bf16x8 a0 = *(const bf16x8*)(ab + ks * 16), a1 = *(const bf16x8*)(ab + 32 * LDT + ks * 16);
;       const bf16x8 b0 = *(const bf16x8*)(bb + ks * 16), b1 = *(const bf16x8*)(bb + 32 * LDT + ks * 16);
;       if (!SWAP) {
;         acc[0][0] = MFMA(a0, b0, acc[0][0]); acc[0][1] = MFMA(a0, b1, acc[0][1]);
;         acc[1][0] = MFMA(a1, b0, acc[1][0]); acc[1][1] = MFMA(a1, b1, acc[1][1]);
;       } else {
;         acc[0][0] = MFMA(b0, a0, acc[0][0]); acc[0][1] = MFMA(b1, a0, acc[0][1]);
;         acc[1][0] = MFMA(b0, a1, acc[1][0]); acc[1][1] = MFMA(b1, a1, acc[1][1]);
;       }
;     }
;     __builtin_amdgcn_s_setprio(0);
;     if (more) {
;       const int nb = (cur ^ 1) * 128 * LDT;
; #pragma unroll
;       for (int i = 0; i < 4; ++i) { *(u32x4*)(sA + nb + soff + i * 32 * LDT) = ra[i]; *(u32x4*)(sB + nb + soff + i * 32 * LDT) = rb[i]; }
;     }
;     __syncthreads();
;   }
	ds_read_b128 v[120:123], v204 offset:32768
	ds_read_b128 v[128:131], v208 offset:32768
	ds_read_b128 v[132:135], v208 offset:36864
	ds_read_b128 v[124:127], v204 offset:36864
	ds_read_b128 v[136:139], v205 offset:32768
	ds_read_b128 v[184:187], v209 offset:32768
	ds_read_b128 v[200:203], v209 offset:36864
	ds_read_b128 v[140:143], v205 offset:36864
	s_setprio 1
	s_waitcnt lgkmcnt(4)
	s_add_u32 m0, s100, 512
	v_mfma_f32_32x32x16_bf16 v[34:49], v[120:123], v[128:131], v[34:49]
	global_load_lds_dwordx4 v[68:69], off offset:1536
	s_add_u32 m0, s100, 16896
	v_mfma_f32_32x32x16_bf16 v[18:33], v[120:123], v[132:135], v[18:33]
	global_load_lds_dwordx4 v[70:71], off offset:1536
	s_add_u32 m0, s100, 4608
	v_mfma_f32_32x32x16_bf16 v[50:65], v[124:127], v[132:135], v[50:65]
	global_load_lds_dwordx4 v[72:73], off offset:1536
	s_add_u32 m0, s100, 20992
	v_mfma_f32_32x32x16_bf16 v[2:17], v[124:127], v[128:131], v[2:17]
	global_load_lds_dwordx4 v[74:75], off offset:1536
	ds_read_b128 v[120:123], v206 offset:32768
	ds_read_b128 v[128:131], v210 offset:32768
	ds_read_b128 v[132:135], v210 offset:36864
	ds_read_b128 v[124:127], v206 offset:36864
	s_waitcnt lgkmcnt(4)
	s_add_u32 m0, s100, 8704
	v_mfma_f32_32x32x16_bf16 v[34:49], v[136:139], v[184:187], v[34:49]
	global_load_lds_dwordx4 v[76:77], off offset:1536
	s_add_u32 m0, s100, 25088
	v_mfma_f32_32x32x16_bf16 v[18:33], v[136:139], v[200:203], v[18:33]
	global_load_lds_dwordx4 v[78:79], off offset:1536
	s_add_u32 m0, s100, 12800
	v_mfma_f32_32x32x16_bf16 v[50:65], v[140:143], v[200:203], v[50:65]
	global_load_lds_dwordx4 v[80:81], off offset:1536
	s_add_u32 m0, s100, 29184
	v_mfma_f32_32x32x16_bf16 v[2:17], v[140:143], v[184:187], v[2:17]
	global_load_lds_dwordx4 v[82:83], off offset:1536
	ds_read_b128 v[136:139], v207 offset:32768
	ds_read_b128 v[184:187], v211 offset:32768
	ds_read_b128 v[200:203], v211 offset:36864
	ds_read_b128 v[140:143], v207 offset:36864
	s_waitcnt lgkmcnt(4)
	v_mfma_f32_32x32x16_bf16 v[34:49], v[120:123], v[128:131], v[34:49]
	v_mfma_f32_32x32x16_bf16 v[18:33], v[120:123], v[132:135], v[18:33]
	v_mfma_f32_32x32x16_bf16 v[50:65], v[124:127], v[132:135], v[50:65]
	v_mfma_f32_32x32x16_bf16 v[2:17], v[124:127], v[128:131], v[2:17]
	s_waitcnt lgkmcnt(0)
	v_mfma_f32_32x32x16_bf16 v[34:49], v[136:139], v[184:187], v[34:49]
	v_mfma_f32_32x32x16_bf16 v[18:33], v[136:139], v[200:203], v[18:33]
	v_mfma_f32_32x32x16_bf16 v[50:65], v[140:143], v[200:203], v[50:65]
	v_mfma_f32_32x32x16_bf16 v[2:17], v[140:143], v[184:187], v[2:17]
	s_setprio 0
	s_waitcnt vmcnt(0)
	s_barrier
	ds_read_b128 v[120:123], v204
	ds_read_b128 v[128:131], v208
	ds_read_b128 v[132:135], v208 offset:4096
	ds_read_b128 v[124:127], v204 offset:4096
	ds_read_b128 v[136:139], v205
	ds_read_b128 v[184:187], v209
	ds_read_b128 v[200:203], v209 offset:4096
	ds_read_b128 v[140:143], v205 offset:4096
	s_setprio 1
	s_waitcnt lgkmcnt(4)
	s_add_u32 m0, s100, 33152
	v_mfma_f32_32x32x16_bf16 v[34:49], v[120:123], v[128:131], v[34:49]
	global_load_lds_dwordx4 v[68:69], off offset:1664
	s_add_u32 m0, s100, 49536
	v_mfma_f32_32x32x16_bf16 v[18:33], v[120:123], v[132:135], v[18:33]
	global_load_lds_dwordx4 v[70:71], off offset:1664
	s_add_u32 m0, s100, 37248
	v_mfma_f32_32x32x16_bf16 v[50:65], v[124:127], v[132:135], v[50:65]
	global_load_lds_dwordx4 v[72:73], off offset:1664
	s_add_u32 m0, s100, 53632
	v_mfma_f32_32x32x16_bf16 v[2:17], v[124:127], v[128:131], v[2:17]
	global_load_lds_dwordx4 v[74:75], off offset:1664
	ds_read_b128 v[120:123], v206
	ds_read_b128 v[128:131], v210
	ds_read_b128 v[132:135], v210 offset:4096
	ds_read_b128 v[124:127], v206 offset:4096
	s_waitcnt lgkmcnt(4)
	s_add_u32 m0, s100, 41344
	v_mfma_f32_32x32x16_bf16 v[34:49], v[136:139], v[184:187], v[34:49]
	global_load_lds_dwordx4 v[76:77], off offset:1664
	s_add_u32 m0, s100, 57728
	v_mfma_f32_32x32x16_bf16 v[18:33], v[136:139], v[200:203], v[18:33]
	global_load_lds_dwordx4 v[78:79], off offset:1664
	s_add_u32 m0, s100, 45440
	v_mfma_f32_32x32x16_bf16 v[50:65], v[140:143], v[200:203], v[50:65]
	global_load_lds_dwordx4 v[80:81], off offset:1664
	s_add_u32 m0, s100, 61824
	v_mfma_f32_32x32x16_bf16 v[2:17], v[140:143], v[184:187], v[2:17]
	global_load_lds_dwordx4 v[82:83], off offset:1664
	ds_read_b128 v[136:139], v207
	ds_read_b128 v[184:187], v211
	ds_read_b128 v[200:203], v211 offset:4096
	ds_read_b128 v[140:143], v207 offset:4096
	s_waitcnt lgkmcnt(4)
	v_mfma_f32_32x32x16_bf16 v[34:49], v[120:123], v[128:131], v[34:49]
	v_mfma_f32_32x32x16_bf16 v[18:33], v[120:123], v[132:135], v[18:33]
	v_mfma_f32_32x32x16_bf16 v[50:65], v[124:127], v[132:135], v[50:65]
	v_mfma_f32_32x32x16_bf16 v[2:17], v[124:127], v[128:131], v[2:17]
	s_waitcnt lgkmcnt(0)
	v_mfma_f32_32x32x16_bf16 v[34:49], v[136:139], v[184:187], v[34:49]
	v_mfma_f32_32x32x16_bf16 v[18:33], v[136:139], v[200:203], v[18:33]
	v_mfma_f32_32x32x16_bf16 v[50:65], v[140:143], v[200:203], v[50:65]
	v_mfma_f32_32x32x16_bf16 v[2:17], v[140:143], v[184:187], v[2:17]
	s_setprio 0
	s_waitcnt vmcnt(0)
	s_barrier
; #define MFMA(a, b, c) __builtin_amdgcn_mfma_f32_32x32x16_bf16((a), (b), (c), 0, 0, 0)
; template <bool SWAP>
; DI void gemm_block(const bf16_t* __restrict__ A, int lda, const bf16_t* __restrict__ Bt, int ldb, int K, f32x16 (&acc)[2][2], bf16_t* sA, bf16_t* sB) {
;     ...
;   for (int kt = 0; kt < nk; ++kt) {
;     const int cur = kt & 1;
;     const bool more = kt + 1 < nk;
;     if (more) {
;       const int k0 = (kt + 1) * 64;
; #pragma unroll
;       for (int i = 0; i < 4; ++i) { ra[i] = *(const u32x4*)(ga + (size_t)i * 32 * lda + k0); rb[i] = *(const u32x4*)(gb + (size_t)i * 32 * ldb + k0); }
;     }
;     const bf16_t* ab = sA + cur * 128 * LDT + (64 * wr + l32) * LDT + h * 8;
;     const bf16_t* bb = sB + cur * 128 * LDT + (64 * wc + l32) * LDT + h * 8;
;     __builtin_amdgcn_s_setprio(1);
;     __builtin_amdgcn_iglp_opt(0);
; #pragma unroll
;     for (int ks = 0; ks < 4; ++ks) {
;       const bf16x8 a0 = *(const bf16x8*)(ab + ks * 16), a1 = *(const bf16x8*)(ab + 32 * LDT + ks * 16);
;       const bf16x8 b0 = *(const bf16x8*)(bb + ks * 16), b1 = *(const bf16x8*)(bb + 32 * LDT + ks * 16);
;       if (!SWAP) {
;         acc[0][0] = MFMA(a0, b0, acc[0][0]); acc[0][1] = MFMA(a0, b1, acc[0][1]);
;         acc[1][0] = MFMA(a1, b0, acc[1][0]); acc[1][1] = MFMA(a1, b1, acc[1][1]);
;       } else {
;         acc[0][0] = MFMA(b0, a0, acc[0][0]); acc[0][1] = MFMA(b1, a0, acc[0][1]);
;         acc[1][0] = MFMA(b0, a1, acc[1][0]); acc[1][1] = MFMA(b1, a1, acc[1][1]);
;       }
;     }
;     __builtin_amdgcn_s_setprio(0);
;     if (more) {
;       const int nb = (cur ^ 1) * 128 * LDT;
; #pragma unroll
;       for (int i = 0; i < 4; ++i) { *(u32x4*)(sA + nb + soff + i * 32 * LDT) = ra[i]; *(u32x4*)(sB + nb + soff + i * 32 * LDT) = rb[i]; }
;     }
;     __syncthreads();
;   }
	ds_read_b128 v[120:123], v204 offset:32768
	ds_read_b128 v[128:131], v208 offset:32768
	ds_read_b128 v[132:135], v208 offset:36864
	ds_read_b128 v[124:127], v204 offset:36864
	ds_read_b128 v[136:139], v205 offset:32768
	ds_read_b128 v[184:187], v209 offset:32768
	ds_read_b128 v[200:203], v209 offset:36864
	ds_read_b128 v[140:143], v205 offset:36864
	s_setprio 1
	s_waitcnt lgkmcnt(4)
	s_add_u32 m0, s100, 256
	v_mfma_f32_32x32x16_bf16 v[34:49], v[120:123], v[128:131], v[34:49]
	global_load_lds_dwordx4 v[68:69], off offset:1792
	s_add_u32 m0, s100, 16640
	v_mfma_f32_32x32x16_bf16 v[18:33], v[120:123], v[132:135], v[18:33]
	global_load_lds_dwordx4 v[70:71], off offset:1792
	s_add_u32 m0, s100, 4352
	v_mfma_f32_32x32x16_bf16 v[50:65], v[124:127], v[132:135], v[50:65]
	global_load_lds_dwordx4 v[72:73], off offset:1792
	s_add_u32 m0, s100, 20736
	v_mfma_f32_32x32x16_bf16 v[2:17], v[124:127], v[128:131], v[2:17]
	global_load_lds_dwordx4 v[74:75], off offset:1792
	ds_read_b128 v[120:123], v206 offset:32768
	ds_read_b128 v[128:131], v210 offset:32768
	ds_read_b128 v[132:135], v210 offset:36864
	ds_read_b128 v[124:127], v206 offset:36864
	s_waitcnt lgkmcnt(4)
	s_add_u32 m0, s100, 8448
	v_mfma_f32_32x32x16_bf16 v[34:49], v[136:139], v[184:187], v[34:49]
	global_load_lds_dwordx4 v[76:77], off offset:1792
	s_add_u32 m0, s100, 24832
	v_mfma_f32_32x32x16_bf16 v[18:33], v[136:139], v[200:203], v[18:33]
	global_load_lds_dwordx4 v[78:79], off offset:1792
	s_add_u32 m0, s100, 12544
	v_mfma_f32_32x32x16_bf16 v[50:65], v[140:143], v[200:203], v[50:65]
	global_load_lds_dwordx4 v[80:81], off offset:1792
	s_add_u32 m0, s100, 28928
	v_mfma_f32_32x32x16_bf16 v[2:17], v[140:143], v[184:187], v[2:17]
	global_load_lds_dwordx4 v[82:83], off offset:1792
	ds_read_b128 v[136:139], v207 offset:32768
	ds_read_b128 v[184:187], v211 offset:32768
	ds_read_b128 v[200:203], v211 offset:36864
	ds_read_b128 v[140:143], v207 offset:36864
	s_waitcnt lgkmcnt(4)
	v_mfma_f32_32x32x16_bf16 v[34:49], v[120:123], v[128:131], v[34:49]
	v_mfma_f32_32x32x16_bf16 v[18:33], v[120:123], v[132:135], v[18:33]
	v_mfma_f32_32x32x16_bf16 v[50:65], v[124:127], v[132:135], v[50:65]
	v_mfma_f32_32x32x16_bf16 v[2:17], v[124:127], v[128:131], v[2:17]
	s_waitcnt lgkmcnt(0)
	v_mfma_f32_32x32x16_bf16 v[34:49], v[136:139], v[184:187], v[34:49]
	v_mfma_f32_32x32x16_bf16 v[18:33], v[136:139], v[200:203], v[18:33]
	v_mfma_f32_32x32x16_bf16 v[50:65], v[140:143], v[200:203], v[50:65]
	v_mfma_f32_32x32x16_bf16 v[2:17], v[140:143], v[184:187], v[2:17]
	s_setprio 0
	s_waitcnt vmcnt(0)
	s_barrier
	ds_read_b128 v[120:123], v204
	ds_read_b128 v[128:131], v208
	ds_read_b128 v[132:135], v208 offset:4096
	ds_read_b128 v[124:127], v204 offset:4096
	ds_read_b128 v[136:139], v205
	ds_read_b128 v[184:187], v209
	ds_read_b128 v[200:203], v209 offset:4096
	ds_read_b128 v[140:143], v205 offset:4096
	s_setprio 1
	s_waitcnt lgkmcnt(4)
	s_add_u32 m0, s100, 32896
	v_mfma_f32_32x32x16_bf16 v[34:49], v[120:123], v[128:131], v[34:49]
	global_load_lds_dwordx4 v[68:69], off offset:1920
	s_add_u32 m0, s100, 49280
	v_mfma_f32_32x32x16_bf16 v[18:33], v[120:123], v[132:135], v[18:33]
	global_load_lds_dwordx4 v[70:71], off offset:1920
	s_add_u32 m0, s100, 36992
	v_mfma_f32_32x32x16_bf16 v[50:65], v[124:127], v[132:135], v[50:65]
	global_load_lds_dwordx4 v[72:73], off offset:1920
	s_add_u32 m0, s100, 53376
	v_mfma_f32_32x32x16_bf16 v[2:17], v[124:127], v[128:131], v[2:17]
	global_load_lds_dwordx4 v[74:75], off offset:1920
	ds_read_b128 v[120:123], v206
	ds_read_b128 v[128:131], v210
	ds_read_b128 v[132:135], v210 offset:4096
	ds_read_b128 v[124:127], v206 offset:4096
	s_waitcnt lgkmcnt(4)
	s_add_u32 m0, s100, 41088
	v_mfma_f32_32x32x16_bf16 v[34:49], v[136:139], v[184:187], v[34:49]
	global_load_lds_dwordx4 v[76:77], off offset:1920
	s_add_u32 m0, s100, 57472
	v_mfma_f32_32x32x16_bf16 v[18:33], v[136:139], v[200:203], v[18:33]
	global_load_lds_dwordx4 v[78:79], off offset:1920
	s_add_u32 m0, s100, 45184
	v_mfma_f32_32x32x16_bf16 v[50:65], v[140:143], v[200:203], v[50:65]
	global_load_lds_dwordx4 v[80:81], off offset:1920
	s_add_u32 m0, s100, 61568
	v_mfma_f32_32x32x16_bf16 v[2:17], v[140:143], v[184:187], v[2:17]
	global_load_lds_dwordx4 v[82:83], off offset:1920
	ds_read_b128 v[136:139], v207
	ds_read_b128 v[184:187], v211
	ds_read_b128 v[200:203], v211 offset:4096
	ds_read_b128 v[140:143], v207 offset:4096
	s_waitcnt lgkmcnt(4)
	v_mfma_f32_32x32x16_bf16 v[34:49], v[120:123], v[128:131], v[34:49]
	v_mfma_f32_32x32x16_bf16 v[18:33], v[120:123], v[132:135], v[18:33]
	v_mfma_f32_32x32x16_bf16 v[50:65], v[124:127], v[132:135], v[50:65]
	v_mfma_f32_32x32x16_bf16 v[2:17], v[124:127], v[128:131], v[2:17]
	s_waitcnt lgkmcnt(0)
	v_mfma_f32_32x32x16_bf16 v[34:49], v[136:139], v[184:187], v[34:49]
	v_mfma_f32_32x32x16_bf16 v[18:33], v[136:139], v[200:203], v[18:33]
	v_mfma_f32_32x32x16_bf16 v[50:65], v[140:143], v[200:203], v[50:65]
	v_mfma_f32_32x32x16_bf16 v[2:17], v[140:143], v[184:187], v[2:17]
	s_setprio 0
	s_waitcnt vmcnt(0)
	s_barrier
	ds_read_b128 v[120:123], v204 offset:32768
	ds_read_b128 v[128:131], v208 offset:32768
	ds_read_b128 v[132:135], v208 offset:36864
	ds_read_b128 v[124:127], v204 offset:36864
	ds_read_b128 v[136:139], v205 offset:32768
	ds_read_b128 v[184:187], v209 offset:32768
	ds_read_b128 v[200:203], v209 offset:36864
	ds_read_b128 v[140:143], v205 offset:36864
	s_setprio 1
	s_waitcnt lgkmcnt(4)
	v_mfma_f32_32x32x16_bf16 v[34:49], v[120:123], v[128:131], v[34:49]
	v_mfma_f32_32x32x16_bf16 v[18:33], v[120:123], v[132:135], v[18:33]
	v_mfma_f32_32x32x16_bf16 v[50:65], v[124:127], v[132:135], v[50:65]
	v_mfma_f32_32x32x16_bf16 v[2:17], v[124:127], v[128:131], v[2:17]
	ds_read_b128 v[120:123], v206 offset:32768
	ds_read_b128 v[128:131], v210 offset:32768
	ds_read_b128 v[132:135], v210 offset:36864
	ds_read_b128 v[124:127], v206 offset:36864
	s_waitcnt lgkmcnt(4)
	v_mfma_f32_32x32x16_bf16 v[34:49], v[136:139], v[184:187], v[34:49]
	v_mfma_f32_32x32x16_bf16 v[18:33], v[136:139], v[200:203], v[18:33]
	v_mfma_f32_32x32x16_bf16 v[50:65], v[140:143], v[200:203], v[50:65]
	v_mfma_f32_32x32x16_bf16 v[2:17], v[140:143], v[184:187], v[2:17]
	ds_read_b128 v[136:139], v207 offset:32768
	ds_read_b128 v[184:187], v211 offset:32768
	ds_read_b128 v[200:203], v211 offset:36864
	ds_read_b128 v[140:143], v207 offset:36864
	s_waitcnt lgkmcnt(4)
	v_mfma_f32_32x32x16_bf16 v[34:49], v[120:123], v[128:131], v[34:49]
	v_mfma_f32_32x32x16_bf16 v[18:33], v[120:123], v[132:135], v[18:33]
	v_mfma_f32_32x32x16_bf16 v[50:65], v[124:127], v[132:135], v[50:65]
	v_mfma_f32_32x32x16_bf16 v[2:17], v[124:127], v[128:131], v[2:17]
	s_waitcnt lgkmcnt(0)
	v_mfma_f32_32x32x16_bf16 v[34:49], v[136:139], v[184:187], v[34:49]
	v_mfma_f32_32x32x16_bf16 v[18:33], v[136:139], v[200:203], v[18:33]
	v_mfma_f32_32x32x16_bf16 v[50:65], v[140:143], v[200:203], v[50:65]
	v_mfma_f32_32x32x16_bf16 v[2:17], v[140:143], v[184:187], v[2:17]
	s_setprio 0
	s_nop 7
	s_nop 7
	s_barrier

; template <bool SWAP>
; DI void gemm_block(const bf16_t* __restrict__ A, int lda, const bf16_t* __restrict__ Bt, int ldb, int K, f32x16 (&acc)[2][2], bf16_t* sA, bf16_t* sB) {
;     ...
;   const int lrow = tid >> 3, lch = (tid & 7) * 8;
;   const bf16_t* ga = A + (size_t)lrow * lda + lch;
;   const bf16_t* gb = Bt + (size_t)lrow * ldb + lch;
;   const int soff = lrow * LDT + lch;
;   u32x4 ra[4], rb[4];
; #pragma unroll
;   for (int i = 0; i < 4; ++i) { ra[i] = *(const u32x4*)(ga + (size_t)i * 32 * lda); rb[i] = *(const u32x4*)(gb + (size_t)i * 32 * ldb); }
; #pragma unroll
;   for (int i = 0; i < 4; ++i) { *(u32x4*)(sA + soff + i * 32 * LDT) = ra[i]; *(u32x4*)(sB + soff + i * 32 * LDT) = rb[i]; }
;   __syncthreads();
;   const int nk = K >> 6;
;   for (int kt = 0; kt < nk; ++kt) {
;     const int cur = kt & 1;
;     const bool more = kt + 1 < nk;
;     if (more) {
;       const int k0 = (kt + 1) * 64;
; #pragma unroll
;       for (int i = 0; i < 4; ++i) { ra[i] = *(const u32x4*)(ga + (size_t)i * 32 * lda + k0); rb[i] = *(const u32x4*)(gb + (size_t)i * 32 * ldb + k0); }
;     }
;     const bf16_t* ab = sA + cur * 128 * LDT + (64 * wr + l32) * LDT + h * 8;
;     const bf16_t* bb = sB + cur * 128 * LDT + (64 * wc + l32) * LDT + h * 8;
;     __builtin_amdgcn_s_setprio(1);
;     __builtin_amdgcn_iglp_opt(0);
; #pragma unroll
;     for (int ks = 0; ks < 4; ++ks) {
;       const bf16x8 a0 = *(const bf16x8*)(ab + ks * 16), a1 = *(const bf16x8*)(ab + 32 * LDT + ks * 16);
;       const bf16x8 b0 = *(const bf16x8*)(bb + ks * 16), b1 = *(const bf16x8*)(bb + 32 * LDT + ks * 16);
;       if (!SWAP) {
;         acc[0][0] = MFMA(a0, b0, acc[0][0]); acc[0][1] = MFMA(a0, b1, acc[0][1]);
;         acc[1][0] = MFMA(a1, b0, acc[1][0]); acc[1][1] = MFMA(a1, b1, acc[1][1]);
;       } else {
;         acc[0][0] = MFMA(b0, a0, acc[0][0]); acc[0][1] = MFMA(b1, a0, acc[0][1]);
;         acc[1][0] = MFMA(b0, a1, acc[1][0]); acc[1][1] = MFMA(b1, a1, acc[1][1]);
;       }
;     }
; DI void phase4(PP p, int l, char* smem) {
;     ...
;     const int xcd = job & 7, q = job >> 3;
;     const int mt = (q >> 3) * 8 + xcd, nt = q & 7;
;     GJob J;
;     J.rs_k = 0; J.scale = 1.f; J.ld = 1024; J.headbase = 0; J.sshift = 13; J.dst = nullptr;
;     J.A = p->mixedg + (size_t)mt * 128 * 1024; J.lda = 1024; J.K = 1024; J.m0 = mt * 128;
;     J.Bt = p->WoutT + ((size_t)l * 1024 + nt * 128) * 1024; J.ldb = 1024;
.LBB0_645:
	s_ashr_i32 s10, s25, 3
	s_and_b32 s2, s25, 7
	s_and_b32 s10, s10, -8
	s_or_b32 s10, s10, s2
	s_ashr_i32 s11, s10, 31
	s_lshl_b64 s[12:13], s[10:11], 18
	s_waitcnt lgkmcnt(0)
	s_add_u32 s12, s6, s12
	s_addc_u32 s13, s7, s13
	s_lshl_b32 s2, s25, 4
	v_mov_b32_e32 v84, v188
	v_mov_b32_e32 v34, v188
	s_and_b32 s39, s2, 0x380
	s_lshl_b32 s2, s39, 11
	s_waitcnt vmcnt(7)
	v_ashrrev_i32_e32 v2, 3, v34
	v_lshlrev_b32_e32 v0, 3, v34
	v_ashrrev_i32_e32 v3, 31, v2
	s_or_b32 s2, s2, s24
	v_and_b32_e32 v35, 56, v0
	v_lshlrev_b64 v[4:5], 11, v[2:3]
	s_add_u32 s18, s8, s2
	s_waitcnt vmcnt(6)
	v_lshl_add_u64 v[6:7], s[12:13], 0, v[4:5]
	v_lshrrev_b32_e32 v20, 4, v34
	v_and_b32_e32 v21, 7, v34
	v_and_b32_e32 v20, 7, v20
	v_xor_b32_e32 v20, v20, v21
	v_lshlrev_b32_e32 v0, 4, v20
	s_addc_u32 s19, s9, 0
	v_lshl_add_u64 v[68:69], v[6:7], 0, v[0:1]
	v_lshl_add_u64 v[4:5], s[18:19], 0, v[4:5]
	v_add_co_u32_e32 v72, vcc, s50, v68
	v_lshl_add_u64 v[70:71], v[4:5], 0, v[0:1]
	s_nop 0
	v_addc_co_u32_e32 v73, vcc, 0, v69, vcc
	v_add_co_u32_e32 v74, vcc, s50, v70
	v_mul_lo_u32 v0, v2, s33
	s_nop 0
	v_addc_co_u32_e32 v75, vcc, 0, v71, vcc
	v_add_co_u32_e32 v76, vcc, s51, v68
	s_nop 0
	s_nop 0
	v_addc_co_u32_e32 v77, vcc, 0, v69, vcc
	v_add_co_u32_e32 v78, vcc, s51, v70
	s_nop 0
	s_nop 0
	v_addc_co_u32_e32 v79, vcc, 0, v71, vcc
	v_add_co_u32_e32 v80, vcc, s52, v68
	s_nop 0
	s_nop 0
	v_addc_co_u32_e32 v81, vcc, 0, v69, vcc
	v_add_co_u32_e32 v82, vcc, s52, v70
	s_nop 0
	s_nop 0
	v_addc_co_u32_e32 v83, vcc, 0, v71, vcc
	s_nop 0
	s_nop 0
	s_nop 0
	s_nop 0
	v_add_lshl_u32 v85, v0, v35, 1
	v_and_b32_e32 v0, 31, v34
	s_mov_b32 s38, 0
	v_add_u32_e32 v86, 0x9000, v85
	v_lshrrev_b32_e32 v2, 1, v34
	v_and_or_b32 v3, v2, s53, v0
	v_and_b32_e32 v0, 16, v2
	v_and_b32_e32 v2, 0x5f, v34
	v_mad_u64_u32 v[66:67], s[12:13], v3, s54, v[0:1]
	v_mad_u32_u24 v0, v2, s54, v0
	v_lshrrev_b32_e32 v20, 6, v34
	v_and_b32_e32 v21, 31, v34
	v_readfirstlane_b32 s100, v20
	v_lshrrev_b32_e32 v22, 7, v34
	v_bfe_u32 v23, v34, 6, 1
	s_lshl_b32 s100, s100, 10
	v_lshl_or_b32 v22, v22, 6, v21
	v_lshl_or_b32 v23, v23, 6, v21
	s_add_u32 m0, s100, 2048
	s_nop 0
	global_load_lds_dwordx4 v[68:69], off
	s_add_u32 m0, s100, 18432
	s_nop 0
	global_load_lds_dwordx4 v[70:71], off
	s_add_u32 m0, s100, 6144
	s_nop 0
	global_load_lds_dwordx4 v[72:73], off
	s_add_u32 m0, s100, 22528
	s_nop 0
	global_load_lds_dwordx4 v[74:75], off
	s_add_u32 m0, s100, 10240
	s_nop 0
	global_load_lds_dwordx4 v[76:77], off
	s_add_u32 m0, s100, 26624
	s_nop 0
	global_load_lds_dwordx4 v[78:79], off
	s_add_u32 m0, s100, 14336
	s_nop 0
	global_load_lds_dwordx4 v[80:81], off
	s_add_u32 m0, s100, 30720
	s_nop 0
	global_load_lds_dwordx4 v[82:83], off
	v_lshrrev_b32_e32 v24, 5, v34
	v_lshrrev_b32_e32 v25, 1, v34
	v_xor_b32_e32 v24, v24, v25
	v_and_b32_e32 v24, 1, v24
	v_bfe_u32 v25, v34, 2, 2
	v_lshlrev_b32_e32 v22, 7, v22
	v_lshlrev_b32_e32 v23, 7, v23
	v_lshl_add_u32 v22, v24, 4, v22
	v_lshl_add_u32 v23, v24, 4, v23
	v_add_u32_e32 v22, 2048, v22
	v_add_u32_e32 v23, 18432, v23
	v_lshl_add_u32 v204, v25, 5, v22
	v_lshl_add_u32 v208, v25, 5, v23
	v_xor_b32_e32 v26, 1, v25
	v_lshl_add_u32 v205, v26, 5, v22
	v_lshl_add_u32 v209, v26, 5, v23
	v_xor_b32_e32 v26, 2, v25
	v_lshl_add_u32 v206, v26, 5, v22
	v_lshl_add_u32 v210, v26, 5, v23
	v_xor_b32_e32 v26, 3, v25
	v_lshl_add_u32 v207, v26, 5, v22
	v_lshl_add_u32 v211, v26, 5, v23
	s_waitcnt vmcnt(0)
	s_waitcnt lgkmcnt(0)
	s_barrier
	ds_read_b128 v[120:123], v204
	ds_read_b128 v[128:131], v208
	ds_read_b128 v[132:135], v208 offset:4096
	ds_read_b128 v[124:127], v204 offset:4096
	ds_read_b128 v[136:139], v205
	ds_read_b128 v[184:187], v209
	ds_read_b128 v[200:203], v209 offset:4096
	ds_read_b128 v[140:143], v205 offset:4096
	s_setprio 1
	s_waitcnt lgkmcnt(4)
	s_add_u32 m0, s100, 34688
	v_mfma_f32_32x32x16_bf16 v[50:65], v[128:131], v[120:123], 0
	global_load_lds_dwordx4 v[68:69], off offset:128
	s_add_u32 m0, s100, 51072
	v_mfma_f32_32x32x16_bf16 v[34:49], v[132:135], v[120:123], 0
	global_load_lds_dwordx4 v[70:71], off offset:128
	s_add_u32 m0, s100, 38784
	v_mfma_f32_32x32x16_bf16 v[18:33], v[132:135], v[124:127], 0
	global_load_lds_dwordx4 v[72:73], off offset:128
	s_add_u32 m0, s100, 55168
	v_mfma_f32_32x32x16_bf16 v[2:17], v[128:131], v[124:127], 0
	global_load_lds_dwordx4 v[74:75], off offset:128
	ds_read_b128 v[120:123], v206
	ds_read_b128 v[128:131], v210
	ds_read_b128 v[132:135], v210 offset:4096
	ds_read_b128 v[124:127], v206 offset:4096
	s_waitcnt lgkmcnt(4)
	s_add_u32 m0, s100, 42880
	v_mfma_f32_32x32x16_bf16 v[50:65], v[184:187], v[136:139], v[50:65]
	global_load_lds_dwordx4 v[76:77], off offset:128
	s_add_u32 m0, s100, 59264
	v_mfma_f32_32x32x16_bf16 v[34:49], v[200:203], v[136:139], v[34:49]
	global_load_lds_dwordx4 v[78:79], off offset:128
	s_add_u32 m0, s100, 46976
	v_mfma_f32_32x32x16_bf16 v[18:33], v[200:203], v[140:143], v[18:33]
	global_load_lds_dwordx4 v[80:81], off offset:128
	s_add_u32 m0, s100, 63360
	v_mfma_f32_32x32x16_bf16 v[2:17], v[184:187], v[140:143], v[2:17]
	global_load_lds_dwordx4 v[82:83], off offset:128
	ds_read_b128 v[136:139], v207
	ds_read_b128 v[184:187], v211
	ds_read_b128 v[200:203], v211 offset:4096
	ds_read_b128 v[140:143], v207 offset:4096
	s_waitcnt lgkmcnt(4)
	v_mfma_f32_32x32x16_bf16 v[50:65], v[128:131], v[120:123], v[50:65]
	v_mfma_f32_32x32x16_bf16 v[34:49], v[132:135], v[120:123], v[34:49]
	v_mfma_f32_32x32x16_bf16 v[18:33], v[132:135], v[124:127], v[18:33]
	v_mfma_f32_32x32x16_bf16 v[2:17], v[128:131], v[124:127], v[2:17]
	s_waitcnt lgkmcnt(0)
	v_mfma_f32_32x32x16_bf16 v[50:65], v[184:187], v[136:139], v[50:65]
	v_mfma_f32_32x32x16_bf16 v[34:49], v[200:203], v[136:139], v[34:49]
	v_mfma_f32_32x32x16_bf16 v[18:33], v[200:203], v[140:143], v[18:33]
	v_mfma_f32_32x32x16_bf16 v[2:17], v[184:187], v[140:143], v[2:17]
	s_setprio 0
	s_waitcnt vmcnt(0)
	s_barrier
; #define MFMA(a, b, c) __builtin_amdgcn_mfma_f32_32x32x16_bf16((a), (b), (c), 0, 0, 0)
; template <bool SWAP>
; DI void gemm_block(const bf16_t* __restrict__ A, int lda, const bf16_t* __restrict__ Bt, int ldb, int K, f32x16 (&acc)[2][2], bf16_t* sA, bf16_t* sB) {
;     ...
;   for (int kt = 0; kt < nk; ++kt) {
;     const int cur = kt & 1;
;     const bool more = kt + 1 < nk;
;     if (more) {
;       const int k0 = (kt + 1) * 64;
; #pragma unroll
;       for (int i = 0; i < 4; ++i) { ra[i] = *(const u32x4*)(ga + (size_t)i * 32 * lda + k0); rb[i] = *(const u32x4*)(gb + (size_t)i * 32 * ldb + k0); }
;     }
;     const bf16_t* ab = sA + cur * 128 * LDT + (64 * wr + l32) * LDT + h * 8;
;     const bf16_t* bb = sB + cur * 128 * LDT + (64 * wc + l32) * LDT + h * 8;
;     __builtin_amdgcn_s_setprio(1);
;     __builtin_amdgcn_iglp_opt(0);
; #pragma unroll
;     for (int ks = 0; ks < 4; ++ks) {
;       const bf16x8 a0 = *(const bf16x8*)(ab + ks * 16), a1 = *(const bf16x8*)(ab + 32 * LDT + ks * 16);
;       const bf16x8 b0 = *(const bf16x8*)(bb + ks * 16), b1 = *(const bf16x8*)(bb + 32 * LDT + ks * 16);
;       if (!SWAP) {
;         acc[0][0] = MFMA(a0, b0, acc[0][0]); acc[0][1] = MFMA(a0, b1, acc[0][1]);
;         acc[1][0] = MFMA(a1, b0, acc[1][0]); acc[1][1] = MFMA(a1, b1, acc[1][1]);
;       } else {
;         acc[0][0] = MFMA(b0, a0, acc[0][0]); acc[0][1] = MFMA(b1, a0, acc[0][1]);
;         acc[1][0] = MFMA(b0, a1, acc[1][0]); acc[1][1] = MFMA(b1, a1, acc[1][1]);
;       }
;     }
;     __builtin_amdgcn_s_setprio(0);
;     if (more) {
;       const int nb = (cur ^ 1) * 128 * LDT;
; #pragma unroll
;       for (int i = 0; i < 4; ++i) { *(u32x4*)(sA + nb + soff + i * 32 * LDT) = ra[i]; *(u32x4*)(sB + nb + soff + i * 32 * LDT) = rb[i]; }
;     }
;     __syncthreads();
;   }
	ds_read_b128 v[120:123], v204 offset:32768
	ds_read_b128 v[128:131], v208 offset:32768
	ds_read_b128 v[132:135], v208 offset:36864
	ds_read_b128 v[124:127], v204 offset:36864
	ds_read_b128 v[136:139], v205 offset:32768
	ds_read_b128 v[184:187], v209 offset:32768
	ds_read_b128 v[200:203], v209 offset:36864
	ds_read_b128 v[140:143], v205 offset:36864
	s_setprio 1
	s_waitcnt lgkmcnt(4)
	s_add_u32 m0, s100, 1792
	v_mfma_f32_32x32x16_bf16 v[50:65], v[128:131], v[120:123], v[50:65]
	global_load_lds_dwordx4 v[68:69], off offset:256
	s_add_u32 m0, s100, 18176
	v_mfma_f32_32x32x16_bf16 v[34:49], v[132:135], v[120:123], v[34:49]
	global_load_lds_dwordx4 v[70:71], off offset:256
	s_add_u32 m0, s100, 5888
	v_mfma_f32_32x32x16_bf16 v[18:33], v[132:135], v[124:127], v[18:33]
	global_load_lds_dwordx4 v[72:73], off offset:256
	s_add_u32 m0, s100, 22272
	v_mfma_f32_32x32x16_bf16 v[2:17], v[128:131], v[124:127], v[2:17]
	global_load_lds_dwordx4 v[74:75], off offset:256
	ds_read_b128 v[120:123], v206 offset:32768
	ds_read_b128 v[128:131], v210 offset:32768
	ds_read_b128 v[132:135], v210 offset:36864
	ds_read_b128 v[124:127], v206 offset:36864
	s_waitcnt lgkmcnt(4)
	s_add_u32 m0, s100, 9984
	v_mfma_f32_32x32x16_bf16 v[50:65], v[184:187], v[136:139], v[50:65]
	global_load_lds_dwordx4 v[76:77], off offset:256
	s_add_u32 m0, s100, 26368
	v_mfma_f32_32x32x16_bf16 v[34:49], v[200:203], v[136:139], v[34:49]
	global_load_lds_dwordx4 v[78:79], off offset:256
	s_add_u32 m0, s100, 14080
	v_mfma_f32_32x32x16_bf16 v[18:33], v[200:203], v[140:143], v[18:33]
	global_load_lds_dwordx4 v[80:81], off offset:256
	s_add_u32 m0, s100, 30464
	v_mfma_f32_32x32x16_bf16 v[2:17], v[184:187], v[140:143], v[2:17]
	global_load_lds_dwordx4 v[82:83], off offset:256
	ds_read_b128 v[136:139], v207 offset:32768
	ds_read_b128 v[184:187], v211 offset:32768
	ds_read_b128 v[200:203], v211 offset:36864
	ds_read_b128 v[140:143], v207 offset:36864
	s_waitcnt lgkmcnt(4)
	v_mfma_f32_32x32x16_bf16 v[50:65], v[128:131], v[120:123], v[50:65]
	v_mfma_f32_32x32x16_bf16 v[34:49], v[132:135], v[120:123], v[34:49]
	v_mfma_f32_32x32x16_bf16 v[18:33], v[132:135], v[124:127], v[18:33]
	v_mfma_f32_32x32x16_bf16 v[2:17], v[128:131], v[124:127], v[2:17]
	s_waitcnt lgkmcnt(0)
	v_mfma_f32_32x32x16_bf16 v[50:65], v[184:187], v[136:139], v[50:65]
	v_mfma_f32_32x32x16_bf16 v[34:49], v[200:203], v[136:139], v[34:49]
	v_mfma_f32_32x32x16_bf16 v[18:33], v[200:203], v[140:143], v[18:33]
	v_mfma_f32_32x32x16_bf16 v[2:17], v[184:187], v[140:143], v[2:17]
	s_setprio 0
	s_waitcnt vmcnt(0)
	s_barrier
	ds_read_b128 v[120:123], v204
	ds_read_b128 v[128:131], v208
	ds_read_b128 v[132:135], v208 offset:4096
	ds_read_b128 v[124:127], v204 offset:4096
	ds_read_b128 v[136:139], v205
	ds_read_b128 v[184:187], v209
	ds_read_b128 v[200:203], v209 offset:4096
	ds_read_b128 v[140:143], v205 offset:4096
	s_setprio 1
	s_waitcnt lgkmcnt(4)
	s_add_u32 m0, s100, 34432
	v_mfma_f32_32x32x16_bf16 v[50:65], v[128:131], v[120:123], v[50:65]
	global_load_lds_dwordx4 v[68:69], off offset:384
	s_add_u32 m0, s100, 50816
	v_mfma_f32_32x32x16_bf16 v[34:49], v[132:135], v[120:123], v[34:49]
	global_load_lds_dwordx4 v[70:71], off offset:384
	s_add_u32 m0, s100, 38528
	v_mfma_f32_32x32x16_bf16 v[18:33], v[132:135], v[124:127], v[18:33]
	global_load_lds_dwordx4 v[72:73], off offset:384
	s_add_u32 m0, s100, 54912
	v_mfma_f32_32x32x16_bf16 v[2:17], v[128:131], v[124:127], v[2:17]
	global_load_lds_dwordx4 v[74:75], off offset:384
	ds_read_b128 v[120:123], v206
	ds_read_b128 v[128:131], v210
	ds_read_b128 v[132:135], v210 offset:4096
	ds_read_b128 v[124:127], v206 offset:4096
	s_waitcnt lgkmcnt(4)
	s_add_u32 m0, s100, 42624
	v_mfma_f32_32x32x16_bf16 v[50:65], v[184:187], v[136:139], v[50:65]
	global_load_lds_dwordx4 v[76:77], off offset:384
	s_add_u32 m0, s100, 59008
	v_mfma_f32_32x32x16_bf16 v[34:49], v[200:203], v[136:139], v[34:49]
	global_load_lds_dwordx4 v[78:79], off offset:384
	s_add_u32 m0, s100, 46720
	v_mfma_f32_32x32x16_bf16 v[18:33], v[200:203], v[140:143], v[18:33]
	global_load_lds_dwordx4 v[80:81], off offset:384
	s_add_u32 m0, s100, 63104
	v_mfma_f32_32x32x16_bf16 v[2:17], v[184:187], v[140:143], v[2:17]
	global_load_lds_dwordx4 v[82:83], off offset:384
	ds_read_b128 v[136:139], v207
	ds_read_b128 v[184:187], v211
	ds_read_b128 v[200:203], v211 offset:4096
	ds_read_b128 v[140:143], v207 offset:4096
	s_waitcnt lgkmcnt(4)
	v_mfma_f32_32x32x16_bf16 v[50:65], v[128:131], v[120:123], v[50:65]
	v_mfma_f32_32x32x16_bf16 v[34:49], v[132:135], v[120:123], v[34:49]
	v_mfma_f32_32x32x16_bf16 v[18:33], v[132:135], v[124:127], v[18:33]
	v_mfma_f32_32x32x16_bf16 v[2:17], v[128:131], v[124:127], v[2:17]
	s_waitcnt lgkmcnt(0)
	v_mfma_f32_32x32x16_bf16 v[50:65], v[184:187], v[136:139], v[50:65]
	v_mfma_f32_32x32x16_bf16 v[34:49], v[200:203], v[136:139], v[34:49]
	v_mfma_f32_32x32x16_bf16 v[18:33], v[200:203], v[140:143], v[18:33]
	v_mfma_f32_32x32x16_bf16 v[2:17], v[184:187], v[140:143], v[2:17]
	s_setprio 0
	s_waitcnt vmcnt(0)
	s_barrier
; #define MFMA(a, b, c) __builtin_amdgcn_mfma_f32_32x32x16_bf16((a), (b), (c), 0, 0, 0)
; template <bool SWAP>
; DI void gemm_block(const bf16_t* __restrict__ A, int lda, const bf16_t* __restrict__ Bt, int ldb, int K, f32x16 (&acc)[2][2], bf16_t* sA, bf16_t* sB) {
;     ...
;   for (int kt = 0; kt < nk; ++kt) {
;     const int cur = kt & 1;
;     const bool more = kt + 1 < nk;
;     if (more) {
;       const int k0 = (kt + 1) * 64;
; #pragma unroll
;       for (int i = 0; i < 4; ++i) { ra[i] = *(const u32x4*)(ga + (size_t)i * 32 * lda + k0); rb[i] = *(const u32x4*)(gb + (size_t)i * 32 * ldb + k0); }
;     }
;     const bf16_t* ab = sA + cur * 128 * LDT + (64 * wr + l32) * LDT + h * 8;
;     const bf16_t* bb = sB + cur * 128 * LDT + (64 * wc + l32) * LDT + h * 8;
;     __builtin_amdgcn_s_setprio(1);
;     __builtin_amdgcn_iglp_opt(0);
; #pragma unroll
;     for (int ks = 0; ks < 4; ++ks) {
;       const bf16x8 a0 = *(const bf16x8*)(ab + ks * 16), a1 = *(const bf16x8*)(ab + 32 * LDT + ks * 16);
;       const bf16x8 b0 = *(const bf16x8*)(bb + ks * 16), b1 = *(const bf16x8*)(bb + 32 * LDT + ks * 16);
;       if (!SWAP) {
;         acc[0][0] = MFMA(a0, b0, acc[0][0]); acc[0][1] = MFMA(a0, b1, acc[0][1]);
;         acc[1][0] = MFMA(a1, b0, acc[1][0]); acc[1][1] = MFMA(a1, b1, acc[1][1]);
;       } else {
;         acc[0][0] = MFMA(b0, a0, acc[0][0]); acc[0][1] = MFMA(b1, a0, acc[0][1]);
;         acc[1][0] = MFMA(b0, a1, acc[1][0]); acc[1][1] = MFMA(b1, a1, acc[1][1]);
;       }
;     }
;     __builtin_amdgcn_s_setprio(0);
;     if (more) {
;       const int nb = (cur ^ 1) * 128 * LDT;
; #pragma unroll
;       for (int i = 0; i < 4; ++i) { *(u32x4*)(sA + nb + soff + i * 32 * LDT) = ra[i]; *(u32x4*)(sB + nb + soff + i * 32 * LDT) = rb[i]; }
;     }
;     __syncthreads();
;   }
	ds_read_b128 v[120:123], v204 offset:32768
	ds_read_b128 v[128:131], v208 offset:32768
	ds_read_b128 v[132:135], v208 offset:36864
	ds_read_b128 v[124:127], v204 offset:36864
	ds_read_b128 v[136:139], v205 offset:32768
	ds_read_b128 v[184:187], v209 offset:32768
	ds_read_b128 v[200:203], v209 offset:36864
	ds_read_b128 v[140:143], v205 offset:36864
	s_setprio 1
	s_waitcnt lgkmcnt(4)
	s_add_u32 m0, s100, 1536
	v_mfma_f32_32x32x16_bf16 v[50:65], v[128:131], v[120:123], v[50:65]
	global_load_lds_dwordx4 v[68:69], off offset:512
	s_add_u32 m0, s100, 17920
	v_mfma_f32_32x32x16_bf16 v[34:49], v[132:135], v[120:123], v[34:49]
	global_load_lds_dwordx4 v[70:71], off offset:512
	s_add_u32 m0, s100, 5632
	v_mfma_f32_32x32x16_bf16 v[18:33], v[132:135], v[124:127], v[18:33]
	global_load_lds_dwordx4 v[72:73], off offset:512
	s_add_u32 m0, s100, 22016
	v_mfma_f32_32x32x16_bf16 v[2:17], v[128:131], v[124:127], v[2:17]
	global_load_lds_dwordx4 v[74:75], off offset:512
	ds_read_b128 v[120:123], v206 offset:32768
	ds_read_b128 v[128:131], v210 offset:32768
	ds_read_b128 v[132:135], v210 offset:36864
	ds_read_b128 v[124:127], v206 offset:36864
	s_waitcnt lgkmcnt(4)
	s_add_u32 m0, s100, 9728
	v_mfma_f32_32x32x16_bf16 v[50:65], v[184:187], v[136:139], v[50:65]
	global_load_lds_dwordx4 v[76:77], off offset:512
	s_add_u32 m0, s100, 26112
	v_mfma_f32_32x32x16_bf16 v[34:49], v[200:203], v[136:139], v[34:49]
	global_load_lds_dwordx4 v[78:79], off offset:512
	s_add_u32 m0, s100, 13824
	v_mfma_f32_32x32x16_bf16 v[18:33], v[200:203], v[140:143], v[18:33]
	global_load_lds_dwordx4 v[80:81], off offset:512
	s_add_u32 m0, s100, 30208
	v_mfma_f32_32x32x16_bf16 v[2:17], v[184:187], v[140:143], v[2:17]
	global_load_lds_dwordx4 v[82:83], off offset:512
	ds_read_b128 v[136:139], v207 offset:32768
	ds_read_b128 v[184:187], v211 offset:32768
	ds_read_b128 v[200:203], v211 offset:36864
	ds_read_b128 v[140:143], v207 offset:36864
	s_waitcnt lgkmcnt(4)
	v_mfma_f32_32x32x16_bf16 v[50:65], v[128:131], v[120:123], v[50:65]
	v_mfma_f32_32x32x16_bf16 v[34:49], v[132:135], v[120:123], v[34:49]
	v_mfma_f32_32x32x16_bf16 v[18:33], v[132:135], v[124:127], v[18:33]
	v_mfma_f32_32x32x16_bf16 v[2:17], v[128:131], v[124:127], v[2:17]
	s_waitcnt lgkmcnt(0)
	v_mfma_f32_32x32x16_bf16 v[50:65], v[184:187], v[136:139], v[50:65]
	v_mfma_f32_32x32x16_bf16 v[34:49], v[200:203], v[136:139], v[34:49]
	v_mfma_f32_32x32x16_bf16 v[18:33], v[200:203], v[140:143], v[18:33]
	v_mfma_f32_32x32x16_bf16 v[2:17], v[184:187], v[140:143], v[2:17]
	s_setprio 0
	s_waitcnt vmcnt(0)
	s_barrier
	ds_read_b128 v[120:123], v204
	ds_read_b128 v[128:131], v208
	ds_read_b128 v[132:135], v208 offset:4096
	ds_read_b128 v[124:127], v204 offset:4096
	ds_read_b128 v[136:139], v205
	ds_read_b128 v[184:187], v209
	ds_read_b128 v[200:203], v209 offset:4096
	ds_read_b128 v[140:143], v205 offset:4096
	s_setprio 1
	s_waitcnt lgkmcnt(4)
	s_add_u32 m0, s100, 34176
	v_mfma_f32_32x32x16_bf16 v[50:65], v[128:131], v[120:123], v[50:65]
	global_load_lds_dwordx4 v[68:69], off offset:640
	s_add_u32 m0, s100, 50560
	v_mfma_f32_32x32x16_bf16 v[34:49], v[132:135], v[120:123], v[34:49]
	global_load_lds_dwordx4 v[70:71], off offset:640
	s_add_u32 m0, s100, 38272
	v_mfma_f32_32x32x16_bf16 v[18:33], v[132:135], v[124:127], v[18:33]
	global_load_lds_dwordx4 v[72:73], off offset:640
	s_add_u32 m0, s100, 54656
	v_mfma_f32_32x32x16_bf16 v[2:17], v[128:131], v[124:127], v[2:17]
	global_load_lds_dwordx4 v[74:75], off offset:640
	ds_read_b128 v[120:123], v206
	ds_read_b128 v[128:131], v210
	ds_read_b128 v[132:135], v210 offset:4096
	ds_read_b128 v[124:127], v206 offset:4096
	s_waitcnt lgkmcnt(4)
	s_add_u32 m0, s100, 42368
	v_mfma_f32_32x32x16_bf16 v[50:65], v[184:187], v[136:139], v[50:65]
	global_load_lds_dwordx4 v[76:77], off offset:640
	s_add_u32 m0, s100, 58752
	v_mfma_f32_32x32x16_bf16 v[34:49], v[200:203], v[136:139], v[34:49]
	global_load_lds_dwordx4 v[78:79], off offset:640
	s_add_u32 m0, s100, 46464
	v_mfma_f32_32x32x16_bf16 v[18:33], v[200:203], v[140:143], v[18:33]
	global_load_lds_dwordx4 v[80:81], off offset:640
	s_add_u32 m0, s100, 62848
	v_mfma_f32_32x32x16_bf16 v[2:17], v[184:187], v[140:143], v[2:17]
	global_load_lds_dwordx4 v[82:83], off offset:640
	ds_read_b128 v[136:139], v207
	ds_read_b128 v[184:187], v211
	ds_read_b128 v[200:203], v211 offset:4096
	ds_read_b128 v[140:143], v207 offset:4096
	s_waitcnt lgkmcnt(4)
	v_mfma_f32_32x32x16_bf16 v[50:65], v[128:131], v[120:123], v[50:65]
	v_mfma_f32_32x32x16_bf16 v[34:49], v[132:135], v[120:123], v[34:49]
	v_mfma_f32_32x32x16_bf16 v[18:33], v[132:135], v[124:127], v[18:33]
	v_mfma_f32_32x32x16_bf16 v[2:17], v[128:131], v[124:127], v[2:17]
	s_waitcnt lgkmcnt(0)
	v_mfma_f32_32x32x16_bf16 v[50:65], v[184:187], v[136:139], v[50:65]
	v_mfma_f32_32x32x16_bf16 v[34:49], v[200:203], v[136:139], v[34:49]
	v_mfma_f32_32x32x16_bf16 v[18:33], v[200:203], v[140:143], v[18:33]
	v_mfma_f32_32x32x16_bf16 v[2:17], v[184:187], v[140:143], v[2:17]
	s_setprio 0
	s_waitcnt vmcnt(0)
	s_barrier
; #define MFMA(a, b, c) __builtin_amdgcn_mfma_f32_32x32x16_bf16((a), (b), (c), 0, 0, 0)
; template <bool SWAP>
; DI void gemm_block(const bf16_t* __restrict__ A, int lda, const bf16_t* __restrict__ Bt, int ldb, int K, f32x16 (&acc)[2][2], bf16_t* sA, bf16_t* sB) {
;     ...
;   for (int kt = 0; kt < nk; ++kt) {
;     const int cur = kt & 1;
;     const bool more = kt + 1 < nk;
;     if (more) {
;       const int k0 = (kt + 1) * 64;
; #pragma unroll
;       for (int i = 0; i < 4; ++i) { ra[i] = *(const u32x4*)(ga + (size_t)i * 32 * lda + k0); rb[i] = *(const u32x4*)(gb + (size_t)i * 32 * ldb + k0); }
;     }
;     const bf16_t* ab = sA + cur * 128 * LDT + (64 * wr + l32) * LDT + h * 8;
;     const bf16_t* bb = sB + cur * 128 * LDT + (64 * wc + l32) * LDT + h * 8;
;     __builtin_amdgcn_s_setprio(1);
;     __builtin_amdgcn_iglp_opt(0);
; #pragma unroll
;     for (int ks = 0; ks < 4; ++ks) {
;       const bf16x8 a0 = *(const bf16x8*)(ab + ks * 16), a1 = *(const bf16x8*)(ab + 32 * LDT + ks * 16);
;       const bf16x8 b0 = *(const bf16x8*)(bb + ks * 16), b1 = *(const bf16x8*)(bb + 32 * LDT + ks * 16);
;       if (!SWAP) {
;         acc[0][0] = MFMA(a0, b0, acc[0][0]); acc[0][1] = MFMA(a0, b1, acc[0][1]);
;         acc[1][0] = MFMA(a1, b0, acc[1][0]); acc[1][1] = MFMA(a1, b1, acc[1][1]);
;       } else {
;         acc[0][0] = MFMA(b0, a0, acc[0][0]); acc[0][1] = MFMA(b1, a0, acc[0][1]);
;         acc[1][0] = MFMA(b0, a1, acc[1][0]); acc[1][1] = MFMA(b1, a1, acc[1][1]);
;       }
;     }
;     __builtin_amdgcn_s_setprio(0);
;     if (more) {
;       const int nb = (cur ^ 1) * 128 * LDT;
; #pragma unroll
;       for (int i = 0; i < 4; ++i) { *(u32x4*)(sA + nb + soff + i * 32 * LDT) = ra[i]; *(u32x4*)(sB + nb + soff + i * 32 * LDT) = rb[i]; }
;     }
;     __syncthreads();
;   }
	ds_read_b128 v[120:123], v204 offset:32768
	ds_read_b128 v[128:131], v208 offset:32768
	ds_read_b128 v[132:135], v208 offset:36864
	ds_read_b128 v[124:127], v204 offset:36864
	ds_read_b128 v[136:139], v205 offset:32768
	ds_read_b128 v[184:187], v209 offset:32768
	ds_read_b128 v[200:203], v209 offset:36864
	ds_read_b128 v[140:143], v205 offset:36864
	s_setprio 1
	s_waitcnt lgkmcnt(4)
	s_add_u32 m0, s100, 1280
	v_mfma_f32_32x32x16_bf16 v[50:65], v[128:131], v[120:123], v[50:65]
	global_load_lds_dwordx4 v[68:69], off offset:768
	s_add_u32 m0, s100, 17664
	v_mfma_f32_32x32x16_bf16 v[34:49], v[132:135], v[120:123], v[34:49]
	global_load_lds_dwordx4 v[70:71], off offset:768
	s_add_u32 m0, s100, 5376
	v_mfma_f32_32x32x16_bf16 v[18:33], v[132:135], v[124:127], v[18:33]
	global_load_lds_dwordx4 v[72:73], off offset:768
	s_add_u32 m0, s100, 21760
	v_mfma_f32_32x32x16_bf16 v[2:17], v[128:131], v[124:127], v[2:17]
	global_load_lds_dwordx4 v[74:75], off offset:768
	ds_read_b128 v[120:123], v206 offset:32768
	ds_read_b128 v[128:131], v210 offset:32768
	ds_read_b128 v[132:135], v210 offset:36864
	ds_read_b128 v[124:127], v206 offset:36864
	s_waitcnt lgkmcnt(4)
	s_add_u32 m0, s100, 9472
	v_mfma_f32_32x32x16_bf16 v[50:65], v[184:187], v[136:139], v[50:65]
	global_load_lds_dwordx4 v[76:77], off offset:768
	s_add_u32 m0, s100, 25856
	v_mfma_f32_32x32x16_bf16 v[34:49], v[200:203], v[136:139], v[34:49]
	global_load_lds_dwordx4 v[78:79], off offset:768
	s_add_u32 m0, s100, 13568
	v_mfma_f32_32x32x16_bf16 v[18:33], v[200:203], v[140:143], v[18:33]
	global_load_lds_dwordx4 v[80:81], off offset:768
	s_add_u32 m0, s100, 29952
	v_mfma_f32_32x32x16_bf16 v[2:17], v[184:187], v[140:143], v[2:17]
	global_load_lds_dwordx4 v[82:83], off offset:768
	ds_read_b128 v[136:139], v207 offset:32768
	ds_read_b128 v[184:187], v211 offset:32768
	ds_read_b128 v[200:203], v211 offset:36864
	ds_read_b128 v[140:143], v207 offset:36864
	s_waitcnt lgkmcnt(4)
	v_mfma_f32_32x32x16_bf16 v[50:65], v[128:131], v[120:123], v[50:65]
	v_mfma_f32_32x32x16_bf16 v[34:49], v[132:135], v[120:123], v[34:49]
	v_mfma_f32_32x32x16_bf16 v[18:33], v[132:135], v[124:127], v[18:33]
	v_mfma_f32_32x32x16_bf16 v[2:17], v[128:131], v[124:127], v[2:17]
	s_waitcnt lgkmcnt(0)
	v_mfma_f32_32x32x16_bf16 v[50:65], v[184:187], v[136:139], v[50:65]
	v_mfma_f32_32x32x16_bf16 v[34:49], v[200:203], v[136:139], v[34:49]
	v_mfma_f32_32x32x16_bf16 v[18:33], v[200:203], v[140:143], v[18:33]
	v_mfma_f32_32x32x16_bf16 v[2:17], v[184:187], v[140:143], v[2:17]
	s_setprio 0
	s_waitcnt vmcnt(0)
	s_barrier
	ds_read_b128 v[120:123], v204
	ds_read_b128 v[128:131], v208
	ds_read_b128 v[132:135], v208 offset:4096
	ds_read_b128 v[124:127], v204 offset:4096
	ds_read_b128 v[136:139], v205
	ds_read_b128 v[184:187], v209
	ds_read_b128 v[200:203], v209 offset:4096
	ds_read_b128 v[140:143], v205 offset:4096
	s_setprio 1
	s_waitcnt lgkmcnt(4)
	s_add_u32 m0, s100, 33920
	v_mfma_f32_32x32x16_bf16 v[50:65], v[128:131], v[120:123], v[50:65]
	global_load_lds_dwordx4 v[68:69], off offset:896
	s_add_u32 m0, s100, 50304
	v_mfma_f32_32x32x16_bf16 v[34:49], v[132:135], v[120:123], v[34:49]
	global_load_lds_dwordx4 v[70:71], off offset:896
	s_add_u32 m0, s100, 38016
	v_mfma_f32_32x32x16_bf16 v[18:33], v[132:135], v[124:127], v[18:33]
	global_load_lds_dwordx4 v[72:73], off offset:896
	s_add_u32 m0, s100, 54400
	v_mfma_f32_32x32x16_bf16 v[2:17], v[128:131], v[124:127], v[2:17]
	global_load_lds_dwordx4 v[74:75], off offset:896
	ds_read_b128 v[120:123], v206
	ds_read_b128 v[128:131], v210
	ds_read_b128 v[132:135], v210 offset:4096
	ds_read_b128 v[124:127], v206 offset:4096
	s_waitcnt lgkmcnt(4)
	s_add_u32 m0, s100, 42112
	v_mfma_f32_32x32x16_bf16 v[50:65], v[184:187], v[136:139], v[50:65]
	global_load_lds_dwordx4 v[76:77], off offset:896
	s_add_u32 m0, s100, 58496
	v_mfma_f32_32x32x16_bf16 v[34:49], v[200:203], v[136:139], v[34:49]
	global_load_lds_dwordx4 v[78:79], off offset:896
	s_add_u32 m0, s100, 46208
	v_mfma_f32_32x32x16_bf16 v[18:33], v[200:203], v[140:143], v[18:33]
	global_load_lds_dwordx4 v[80:81], off offset:896
	s_add_u32 m0, s100, 62592
	v_mfma_f32_32x32x16_bf16 v[2:17], v[184:187], v[140:143], v[2:17]
	global_load_lds_dwordx4 v[82:83], off offset:896
	ds_read_b128 v[136:139], v207
	ds_read_b128 v[184:187], v211
	ds_read_b128 v[200:203], v211 offset:4096
	ds_read_b128 v[140:143], v207 offset:4096
	s_waitcnt lgkmcnt(4)
	v_mfma_f32_32x32x16_bf16 v[50:65], v[128:131], v[120:123], v[50:65]
	v_mfma_f32_32x32x16_bf16 v[34:49], v[132:135], v[120:123], v[34:49]
	v_mfma_f32_32x32x16_bf16 v[18:33], v[132:135], v[124:127], v[18:33]
	v_mfma_f32_32x32x16_bf16 v[2:17], v[128:131], v[124:127], v[2:17]
	s_waitcnt lgkmcnt(0)
	v_mfma_f32_32x32x16_bf16 v[50:65], v[184:187], v[136:139], v[50:65]
	v_mfma_f32_32x32x16_bf16 v[34:49], v[200:203], v[136:139], v[34:49]
	v_mfma_f32_32x32x16_bf16 v[18:33], v[200:203], v[140:143], v[18:33]
	v_mfma_f32_32x32x16_bf16 v[2:17], v[184:187], v[140:143], v[2:17]
	s_setprio 0
	s_waitcnt vmcnt(0)
	s_barrier
; #define MFMA(a, b, c) __builtin_amdgcn_mfma_f32_32x32x16_bf16((a), (b), (c), 0, 0, 0)
; template <bool SWAP>
; DI void gemm_block(const bf16_t* __restrict__ A, int lda, const bf16_t* __restrict__ Bt, int ldb, int K, f32x16 (&acc)[2][2], bf16_t* sA, bf16_t* sB) {
;     ...
;   for (int kt = 0; kt < nk; ++kt) {
;     const int cur = kt & 1;
;     const bool more = kt + 1 < nk;
;     if (more) {
;       const int k0 = (kt + 1) * 64;
; #pragma unroll
;       for (int i = 0; i < 4; ++i) { ra[i] = *(const u32x4*)(ga + (size_t)i * 32 * lda + k0); rb[i] = *(const u32x4*)(gb + (size_t)i * 32 * ldb + k0); }
;     }
;     const bf16_t* ab = sA + cur * 128 * LDT + (64 * wr + l32) * LDT + h * 8;
;     const bf16_t* bb = sB + cur * 128 * LDT + (64 * wc + l32) * LDT + h * 8;
;     __builtin_amdgcn_s_setprio(1);
;     __builtin_amdgcn_iglp_opt(0);
; #pragma unroll
;     for (int ks = 0; ks < 4; ++ks) {
;       const bf16x8 a0 = *(const bf16x8*)(ab + ks * 16), a1 = *(const bf16x8*)(ab + 32 * LDT + ks * 16);
;       const bf16x8 b0 = *(const bf16x8*)(bb + ks * 16), b1 = *(const bf16x8*)(bb + 32 * LDT + ks * 16);
;       if (!SWAP) {
;         acc[0][0] = MFMA(a0, b0, acc[0][0]); acc[0][1] = MFMA(a0, b1, acc[0][1]);
;         acc[1][0] = MFMA(a1, b0, acc[1][0]); acc[1][1] = MFMA(a1, b1, acc[1][1]);
;       } else {
;         acc[0][0] = MFMA(b0, a0, acc[0][0]); acc[0][1] = MFMA(b1, a0, acc[0][1]);
;         acc[1][0] = MFMA(b0, a1, acc[1][0]); acc[1][1] = MFMA(b1, a1, acc[1][1]);
;       }
;     }
;     __builtin_amdgcn_s_setprio(0);
;     if (more) {
;       const int nb = (cur ^ 1) * 128 * LDT;
; #pragma unroll
;       for (int i = 0; i < 4; ++i) { *(u32x4*)(sA + nb + soff + i * 32 * LDT) = ra[i]; *(u32x4*)(sB + nb + soff + i * 32 * LDT) = rb[i]; }
;     }
;     __syncthreads();
;   }
	ds_read_b128 v[120:123], v204 offset:32768
	ds_read_b128 v[128:131], v208 offset:32768
	ds_read_b128 v[132:135], v208 offset:36864
	ds_read_b128 v[124:127], v204 offset:36864
	ds_read_b128 v[136:139], v205 offset:32768
	ds_read_b128 v[184:187], v209 offset:32768
	ds_read_b128 v[200:203], v209 offset:36864
	ds_read_b128 v[140:143], v205 offset:36864
	s_setprio 1
	s_waitcnt lgkmcnt(4)
	s_add_u32 m0, s100, 1024
	v_mfma_f32_32x32x16_bf16 v[50:65], v[128:131], v[120:123], v[50:65]
	global_load_lds_dwordx4 v[68:69], off offset:1024
	s_add_u32 m0, s100, 17408
	v_mfma_f32_32x32x16_bf16 v[34:49], v[132:135], v[120:123], v[34:49]
	global_load_lds_dwordx4 v[70:71], off offset:1024
	s_add_u32 m0, s100, 5120
	v_mfma_f32_32x32x16_bf16 v[18:33], v[132:135], v[124:127], v[18:33]
	global_load_lds_dwordx4 v[72:73], off offset:1024
	s_add_u32 m0, s100, 21504
	v_mfma_f32_32x32x16_bf16 v[2:17], v[128:131], v[124:127], v[2:17]
	global_load_lds_dwordx4 v[74:75], off offset:1024
	ds_read_b128 v[120:123], v206 offset:32768
	ds_read_b128 v[128:131], v210 offset:32768
	ds_read_b128 v[132:135], v210 offset:36864
	ds_read_b128 v[124:127], v206 offset:36864
	s_waitcnt lgkmcnt(4)
	s_add_u32 m0, s100, 9216
	v_mfma_f32_32x32x16_bf16 v[50:65], v[184:187], v[136:139], v[50:65]
	global_load_lds_dwordx4 v[76:77], off offset:1024
	s_add_u32 m0, s100, 25600
	v_mfma_f32_32x32x16_bf16 v[34:49], v[200:203], v[136:139], v[34:49]
	global_load_lds_dwordx4 v[78:79], off offset:1024
	s_add_u32 m0, s100, 13312
	v_mfma_f32_32x32x16_bf16 v[18:33], v[200:203], v[140:143], v[18:33]
	global_load_lds_dwordx4 v[80:81], off offset:1024
	s_add_u32 m0, s100, 29696
	v_mfma_f32_32x32x16_bf16 v[2:17], v[184:187], v[140:143], v[2:17]
	global_load_lds_dwordx4 v[82:83], off offset:1024
	ds_read_b128 v[136:139], v207 offset:32768
	ds_read_b128 v[184:187], v211 offset:32768
	ds_read_b128 v[200:203], v211 offset:36864
	ds_read_b128 v[140:143], v207 offset:36864
	s_waitcnt lgkmcnt(4)
	v_mfma_f32_32x32x16_bf16 v[50:65], v[128:131], v[120:123], v[50:65]
	v_mfma_f32_32x32x16_bf16 v[34:49], v[132:135], v[120:123], v[34:49]
	v_mfma_f32_32x32x16_bf16 v[18:33], v[132:135], v[124:127], v[18:33]
	v_mfma_f32_32x32x16_bf16 v[2:17], v[128:131], v[124:127], v[2:17]
	s_waitcnt lgkmcnt(0)
	v_mfma_f32_32x32x16_bf16 v[50:65], v[184:187], v[136:139], v[50:65]
	v_mfma_f32_32x32x16_bf16 v[34:49], v[200:203], v[136:139], v[34:49]
	v_mfma_f32_32x32x16_bf16 v[18:33], v[200:203], v[140:143], v[18:33]
	v_mfma_f32_32x32x16_bf16 v[2:17], v[184:187], v[140:143], v[2:17]
	s_setprio 0
	s_waitcnt vmcnt(0)
	s_barrier
	ds_read_b128 v[120:123], v204
	ds_read_b128 v[128:131], v208
	ds_read_b128 v[132:135], v208 offset:4096
	ds_read_b128 v[124:127], v204 offset:4096
	ds_read_b128 v[136:139], v205
	ds_read_b128 v[184:187], v209
	ds_read_b128 v[200:203], v209 offset:4096
	ds_read_b128 v[140:143], v205 offset:4096
	s_setprio 1
	s_waitcnt lgkmcnt(4)
	s_add_u32 m0, s100, 33664
	v_mfma_f32_32x32x16_bf16 v[50:65], v[128:131], v[120:123], v[50:65]
	global_load_lds_dwordx4 v[68:69], off offset:1152
	s_add_u32 m0, s100, 50048
	v_mfma_f32_32x32x16_bf16 v[34:49], v[132:135], v[120:123], v[34:49]
	global_load_lds_dwordx4 v[70:71], off offset:1152
	s_add_u32 m0, s100, 37760
	v_mfma_f32_32x32x16_bf16 v[18:33], v[132:135], v[124:127], v[18:33]
	global_load_lds_dwordx4 v[72:73], off offset:1152
	s_add_u32 m0, s100, 54144
	v_mfma_f32_32x32x16_bf16 v[2:17], v[128:131], v[124:127], v[2:17]
	global_load_lds_dwordx4 v[74:75], off offset:1152
	ds_read_b128 v[120:123], v206
	ds_read_b128 v[128:131], v210
	ds_read_b128 v[132:135], v210 offset:4096
	ds_read_b128 v[124:127], v206 offset:4096
	s_waitcnt lgkmcnt(4)
	s_add_u32 m0, s100, 41856
	v_mfma_f32_32x32x16_bf16 v[50:65], v[184:187], v[136:139], v[50:65]
	global_load_lds_dwordx4 v[76:77], off offset:1152
	s_add_u32 m0, s100, 58240
	v_mfma_f32_32x32x16_bf16 v[34:49], v[200:203], v[136:139], v[34:49]
	global_load_lds_dwordx4 v[78:79], off offset:1152
	s_add_u32 m0, s100, 45952
	v_mfma_f32_32x32x16_bf16 v[18:33], v[200:203], v[140:143], v[18:33]
	global_load_lds_dwordx4 v[80:81], off offset:1152
	s_add_u32 m0, s100, 62336
	v_mfma_f32_32x32x16_bf16 v[2:17], v[184:187], v[140:143], v[2:17]
	global_load_lds_dwordx4 v[82:83], off offset:1152
	ds_read_b128 v[136:139], v207
	ds_read_b128 v[184:187], v211
	ds_read_b128 v[200:203], v211 offset:4096
	ds_read_b128 v[140:143], v207 offset:4096
	s_waitcnt lgkmcnt(4)
	v_mfma_f32_32x32x16_bf16 v[50:65], v[128:131], v[120:123], v[50:65]
	v_mfma_f32_32x32x16_bf16 v[34:49], v[132:135], v[120:123], v[34:49]
	v_mfma_f32_32x32x16_bf16 v[18:33], v[132:135], v[124:127], v[18:33]
	v_mfma_f32_32x32x16_bf16 v[2:17], v[128:131], v[124:127], v[2:17]
	s_waitcnt lgkmcnt(0)
	v_mfma_f32_32x32x16_bf16 v[50:65], v[184:187], v[136:139], v[50:65]
	v_mfma_f32_32x32x16_bf16 v[34:49], v[200:203], v[136:139], v[34:49]
	v_mfma_f32_32x32x16_bf16 v[18:33], v[200:203], v[140:143], v[18:33]
	v_mfma_f32_32x32x16_bf16 v[2:17], v[184:187], v[140:143], v[2:17]
	s_setprio 0
	s_waitcnt vmcnt(0)
	s_barrier
; #define MFMA(a, b, c) __builtin_amdgcn_mfma_f32_32x32x16_bf16((a), (b), (c), 0, 0, 0)
; template <bool SWAP>
; DI void gemm_block(const bf16_t* __restrict__ A, int lda, const bf16_t* __restrict__ Bt, int ldb, int K, f32x16 (&acc)[2][2], bf16_t* sA, bf16_t* sB) {
;     ...
;   for (int kt = 0; kt < nk; ++kt) {
;     const int cur = kt & 1;
;     const bool more = kt + 1 < nk;
;     if (more) {
;       const int k0 = (kt + 1) * 64;
; #pragma unroll
;       for (int i = 0; i < 4; ++i) { ra[i] = *(const u32x4*)(ga + (size_t)i * 32 * lda + k0); rb[i] = *(const u32x4*)(gb + (size_t)i * 32 * ldb + k0); }
;     }
;     const bf16_t* ab = sA + cur * 128 * LDT + (64 * wr + l32) * LDT + h * 8;
;     const bf16_t* bb = sB + cur * 128 * LDT + (64 * wc + l32) * LDT + h * 8;
;     __builtin_amdgcn_s_setprio(1);
;     __builtin_amdgcn_iglp_opt(0);
; #pragma unroll
;     for (int ks = 0; ks < 4; ++ks) {
;       const bf16x8 a0 = *(const bf16x8*)(ab + ks * 16), a1 = *(const bf16x8*)(ab + 32 * LDT + ks * 16);
;       const bf16x8 b0 = *(const bf16x8*)(bb + ks * 16), b1 = *(const bf16x8*)(bb + 32 * LDT + ks * 16);
;       if (!SWAP) {
;         acc[0][0] = MFMA(a0, b0, acc[0][0]); acc[0][1] = MFMA(a0, b1, acc[0][1]);
;         acc[1][0] = MFMA(a1, b0, acc[1][0]); acc[1][1] = MFMA(a1, b1, acc[1][1]);
;       } else {
;         acc[0][0] = MFMA(b0, a0, acc[0][0]); acc[0][1] = MFMA(b1, a0, acc[0][1]);
;         acc[1][0] = MFMA(b0, a1, acc[1][0]); acc[1][1] = MFMA(b1, a1, acc[1][1]);
;       }
;     }
;     __builtin_amdgcn_s_setprio(0);
;     if (more) {
;       const int nb = (cur ^ 1) * 128 * LDT;
; #pragma unroll
;       for (int i = 0; i < 4; ++i) { *(u32x4*)(sA + nb + soff + i * 32 * LDT) = ra[i]; *(u32x4*)(sB + nb + soff + i * 32 * LDT) = rb[i]; }
;     }
;     __syncthreads();
;   }
	ds_read_b128 v[120:123], v204 offset:32768
	ds_read_b128 v[128:131], v208 offset:32768
	ds_read_b128 v[132:135], v208 offset:36864
	ds_read_b128 v[124:127], v204 offset:36864
	ds_read_b128 v[136:139], v205 offset:32768
	ds_read_b128 v[184:187], v209 offset:32768
	ds_read_b128 v[200:203], v209 offset:36864
	ds_read_b128 v[140:143], v205 offset:36864
	s_setprio 1
	s_waitcnt lgkmcnt(4)
	s_add_u32 m0, s100, 768
	v_mfma_f32_32x32x16_bf16 v[50:65], v[128:131], v[120:123], v[50:65]
	global_load_lds_dwordx4 v[68:69], off offset:1280
	s_add_u32 m0, s100, 17152
	v_mfma_f32_32x32x16_bf16 v[34:49], v[132:135], v[120:123], v[34:49]
	global_load_lds_dwordx4 v[70:71], off offset:1280
	s_add_u32 m0, s100, 4864
	v_mfma_f32_32x32x16_bf16 v[18:33], v[132:135], v[124:127], v[18:33]
	global_load_lds_dwordx4 v[72:73], off offset:1280
	s_add_u32 m0, s100, 21248
	v_mfma_f32_32x32x16_bf16 v[2:17], v[128:131], v[124:127], v[2:17]
	global_load_lds_dwordx4 v[74:75], off offset:1280
	ds_read_b128 v[120:123], v206 offset:32768
	ds_read_b128 v[128:131], v210 offset:32768
	ds_read_b128 v[132:135], v210 offset:36864
	ds_read_b128 v[124:127], v206 offset:36864
	s_waitcnt lgkmcnt(4)
	s_add_u32 m0, s100, 8960
	v_mfma_f32_32x32x16_bf16 v[50:65], v[184:187], v[136:139], v[50:65]
	global_load_lds_dwordx4 v[76:77], off offset:1280
	s_add_u32 m0, s100, 25344
	v_mfma_f32_32x32x16_bf16 v[34:49], v[200:203], v[136:139], v[34:49]
	global_load_lds_dwordx4 v[78:79], off offset:1280
	s_add_u32 m0, s100, 13056
	v_mfma_f32_32x32x16_bf16 v[18:33], v[200:203], v[140:143], v[18:33]
	global_load_lds_dwordx4 v[80:81], off offset:1280
	s_add_u32 m0, s100, 29440
	v_mfma_f32_32x32x16_bf16 v[2:17], v[184:187], v[140:143], v[2:17]
	global_load_lds_dwordx4 v[82:83], off offset:1280
	ds_read_b128 v[136:139], v207 offset:32768
	ds_read_b128 v[184:187], v211 offset:32768
	ds_read_b128 v[200:203], v211 offset:36864
	ds_read_b128 v[140:143], v207 offset:36864
	s_waitcnt lgkmcnt(4)
	v_mfma_f32_32x32x16_bf16 v[50:65], v[128:131], v[120:123], v[50:65]
	v_mfma_f32_32x32x16_bf16 v[34:49], v[132:135], v[120:123], v[34:49]
	v_mfma_f32_32x32x16_bf16 v[18:33], v[132:135], v[124:127], v[18:33]
	v_mfma_f32_32x32x16_bf16 v[2:17], v[128:131], v[124:127], v[2:17]
	s_waitcnt lgkmcnt(0)
	v_mfma_f32_32x32x16_bf16 v[50:65], v[184:187], v[136:139], v[50:65]
	v_mfma_f32_32x32x16_bf16 v[34:49], v[200:203], v[136:139], v[34:49]
	v_mfma_f32_32x32x16_bf16 v[18:33], v[200:203], v[140:143], v[18:33]
	v_mfma_f32_32x32x16_bf16 v[2:17], v[184:187], v[140:143], v[2:17]
	s_setprio 0
	s_waitcnt vmcnt(0)
	s_barrier
	ds_read_b128 v[120:123], v204
	ds_read_b128 v[128:131], v208
	ds_read_b128 v[132:135], v208 offset:4096
	ds_read_b128 v[124:127], v204 offset:4096
	ds_read_b128 v[136:139], v205
	ds_read_b128 v[184:187], v209
	ds_read_b128 v[200:203], v209 offset:4096
	ds_read_b128 v[140:143], v205 offset:4096
	s_setprio 1
	s_waitcnt lgkmcnt(4)
	s_add_u32 m0, s100, 33408
	v_mfma_f32_32x32x16_bf16 v[50:65], v[128:131], v[120:123], v[50:65]
	global_load_lds_dwordx4 v[68:69], off offset:1408
	s_add_u32 m0, s100, 49792
	v_mfma_f32_32x32x16_bf16 v[34:49], v[132:135], v[120:123], v[34:49]
	global_load_lds_dwordx4 v[70:71], off offset:1408
	s_add_u32 m0, s100, 37504
	v_mfma_f32_32x32x16_bf16 v[18:33], v[132:135], v[124:127], v[18:33]
	global_load_lds_dwordx4 v[72:73], off offset:1408
	s_add_u32 m0, s100, 53888
	v_mfma_f32_32x32x16_bf16 v[2:17], v[128:131], v[124:127], v[2:17]
	global_load_lds_dwordx4 v[74:75], off offset:1408
	ds_read_b128 v[120:123], v206
	ds_read_b128 v[128:131], v210
	ds_read_b128 v[132:135], v210 offset:4096
	ds_read_b128 v[124:127], v206 offset:4096
	s_waitcnt lgkmcnt(4)
	s_add_u32 m0, s100, 41600
	v_mfma_f32_32x32x16_bf16 v[50:65], v[184:187], v[136:139], v[50:65]
	global_load_lds_dwordx4 v[76:77], off offset:1408
	s_add_u32 m0, s100, 57984
	v_mfma_f32_32x32x16_bf16 v[34:49], v[200:203], v[136:139], v[34:49]
	global_load_lds_dwordx4 v[78:79], off offset:1408
	s_add_u32 m0, s100, 45696
	v_mfma_f32_32x32x16_bf16 v[18:33], v[200:203], v[140:143], v[18:33]
	global_load_lds_dwordx4 v[80:81], off offset:1408
	s_add_u32 m0, s100, 62080
	v_mfma_f32_32x32x16_bf16 v[2:17], v[184:187], v[140:143], v[2:17]
	global_load_lds_dwordx4 v[82:83], off offset:1408
	ds_read_b128 v[136:139], v207
	ds_read_b128 v[184:187], v211
	ds_read_b128 v[200:203], v211 offset:4096
	ds_read_b128 v[140:143], v207 offset:4096
	s_waitcnt lgkmcnt(4)
	v_mfma_f32_32x32x16_bf16 v[50:65], v[128:131], v[120:123], v[50:65]
	v_mfma_f32_32x32x16_bf16 v[34:49], v[132:135], v[120:123], v[34:49]
	v_mfma_f32_32x32x16_bf16 v[18:33], v[132:135], v[124:127], v[18:33]
	v_mfma_f32_32x32x16_bf16 v[2:17], v[128:131], v[124:127], v[2:17]
	s_waitcnt lgkmcnt(0)
	v_mfma_f32_32x32x16_bf16 v[50:65], v[184:187], v[136:139], v[50:65]
	v_mfma_f32_32x32x16_bf16 v[34:49], v[200:203], v[136:139], v[34:49]
	v_mfma_f32_32x32x16_bf16 v[18:33], v[200:203], v[140:143], v[18:33]
	v_mfma_f32_32x32x16_bf16 v[2:17], v[184:187], v[140:143], v[2:17]
	s_setprio 0
	s_waitcnt vmcnt(0)
	s_barrier
; #define MFMA(a, b, c) __builtin_amdgcn_mfma_f32_32x32x16_bf16((a), (b), (c), 0, 0, 0)
; template <bool SWAP>
; DI void gemm_block(const bf16_t* __restrict__ A, int lda, const bf16_t* __restrict__ Bt, int ldb, int K, f32x16 (&acc)[2][2], bf16_t* sA, bf16_t* sB) {
;     ...
;   for (int kt = 0; kt < nk; ++kt) {
;     const int cur = kt & 1;
;     const bool more = kt + 1 < nk;
;     if (more) {
;       const int k0 = (kt + 1) * 64;
; #pragma unroll
;       for (int i = 0; i < 4; ++i) { ra[i] = *(const u32x4*)(ga + (size_t)i * 32 * lda + k0); rb[i] = *(const u32x4*)(gb + (size_t)i * 32 * ldb + k0); }
;     }
;     const bf16_t* ab = sA + cur * 128 * LDT + (64 * wr + l32) * LDT + h * 8;
;     const bf16_t* bb = sB + cur * 128 * LDT + (64 * wc + l32) * LDT + h * 8;
;     __builtin_amdgcn_s_setprio(1);
;     __builtin_amdgcn_iglp_opt(0);
; #pragma unroll
;     for (int ks = 0; ks < 4; ++ks) {
;       const bf16x8 a0 = *(const bf16x8*)(ab + ks * 16), a1 = *(const bf16x8*)(ab + 32 * LDT + ks * 16);
;       const bf16x8 b0 = *(const bf16x8*)(bb + ks * 16), b1 = *(const bf16x8*)(bb + 32 * LDT + ks * 16);
;       if (!SWAP) {
;         acc[0][0] = MFMA(a0, b0, acc[0][0]); acc[0][1] = MFMA(a0, b1, acc[0][1]);
;         acc[1][0] = MFMA(a1, b0, acc[1][0]); acc[1][1] = MFMA(a1, b1, acc[1][1]);
;       } else {
;         acc[0][0] = MFMA(b0, a0, acc[0][0]); acc[0][1] = MFMA(b1, a0, acc[0][1]);
;         acc[1][0] = MFMA(b0, a1, acc[1][0]); acc[1][1] = MFMA(b1, a1, acc[1][1]);
;       }
;     }
;     __builtin_amdgcn_s_setprio(0);
;     if (more) {
;       const int nb = (cur ^ 1) * 128 * LDT;
; #pragma unroll
;       for (int i = 0; i < 4; ++i) { *(u32x4*)(sA + nb + soff + i * 32 * LDT) = ra[i]; *(u32x4*)(sB + nb + soff + i * 32 * LDT) = rb[i]; }
;     }
;     __syncthreads();
;   }
	ds_read_b128 v[120:123], v204 offset:32768
	ds_read_b128 v[128:131], v208 offset:32768
	ds_read_b128 v[132:135], v208 offset:36864
	ds_read_b128 v[124:127], v204 offset:36864
	ds_read_b128 v[136:139], v205 offset:32768
	ds_read_b128 v[184:187], v209 offset:32768
	ds_read_b128 v[200:203], v209 offset:36864
	ds_read_b128 v[140:143], v205 offset:36864
	s_setprio 1
	s_waitcnt lgkmcnt(4)
	s_add_u32 m0, s100, 512
	v_mfma_f32_32x32x16_bf16 v[50:65], v[128:131], v[120:123], v[50:65]
	global_load_lds_dwordx4 v[68:69], off offset:1536
	s_add_u32 m0, s100, 16896
	v_mfma_f32_32x32x16_bf16 v[34:49], v[132:135], v[120:123], v[34:49]
	global_load_lds_dwordx4 v[70:71], off offset:1536
	s_add_u32 m0, s100, 4608
	v_mfma_f32_32x32x16_bf16 v[18:33], v[132:135], v[124:127], v[18:33]
	global_load_lds_dwordx4 v[72:73], off offset:1536
	s_add_u32 m0, s100, 20992
	v_mfma_f32_32x32x16_bf16 v[2:17], v[128:131], v[124:127], v[2:17]
	global_load_lds_dwordx4 v[74:75], off offset:1536
	ds_read_b128 v[120:123], v206 offset:32768
	ds_read_b128 v[128:131], v210 offset:32768
	ds_read_b128 v[132:135], v210 offset:36864
	ds_read_b128 v[124:127], v206 offset:36864
	s_waitcnt lgkmcnt(4)
	s_add_u32 m0, s100, 8704
	v_mfma_f32_32x32x16_bf16 v[50:65], v[184:187], v[136:139], v[50:65]
	global_load_lds_dwordx4 v[76:77], off offset:1536
	s_add_u32 m0, s100, 25088
	v_mfma_f32_32x32x16_bf16 v[34:49], v[200:203], v[136:139], v[34:49]
	global_load_lds_dwordx4 v[78:79], off offset:1536
	s_add_u32 m0, s100, 12800
	v_mfma_f32_32x32x16_bf16 v[18:33], v[200:203], v[140:143], v[18:33]
	global_load_lds_dwordx4 v[80:81], off offset:1536
	s_add_u32 m0, s100, 29184
	v_mfma_f32_32x32x16_bf16 v[2:17], v[184:187], v[140:143], v[2:17]
	global_load_lds_dwordx4 v[82:83], off offset:1536
	ds_read_b128 v[136:139], v207 offset:32768
	ds_read_b128 v[184:187], v211 offset:32768
	ds_read_b128 v[200:203], v211 offset:36864
	ds_read_b128 v[140:143], v207 offset:36864
	s_waitcnt lgkmcnt(4)
	v_mfma_f32_32x32x16_bf16 v[50:65], v[128:131], v[120:123], v[50:65]
	v_mfma_f32_32x32x16_bf16 v[34:49], v[132:135], v[120:123], v[34:49]
	v_mfma_f32_32x32x16_bf16 v[18:33], v[132:135], v[124:127], v[18:33]
	v_mfma_f32_32x32x16_bf16 v[2:17], v[128:131], v[124:127], v[2:17]
	s_waitcnt lgkmcnt(0)
	v_mfma_f32_32x32x16_bf16 v[50:65], v[184:187], v[136:139], v[50:65]
	v_mfma_f32_32x32x16_bf16 v[34:49], v[200:203], v[136:139], v[34:49]
	v_mfma_f32_32x32x16_bf16 v[18:33], v[200:203], v[140:143], v[18:33]
	v_mfma_f32_32x32x16_bf16 v[2:17], v[184:187], v[140:143], v[2:17]
	s_setprio 0
	s_waitcnt vmcnt(0)
	s_barrier
	ds_read_b128 v[120:123], v204
	ds_read_b128 v[128:131], v208
	ds_read_b128 v[132:135], v208 offset:4096
	ds_read_b128 v[124:127], v204 offset:4096
	ds_read_b128 v[136:139], v205
	ds_read_b128 v[184:187], v209
	ds_read_b128 v[200:203], v209 offset:4096
	ds_read_b128 v[140:143], v205 offset:4096
	s_setprio 1
	s_waitcnt lgkmcnt(4)
	s_add_u32 m0, s100, 33152
	v_mfma_f32_32x32x16_bf16 v[50:65], v[128:131], v[120:123], v[50:65]
	global_load_lds_dwordx4 v[68:69], off offset:1664
	s_add_u32 m0, s100, 49536
	v_mfma_f32_32x32x16_bf16 v[34:49], v[132:135], v[120:123], v[34:49]
	global_load_lds_dwordx4 v[70:71], off offset:1664
	s_add_u32 m0, s100, 37248
	v_mfma_f32_32x32x16_bf16 v[18:33], v[132:135], v[124:127], v[18:33]
	global_load_lds_dwordx4 v[72:73], off offset:1664
	s_add_u32 m0, s100, 53632
	v_mfma_f32_32x32x16_bf16 v[2:17], v[128:131], v[124:127], v[2:17]
	global_load_lds_dwordx4 v[74:75], off offset:1664
	ds_read_b128 v[120:123], v206
	ds_read_b128 v[128:131], v210
	ds_read_b128 v[132:135], v210 offset:4096
	ds_read_b128 v[124:127], v206 offset:4096
	s_waitcnt lgkmcnt(4)
	s_add_u32 m0, s100, 41344
	v_mfma_f32_32x32x16_bf16 v[50:65], v[184:187], v[136:139], v[50:65]
	global_load_lds_dwordx4 v[76:77], off offset:1664
	s_add_u32 m0, s100, 57728
	v_mfma_f32_32x32x16_bf16 v[34:49], v[200:203], v[136:139], v[34:49]
	global_load_lds_dwordx4 v[78:79], off offset:1664
	s_add_u32 m0, s100, 45440
	v_mfma_f32_32x32x16_bf16 v[18:33], v[200:203], v[140:143], v[18:33]
	global_load_lds_dwordx4 v[80:81], off offset:1664
	s_add_u32 m0, s100, 61824
	v_mfma_f32_32x32x16_bf16 v[2:17], v[184:187], v[140:143], v[2:17]
	global_load_lds_dwordx4 v[82:83], off offset:1664
	ds_read_b128 v[136:139], v207
	ds_read_b128 v[184:187], v211
	ds_read_b128 v[200:203], v211 offset:4096
	ds_read_b128 v[140:143], v207 offset:4096
	s_waitcnt lgkmcnt(4)
	v_mfma_f32_32x32x16_bf16 v[50:65], v[128:131], v[120:123], v[50:65]
	v_mfma_f32_32x32x16_bf16 v[34:49], v[132:135], v[120:123], v[34:49]
	v_mfma_f32_32x32x16_bf16 v[18:33], v[132:135], v[124:127], v[18:33]
	v_mfma_f32_32x32x16_bf16 v[2:17], v[128:131], v[124:127], v[2:17]
	s_waitcnt lgkmcnt(0)
	v_mfma_f32_32x32x16_bf16 v[50:65], v[184:187], v[136:139], v[50:65]
	v_mfma_f32_32x32x16_bf16 v[34:49], v[200:203], v[136:139], v[34:49]
	v_mfma_f32_32x32x16_bf16 v[18:33], v[200:203], v[140:143], v[18:33]
	v_mfma_f32_32x32x16_bf16 v[2:17], v[184:187], v[140:143], v[2:17]
	s_setprio 0
	s_waitcnt vmcnt(0)
	s_barrier
; #define MFMA(a, b, c) __builtin_amdgcn_mfma_f32_32x32x16_bf16((a), (b), (c), 0, 0, 0)
; template <bool SWAP>
; DI void gemm_block(const bf16_t* __restrict__ A, int lda, const bf16_t* __restrict__ Bt, int ldb, int K, f32x16 (&acc)[2][2], bf16_t* sA, bf16_t* sB) {
;     ...
;   for (int kt = 0; kt < nk; ++kt) {
;     const int cur = kt & 1;
;     const bool more = kt + 1 < nk;
;     if (more) {
;       const int k0 = (kt + 1) * 64;
; #pragma unroll
;       for (int i = 0; i < 4; ++i) { ra[i] = *(const u32x4*)(ga + (size_t)i * 32 * lda + k0); rb[i] = *(const u32x4*)(gb + (size_t)i * 32 * ldb + k0); }
;     }
;     const bf16_t* ab = sA + cur * 128 * LDT + (64 * wr + l32) * LDT + h * 8;
;     const bf16_t* bb = sB + cur * 128 * LDT + (64 * wc + l32) * LDT + h * 8;
;     __builtin_amdgcn_s_setprio(1);
;     __builtin_amdgcn_iglp_opt(0);
; #pragma unroll
;     for (int ks = 0; ks < 4; ++ks) {
;       const bf16x8 a0 = *(const bf16x8*)(ab + ks * 16), a1 = *(const bf16x8*)(ab + 32 * LDT + ks * 16);
;       const bf16x8 b0 = *(const bf16x8*)(bb + ks * 16), b1 = *(const bf16x8*)(bb + 32 * LDT + ks * 16);
;       if (!SWAP) {
;         acc[0][0] = MFMA(a0, b0, acc[0][0]); acc[0][1] = MFMA(a0, b1, acc[0][1]);
;         acc[1][0] = MFMA(a1, b0, acc[1][0]); acc[1][1] = MFMA(a1, b1, acc[1][1]);
;       } else {
;         acc[0][0] = MFMA(b0, a0, acc[0][0]); acc[0][1] = MFMA(b1, a0, acc[0][1]);
;         acc[1][0] = MFMA(b0, a1, acc[1][0]); acc[1][1] = MFMA(b1, a1, acc[1][1]);
;       }
;     }
;     __builtin_amdgcn_s_setprio(0);
;     if (more) {
;       const int nb = (cur ^ 1) * 128 * LDT;
; #pragma unroll
;       for (int i = 0; i < 4; ++i) { *(u32x4*)(sA + nb + soff + i * 32 * LDT) = ra[i]; *(u32x4*)(sB + nb + soff + i * 32 * LDT) = rb[i]; }
;     }
;     __syncthreads();
;   }
	ds_read_b128 v[120:123], v204 offset:32768
	ds_read_b128 v[128:131], v208 offset:32768
	ds_read_b128 v[132:135], v208 offset:36864
	ds_read_b128 v[124:127], v204 offset:36864
	ds_read_b128 v[136:139], v205 offset:32768
	ds_read_b128 v[184:187], v209 offset:32768
	ds_read_b128 v[200:203], v209 offset:36864
	ds_read_b128 v[140:143], v205 offset:36864
	s_setprio 1
	s_waitcnt lgkmcnt(4)
	s_add_u32 m0, s100, 256
	v_mfma_f32_32x32x16_bf16 v[50:65], v[128:131], v[120:123], v[50:65]
	global_load_lds_dwordx4 v[68:69], off offset:1792
	s_add_u32 m0, s100, 16640
	v_mfma_f32_32x32x16_bf16 v[34:49], v[132:135], v[120:123], v[34:49]
	global_load_lds_dwordx4 v[70:71], off offset:1792
	s_add_u32 m0, s100, 4352
	v_mfma_f32_32x32x16_bf16 v[18:33], v[132:135], v[124:127], v[18:33]
	global_load_lds_dwordx4 v[72:73], off offset:1792
	s_add_u32 m0, s100, 20736
	v_mfma_f32_32x32x16_bf16 v[2:17], v[128:131], v[124:127], v[2:17]
	global_load_lds_dwordx4 v[74:75], off offset:1792
	ds_read_b128 v[120:123], v206 offset:32768
	ds_read_b128 v[128:131], v210 offset:32768
	ds_read_b128 v[132:135], v210 offset:36864
	ds_read_b128 v[124:127], v206 offset:36864
	s_waitcnt lgkmcnt(4)
	s_add_u32 m0, s100, 8448
	v_mfma_f32_32x32x16_bf16 v[50:65], v[184:187], v[136:139], v[50:65]
	global_load_lds_dwordx4 v[76:77], off offset:1792
	s_add_u32 m0, s100, 24832
	v_mfma_f32_32x32x16_bf16 v[34:49], v[200:203], v[136:139], v[34:49]
	global_load_lds_dwordx4 v[78:79], off offset:1792
	s_add_u32 m0, s100, 12544
	v_mfma_f32_32x32x16_bf16 v[18:33], v[200:203], v[140:143], v[18:33]
	global_load_lds_dwordx4 v[80:81], off offset:1792
	s_add_u32 m0, s100, 28928
	v_mfma_f32_32x32x16_bf16 v[2:17], v[184:187], v[140:143], v[2:17]
	global_load_lds_dwordx4 v[82:83], off offset:1792
	ds_read_b128 v[136:139], v207 offset:32768
	ds_read_b128 v[184:187], v211 offset:32768
	ds_read_b128 v[200:203], v211 offset:36864
	ds_read_b128 v[140:143], v207 offset:36864
	s_waitcnt lgkmcnt(4)
	v_mfma_f32_32x32x16_bf16 v[50:65], v[128:131], v[120:123], v[50:65]
	v_mfma_f32_32x32x16_bf16 v[34:49], v[132:135], v[120:123], v[34:49]
	v_mfma_f32_32x32x16_bf16 v[18:33], v[132:135], v[124:127], v[18:33]
	v_mfma_f32_32x32x16_bf16 v[2:17], v[128:131], v[124:127], v[2:17]
	s_waitcnt lgkmcnt(0)
	v_mfma_f32_32x32x16_bf16 v[50:65], v[184:187], v[136:139], v[50:65]
	v_mfma_f32_32x32x16_bf16 v[34:49], v[200:203], v[136:139], v[34:49]
	v_mfma_f32_32x32x16_bf16 v[18:33], v[200:203], v[140:143], v[18:33]
	v_mfma_f32_32x32x16_bf16 v[2:17], v[184:187], v[140:143], v[2:17]
	s_setprio 0
	s_waitcnt vmcnt(0)
	s_barrier
	ds_read_b128 v[120:123], v204
	ds_read_b128 v[128:131], v208
	ds_read_b128 v[132:135], v208 offset:4096
	ds_read_b128 v[124:127], v204 offset:4096
	ds_read_b128 v[136:139], v205
	ds_read_b128 v[184:187], v209
	ds_read_b128 v[200:203], v209 offset:4096
	ds_read_b128 v[140:143], v205 offset:4096
	s_setprio 1
	s_waitcnt lgkmcnt(4)
	s_add_u32 m0, s100, 32896
	v_mfma_f32_32x32x16_bf16 v[50:65], v[128:131], v[120:123], v[50:65]
	global_load_lds_dwordx4 v[68:69], off offset:1920
	s_add_u32 m0, s100, 49280
	v_mfma_f32_32x32x16_bf16 v[34:49], v[132:135], v[120:123], v[34:49]
	global_load_lds_dwordx4 v[70:71], off offset:1920
	s_add_u32 m0, s100, 36992
	v_mfma_f32_32x32x16_bf16 v[18:33], v[132:135], v[124:127], v[18:33]
	global_load_lds_dwordx4 v[72:73], off offset:1920
	s_add_u32 m0, s100, 53376
	v_mfma_f32_32x32x16_bf16 v[2:17], v[128:131], v[124:127], v[2:17]
	global_load_lds_dwordx4 v[74:75], off offset:1920
	ds_read_b128 v[120:123], v206
	ds_read_b128 v[128:131], v210
	ds_read_b128 v[132:135], v210 offset:4096
	ds_read_b128 v[124:127], v206 offset:4096
	s_waitcnt lgkmcnt(4)
	s_add_u32 m0, s100, 41088
	v_mfma_f32_32x32x16_bf16 v[50:65], v[184:187], v[136:139], v[50:65]
	global_load_lds_dwordx4 v[76:77], off offset:1920
	s_add_u32 m0, s100, 57472
	v_mfma_f32_32x32x16_bf16 v[34:49], v[200:203], v[136:139], v[34:49]
	global_load_lds_dwordx4 v[78:79], off offset:1920
	s_add_u32 m0, s100, 45184
	v_mfma_f32_32x32x16_bf16 v[18:33], v[200:203], v[140:143], v[18:33]
	global_load_lds_dwordx4 v[80:81], off offset:1920
	s_add_u32 m0, s100, 61568
	v_mfma_f32_32x32x16_bf16 v[2:17], v[184:187], v[140:143], v[2:17]
	global_load_lds_dwordx4 v[82:83], off offset:1920
	ds_read_b128 v[136:139], v207
	ds_read_b128 v[184:187], v211
	ds_read_b128 v[200:203], v211 offset:4096
	ds_read_b128 v[140:143], v207 offset:4096
	s_waitcnt lgkmcnt(4)
	v_mfma_f32_32x32x16_bf16 v[50:65], v[128:131], v[120:123], v[50:65]
	v_mfma_f32_32x32x16_bf16 v[34:49], v[132:135], v[120:123], v[34:49]
	v_mfma_f32_32x32x16_bf16 v[18:33], v[132:135], v[124:127], v[18:33]
	v_mfma_f32_32x32x16_bf16 v[2:17], v[128:131], v[124:127], v[2:17]
	s_waitcnt lgkmcnt(0)
	v_mfma_f32_32x32x16_bf16 v[50:65], v[184:187], v[136:139], v[50:65]
	v_mfma_f32_32x32x16_bf16 v[34:49], v[200:203], v[136:139], v[34:49]
	v_mfma_f32_32x32x16_bf16 v[18:33], v[200:203], v[140:143], v[18:33]
	v_mfma_f32_32x32x16_bf16 v[2:17], v[184:187], v[140:143], v[2:17]
	s_setprio 0
	s_waitcnt vmcnt(0)
	s_barrier
; template <bool SWAP>
; DI void gemm_block(const bf16_t* __restrict__ A, int lda, const bf16_t* __restrict__ Bt, int ldb, int K, f32x16 (&acc)[2][2], bf16_t* sA, bf16_t* sB) {
;     ...
; #pragma unroll
;     for (int ks = 0; ks < 4; ++ks) {
;       const bf16x8 a0 = *(const bf16x8*)(ab + ks * 16), a1 = *(const bf16x8*)(ab + 32 * LDT + ks * 16);
;       const bf16x8 b0 = *(const bf16x8*)(bb + ks * 16), b1 = *(const bf16x8*)(bb + 32 * LDT + ks * 16);
;       if (!SWAP) {
;         acc[0][0] = MFMA(a0, b0, acc[0][0]); acc[0][1] = MFMA(a0, b1, acc[0][1]);
;         acc[1][0] = MFMA(a1, b0, acc[1][0]); acc[1][1] = MFMA(a1, b1, acc[1][1]);
;       } else {
;         acc[0][0] = MFMA(b0, a0, acc[0][0]); acc[0][1] = MFMA(b1, a0, acc[0][1]);
;         acc[1][0] = MFMA(b0, a1, acc[1][0]); acc[1][1] = MFMA(b1, a1, acc[1][1]);
;       }
;     }
;     __builtin_amdgcn_s_setprio(0);
;     if (more) {
;       const int nb = (cur ^ 1) * 128 * LDT;
; #pragma unroll
;       for (int i = 0; i < 4; ++i) { *(u32x4*)(sA + nb + soff + i * 32 * LDT) = ra[i]; *(u32x4*)(sB + nb + soff + i * 32 * LDT) = rb[i]; }
;     }
;     __syncthreads();
;   }
; DI void gemm_job(PP p, int l, const GJob& J, char* smem) {
;     ...
;   if (J.epi == E_OUT) {
;     float* sOf = (float*)smem;
; #pragma unroll
;     for (int i = 0; i < 2; ++i) {
;       const int mloc = 64 * wr + 32 * i + l32;
; #pragma unroll
;       for (int j = 0; j < 2; ++j)
; #pragma unroll
;         for (int g = 0; g < 4; ++g) {
;           f32x4 v = {acc[i][j][4 * g], acc[i][j][4 * g + 1], acc[i][j][4 * g + 2], acc[i][j][4 * g + 3]};
;           *(f32x4*)(sOf + mloc * 132 + 64 * wc + 32 * j + 8 * g + 4 * h) = v;
;         }
;     }
;     __syncthreads();
; #pragma unroll 4
;     for (int it = 0; it < 16; ++it) {
;       const int id = tid + 256 * it, r = id >> 5, c = id & 31;
;       const f32x4 v = *(const f32x4*)(sOf + r * 132 + c * 4);
;       const size_t eo = (size_t)(J.m0 + r) * 1024 + J.coloff + c * 4;
;       const float* rsrc = l == 0 ? p->x : p->hres;
;       const float2 st = (l == 0 ? p->stat0 : p->stat1)[J.m0 + r];
;       const float* gp = l == 0 ? p->ln_in_g : p->ln_g;
;       const float* bp = l == 0 ? p->ln_in_b : p->ln_b;
;       const f32x4 xs = *(const f32x4*)(rsrc + eo);
;       const f32x4 g4 = *(const f32x4*)(gp + J.coloff + c * 4), b4 = *(const f32x4*)(bp + J.coloff + c * 4);
	ds_read_b128 v[120:123], v204 offset:32768
	ds_read_b128 v[128:131], v208 offset:32768
	ds_read_b128 v[132:135], v208 offset:36864
	ds_read_b128 v[124:127], v204 offset:36864
	ds_read_b128 v[136:139], v205 offset:32768
	ds_read_b128 v[184:187], v209 offset:32768
	ds_read_b128 v[200:203], v209 offset:36864
	ds_read_b128 v[140:143], v205 offset:36864
	s_setprio 1
	s_waitcnt lgkmcnt(4)
	v_mfma_f32_32x32x16_bf16 v[50:65], v[128:131], v[120:123], v[50:65]
	v_mfma_f32_32x32x16_bf16 v[34:49], v[132:135], v[120:123], v[34:49]
	v_mfma_f32_32x32x16_bf16 v[18:33], v[132:135], v[124:127], v[18:33]
	v_mfma_f32_32x32x16_bf16 v[2:17], v[128:131], v[124:127], v[2:17]
	ds_read_b128 v[120:123], v206 offset:32768
	ds_read_b128 v[128:131], v210 offset:32768
	ds_read_b128 v[132:135], v210 offset:36864
	ds_read_b128 v[124:127], v206 offset:36864
	s_waitcnt lgkmcnt(4)
	v_mfma_f32_32x32x16_bf16 v[50:65], v[184:187], v[136:139], v[50:65]
	v_mfma_f32_32x32x16_bf16 v[34:49], v[200:203], v[136:139], v[34:49]
	v_mfma_f32_32x32x16_bf16 v[18:33], v[200:203], v[140:143], v[18:33]
	v_mfma_f32_32x32x16_bf16 v[2:17], v[184:187], v[140:143], v[2:17]
	ds_read_b128 v[136:139], v207 offset:32768
	ds_read_b128 v[184:187], v211 offset:32768
	ds_read_b128 v[200:203], v211 offset:36864
	ds_read_b128 v[140:143], v207 offset:36864
	s_waitcnt lgkmcnt(4)
	v_mfma_f32_32x32x16_bf16 v[50:65], v[128:131], v[120:123], v[50:65]
	v_mfma_f32_32x32x16_bf16 v[34:49], v[132:135], v[120:123], v[34:49]
	v_mfma_f32_32x32x16_bf16 v[18:33], v[132:135], v[124:127], v[18:33]
	v_mfma_f32_32x32x16_bf16 v[2:17], v[128:131], v[124:127], v[2:17]
	s_waitcnt lgkmcnt(0)
	v_mfma_f32_32x32x16_bf16 v[50:65], v[184:187], v[136:139], v[50:65]
	v_mfma_f32_32x32x16_bf16 v[34:49], v[200:203], v[136:139], v[34:49]
	v_mfma_f32_32x32x16_bf16 v[18:33], v[200:203], v[140:143], v[18:33]
	v_mfma_f32_32x32x16_bf16 v[2:17], v[184:187], v[140:143], v[2:17]
	s_setprio 0
	s_nop 7
	s_nop 7
	v_and_b32_e32 v0, 31, v84
	v_lshrrev_b32_e32 v66, 1, v84
	s_lshl_b32 s2, s10, 7
	v_and_or_b32 v67, v66, s53, v0
	v_lshlrev_b32_e32 v68, 2, v84
	v_and_b32_e32 v0, 16, v66
	s_movk_i32 s10, 0x100
	v_and_or_b32 v0, v68, s10, v0
	v_mad_u64_u32 v[66:67], s[10:11], v67, s3, v[0:1]
	s_add_u32 s10, s4, s0
	s_addc_u32 s11, s5, 0
	s_add_u32 s12, s4, s1
	s_addc_u32 s13, s5, 0
	s_add_u32 s18, s4, s22
	s_addc_u32 s19, s5, 0
	s_add_u32 s20, s4, s23
	s_addc_u32 s21, s5, 0
	s_barrier
	ds_write_b128 v66, v[50:53]
	ds_write_b128 v66, v[54:57] offset:32
	ds_write_b128 v66, v[58:61] offset:64
	ds_write_b128 v66, v[62:65] offset:96
	ds_write_b128 v66, v[34:37] offset:128
	ds_write_b128 v66, v[38:41] offset:160
	ds_write_b128 v66, v[42:45] offset:192
	ds_write_b128 v66, v[46:49] offset:224
	ds_write_b128 v66, v[2:5] offset:16896
	ds_write_b128 v66, v[6:9] offset:16928
	ds_write_b128 v66, v[10:13] offset:16960
	ds_write_b128 v66, v[14:17] offset:16992
	ds_write_b128 v66, v[18:21] offset:17024
	ds_write_b128 v66, v[22:25] offset:17056
	ds_write_b128 v66, v[26:29] offset:17088
	ds_write_b128 v66, v[30:33] offset:17120
	s_waitcnt lgkmcnt(0)
	s_barrier
	s_load_dwordx2 s[18:19], s[18:19], 0x0
	v_and_b32_e32 v6, 0x7c, v68
	s_load_dwordx2 s[20:21], s[20:21], 0x0
	v_lshlrev_b32_e32 v0, 2, v6
	s_load_dwordx2 s[10:11], s[10:11], 0x0
	s_waitcnt lgkmcnt(0)
	v_lshl_add_u64 v[2:3], s[18:19], 0, v[0:1]
	s_load_dwordx2 s[18:19], s[12:13], 0x0
	v_lshl_add_u64 v[4:5], s[20:21], 0, v[0:1]
	s_load_dwordx2 s[20:21], s[4:5], 0x80
	s_lshl_b32 s30, s39, 2
	v_or_b32_e32 v6, s39, v6
	v_lshl_add_u64 v[2:3], v[2:3], 0, s[30:31]
	v_lshl_add_u64 v[4:5], v[4:5], 0, s[30:31]
	v_lshlrev_b32_e32 v6, 2, v6

; __global__ void __launch_bounds__(256, 2) mega(Params p_unused) {
;   __shared__ __attribute__((aligned(16))) char smem[SMEM_BYTES];
	.amdhsa_kernel _Z4mega6Params
		.amdhsa_group_segment_fixed_size 74752
		.amdhsa_private_segment_fixed_size 0
		.amdhsa_kernarg_size 648
		.amdhsa_user_sgpr_count 2
		.amdhsa_user_sgpr_dispatch_ptr 0
		.amdhsa_user_sgpr_queue_ptr 0
		.amdhsa_user_sgpr_kernarg_segment_ptr 1
		.amdhsa_user_sgpr_dispatch_id 0
		.amdhsa_user_sgpr_kernarg_preload_length 0
		.amdhsa_user_sgpr_kernarg_preload_offset 0
		.amdhsa_user_sgpr_private_segment_size 0
		.amdhsa_uses_dynamic_stack 0
		.amdhsa_enable_private_segment 0
		.amdhsa_system_sgpr_workgroup_id_x 1
		.amdhsa_system_sgpr_workgroup_id_y 0
		.amdhsa_system_sgpr_workgroup_id_z 0
		.amdhsa_system_sgpr_workgroup_info 0
		.amdhsa_system_vgpr_workitem_id 2
		.amdhsa_next_free_vgpr 224
		.amdhsa_next_free_sgpr 102
		.amdhsa_accum_offset 224
		.amdhsa_reserve_vcc 1
		.amdhsa_float_round_mode_32 0
		.amdhsa_float_round_mode_16_64 0
		.amdhsa_float_denorm_mode_32 3
		.amdhsa_float_denorm_mode_16_64 3
		.amdhsa_dx10_clamp 1
		.amdhsa_ieee_mode 1
		.amdhsa_fp16_overflow 0
		.amdhsa_tg_split 0
		.amdhsa_exception_fp_ieee_invalid_op 0
		.amdhsa_exception_fp_denorm_src 0
		.amdhsa_exception_fp_ieee_div_zero 0
		.amdhsa_exception_fp_ieee_overflow 0
		.amdhsa_exception_fp_ieee_underflow 0
		.amdhsa_exception_fp_ieee_inexact 0
		.amdhsa_exception_int_div_zero 0
	.end_amdhsa_kernel

; __global__ void __launch_bounds__(256, 2) mega(Params p_unused) {
;   __shared__ __attribute__((aligned(16))) char smem[SMEM_BYTES];
amdhsa.kernels:
  - .agpr_count:     0
    .args:
      - .offset:         0
        .size:           392
        .value_kind:     by_value
      - .offset:         392
        .size:           4
        .value_kind:     hidden_block_count_x
      - .offset:         396
        .size:           4
        .value_kind:     hidden_block_count_y
      - .offset:         400
        .size:           4
        .value_kind:     hidden_block_count_z
      - .offset:         404
        .size:           2
        .value_kind:     hidden_group_size_x
      - .offset:         406
        .size:           2
        .value_kind:     hidden_group_size_y
      - .offset:         408
        .size:           2
        .value_kind:     hidden_group_size_z
      - .offset:         410
        .size:           2
        .value_kind:     hidden_remainder_x
      - .offset:         412
        .size:           2
        .value_kind:     hidden_remainder_y
      - .offset:         414
        .size:           2
        .value_kind:     hidden_remainder_z
      - .offset:         432
        .size:           8
        .value_kind:     hidden_global_offset_x
      - .offset:         440
        .size:           8
        .value_kind:     hidden_global_offset_y
      - .offset:         448
        .size:           8
        .value_kind:     hidden_global_offset_z
      - .offset:         456
        .size:           2
        .value_kind:     hidden_grid_dims
      - .offset:         480
        .size:           8
        .value_kind:     hidden_multigrid_sync_arg
    .group_segment_fixed_size: 74752
    .kernarg_segment_align: 8
    .kernarg_segment_size: 648
    .language:       OpenCL C
    .language_version:
      - 2
      - 0
    .max_flat_workgroup_size: 256
    .name:           _Z4mega6Params
    .private_segment_fixed_size: 0
    .sgpr_count:     108
    .sgpr_spill_count: 74
    .symbol:         _Z4mega6Params.kd
    .uniform_work_group_size: 1
    .uses_dynamic_stack: false
    .vgpr_count:     224
    .vgpr_spill_count: 0
    .wavefront_size: 64
